# all data-path flat_load/flat_store converted to global_load/global_store (no lgkmcnt coupling of LDS waits with global memory traffic)
# baseline (speedup 1.0000x reference)
; __device__ __forceinline__ unsigned cvt_pk_bf16(float lo, float hi) { unsigned r; asm volatile("v_cvt_pk_bf16_f32 %0, %1, %2" : "=v"(r) : "v"(lo), "v"(hi)); return r; }
; #define PG8_BAR __builtin_amdgcn_s_barrier()
;     __device__ __forceinline__ void operator()(const f32x4 (&acc)[2][2][4][2], const Unit& u, int wr, int wc, int fr, int fq) const {
;     ...
;             for (int m = 0; m < 4; ++m) { bf16_t* rowp = O + (size_t)(u.pm >> 5) * bgap + (size_t)u.pm * sm + (size_t)u.pn * sn + (size_t)(wr * 64 + fr + ai * HALF + m * 16) * ldc + wc * 32 + 8 * fq; const float sc = rs[ai][m]; float s1 = 0.f, s2 = 0.f;
; #pragma unroll
;                 for (int bj = 0; bj < 2; ++bj) { f32x4 v0 = acc[ai][bj][m][0] * sc, v1 = acc[ai][bj][m][1] * sc;
;                     if (do_gelu) { f32x2 a = gelu_pk((f32x2){v0[0], v0[1]}), b = gelu_pk((f32x2){v0[2], v0[3]}), c = gelu_pk((f32x2){v1[0], v1[1]}), d = gelu_pk((f32x2){v1[2], v1[3]});
;                         v0 = (f32x4){a.x, a.y, b.x, b.y}; v1 = (f32x4){c.x, c.y, d.x, d.y}; }
;                     if (do_stat) { s1 += ((v0[0] + v0[1]) + (v0[2] + v0[3])) + ((v1[0] + v1[1]) + (v1[2] + v1[3]));
;                         s2 += ((v0[0] * v0[0] + v0[1] * v0[1]) + (v0[2] * v0[2] + v0[3] * v0[3])) + ((v1[0] * v1[0] + v1[1] * v1[1]) + (v1[2] * v1[2] + v1[3] * v1[3])); }
;                     u32x4 w; w.x = cvt_pk_bf16(v0[0], v0[1]); w.y = cvt_pk_bf16(v0[2], v0[3]); w.z = cvt_pk_bf16(v1[0], v1[1]); w.w = cvt_pk_bf16(v1[2], v1[3]);
;                     *(u32x4*)(rowp + bj * HALF) = w; }
;                 if (do_stat) { s1 += __shfl_xor(s1, 16); s1 += __shfl_xor(s1, 32); s2 += __shfl_xor(s2, 16); s2 += __shfl_xor(s2, 32);
;                     if (fq == 0) *(f32x2*)(vstat + ((size_t)(row0 + ai * HALF + m * 16) * 8 + (u.pn - vstat_pn0) * 4 + wc) * 2) = (f32x2){s1, s2}; }
;                 asm volatile("" ::: "memory"); }
; template <class Epi, class Sched, bool ALIGN_EPI = false, bool SP2 = false>
; __device__ __forceinline__ void gemm_phase(PG8_LAS unsigned char* lds, const Gemm g, const Sched& S, const Epi& E, int wave_in) {
;     ...
;         cur = nxt; cA = nA; cB = nB; ++ui;
;         if constexpr (ALIGN_EPI) { if (wr == 1) PG8_BAR; }
;     }
.LBB0_257:
	s_ashr_i32 s29, s28, 31
	s_lshl_b64 s[28:29], s[28:29], 19
	s_add_u32 s21, s71, s28
	s_addc_u32 s23, s72, s29
	s_ashr_i32 s31, s30, 31
	s_lshl_b64 s[28:29], s[30:31], 17
	s_add_u32 s28, s21, s28
	s_addc_u32 s29, s23, s29
	v_lshl_add_u64 v[162:163], s[28:29], 0, v[138:139]
	v_lshl_add_u64 v[162:163], v[162:163], 0, s[0:1]
	v_lshl_add_u64 v[162:163], v[162:163], 0, v[128:129]
	v_cvt_pk_bf16_f32 v124, v124, v125
	v_cvt_pk_bf16_f32 v125, v126, v127
	v_cvt_pk_bf16_f32 v126, v120, v121
	v_cvt_pk_bf16_f32 v127, v122, v123
	global_store_dwordx4 v[162:163], v[124:127], off
	v_cvt_pk_bf16_f32 v112, v112, v113
	v_cvt_pk_bf16_f32 v113, v114, v115
	v_cvt_pk_bf16_f32 v114, v104, v105
	v_lshl_add_u64 v[104:105], s[28:29], 0, v[148:149]
	v_lshl_add_u64 v[104:105], v[104:105], 0, s[0:1]
	v_cvt_pk_bf16_f32 v115, v106, v107
	global_store_dwordx4 v[162:163], v[112:115], off offset:256
	s_andn2_b64 vcc, exec, s[18:19]
	s_mov_b64 s[18:19], -1
	v_lshl_add_u64 v[112:113], v[104:105], 0, v[128:129]
	v_cvt_pk_bf16_f32 v104, v116, v117
	v_cvt_pk_bf16_f32 v105, v118, v119
	v_cvt_pk_bf16_f32 v106, v108, v109
	v_cvt_pk_bf16_f32 v107, v110, v111
	global_store_dwordx4 v[112:113], v[104:107], off
	v_cvt_pk_bf16_f32 v96, v96, v97
	v_cvt_pk_bf16_f32 v97, v98, v99
	v_cvt_pk_bf16_f32 v98, v88, v89
	v_lshl_add_u64 v[88:89], s[28:29], 0, v[150:151]
	v_lshl_add_u64 v[88:89], v[88:89], 0, s[0:1]
	v_cvt_pk_bf16_f32 v99, v90, v91
	global_store_dwordx4 v[112:113], v[96:99], off offset:256
	s_nop 1
	v_lshl_add_u64 v[96:97], v[88:89], 0, v[128:129]
	v_cvt_pk_bf16_f32 v88, v100, v101
	v_cvt_pk_bf16_f32 v89, v102, v103
	v_cvt_pk_bf16_f32 v90, v92, v93
	v_cvt_pk_bf16_f32 v91, v94, v95
	global_store_dwordx4 v[96:97], v[88:91], off
	v_cvt_pk_bf16_f32 v80, v80, v81
	v_cvt_pk_bf16_f32 v81, v82, v83
	v_cvt_pk_bf16_f32 v82, v72, v73
	v_lshl_add_u64 v[72:73], s[28:29], 0, v[152:153]
	v_lshl_add_u64 v[72:73], v[72:73], 0, s[0:1]
	v_cvt_pk_bf16_f32 v83, v74, v75
	global_store_dwordx4 v[96:97], v[80:83], off offset:256
	s_nop 1
	v_lshl_add_u64 v[80:81], v[72:73], 0, v[128:129]
	v_cvt_pk_bf16_f32 v72, v84, v85
	v_cvt_pk_bf16_f32 v73, v86, v87
	v_cvt_pk_bf16_f32 v74, v76, v77
	v_cvt_pk_bf16_f32 v75, v78, v79
	global_store_dwordx4 v[80:81], v[72:75], off
	v_cvt_pk_bf16_f32 v68, v68, v69
	v_cvt_pk_bf16_f32 v69, v70, v71
	v_cvt_pk_bf16_f32 v70, v64, v65
	v_lshl_add_u64 v[64:65], s[28:29], 0, v[140:141]
	v_lshl_add_u64 v[64:65], v[64:65], 0, s[0:1]
	v_cvt_pk_bf16_f32 v71, v66, v67
	global_store_dwordx4 v[80:81], v[68:71], off offset:256
	v_lshl_add_u64 v[64:65], v[64:65], 0, v[128:129]
	v_cvt_pk_bf16_f32 v60, v60, v61
	v_cvt_pk_bf16_f32 v61, v62, v63
	v_cvt_pk_bf16_f32 v62, v56, v57
	v_cvt_pk_bf16_f32 v63, v58, v59
	global_store_dwordx4 v[64:65], v[60:63], off
	v_cvt_pk_bf16_f32 v48, v48, v49
	v_cvt_pk_bf16_f32 v49, v50, v51
	v_cvt_pk_bf16_f32 v50, v40, v41
	v_lshl_add_u64 v[40:41], s[28:29], 0, v[142:143]
	v_lshl_add_u64 v[40:41], v[40:41], 0, s[0:1]
	v_cvt_pk_bf16_f32 v51, v42, v43
	global_store_dwordx4 v[64:65], v[48:51], off offset:256
	s_nop 1
	v_lshl_add_u64 v[48:49], v[40:41], 0, v[128:129]
	v_cvt_pk_bf16_f32 v40, v52, v53
	v_cvt_pk_bf16_f32 v41, v54, v55
	v_cvt_pk_bf16_f32 v42, v44, v45
	v_cvt_pk_bf16_f32 v43, v46, v47
	global_store_dwordx4 v[48:49], v[40:43], off
	v_cvt_pk_bf16_f32 v32, v32, v33
	v_cvt_pk_bf16_f32 v33, v34, v35
	v_cvt_pk_bf16_f32 v34, v24, v25
	v_lshl_add_u64 v[24:25], s[28:29], 0, v[144:145]
	v_lshl_add_u64 v[24:25], v[24:25], 0, s[0:1]
	v_cvt_pk_bf16_f32 v35, v26, v27
	global_store_dwordx4 v[48:49], v[32:35], off offset:256
	s_nop 1
	v_lshl_add_u64 v[32:33], v[24:25], 0, v[128:129]
	v_cvt_pk_bf16_f32 v24, v36, v37
	v_cvt_pk_bf16_f32 v25, v38, v39
	v_cvt_pk_bf16_f32 v26, v28, v29
	v_cvt_pk_bf16_f32 v27, v30, v31
	global_store_dwordx4 v[32:33], v[24:27], off
	v_cvt_pk_bf16_f32 v16, v16, v17
	v_cvt_pk_bf16_f32 v17, v18, v19
	v_cvt_pk_bf16_f32 v18, v8, v9
	v_lshl_add_u64 v[8:9], s[28:29], 0, v[146:147]
	v_lshl_add_u64 v[8:9], v[8:9], 0, s[0:1]
	v_cvt_pk_bf16_f32 v19, v10, v11
	global_store_dwordx4 v[32:33], v[16:19], off offset:256
	s_nop 1
	v_lshl_add_u64 v[16:17], v[8:9], 0, v[128:129]
	v_cvt_pk_bf16_f32 v8, v20, v21
	v_cvt_pk_bf16_f32 v9, v22, v23
	v_cvt_pk_bf16_f32 v10, v12, v13
	v_cvt_pk_bf16_f32 v11, v14, v15
	global_store_dwordx4 v[16:17], v[8:11], off
	v_cvt_pk_bf16_f32 v4, v4, v5
	v_cvt_pk_bf16_f32 v5, v6, v7
	v_cvt_pk_bf16_f32 v6, v0, v1
	v_cvt_pk_bf16_f32 v7, v2, v3
	global_store_dwordx4 v[16:17], v[4:7], off offset:256
	s_cbranch_vccnz .LBB0_246
	s_andn2_b64 vcc, exec, s[14:15]
	s_cbranch_vccnz .LBB0_245
	s_barrier
	s_branch .LBB0_245

; __device__ __forceinline__ float row_rstd(const float* slots, int row) {
;     const f32x4* s = (const f32x4*)(slots + (size_t)row * 16);
;     const f32x4 a = s[0], b = s[1], c = s[2], d = s[3];
;     const f32x4 t = (a + b) + (c + d);
;     const float ss = (t[0] + t[1]) + (t[2] + t[3]);
;     return __builtin_amdgcn_rsqf(ss * (1.0f / 1024.0f) + 1e-6f);
; }
; __device__ __forceinline__ void load_rs(const float* slots, int rowbase, int fr, int fq, float scale, float (&rs)[2][4]) {
;     float loc[2];
; #pragma unroll
;     for (int ai = 0; ai < 2; ++ai) loc[ai] = scale * row_rstd(slots, rowbase + ai * HALF + fq * 16 + fr);
; #pragma unroll
;     for (int ai = 0; ai < 2; ++ai)
; #pragma unroll
;         for (int m = 0; m < 4; ++m) rs[ai][m] = __shfl(loc[ai], m * 16 + fr);
;     __device__ __forceinline__ void operator()(const f32x4 (&acc)[2][2][4][2], const Unit& u, int wr, int wc, int fr, int fq) const {
;     ...
;         const bool do_gelu = u.pn >= gelu_pn0, do_stat = u.pn >= vstat_pn0;
;         float rs[2][4];
;         if (slots) load_rs(slots, u.pm * BM + wr * 64, fr, fq, scale, rs);
.LBB0_276:
	s_lshl_b32 s8, s6, 8
	s_add_i32 s8, s8, s46
	v_or_b32_e32 v172, s8, v178
	v_ashrrev_i32_e32 v173, 31, v172
	v_lshlrev_b64 v[156:157], 6, v[172:173]
	v_lshl_add_u64 v[168:169], s[18:19], 0, v[156:157]
	global_load_dwordx4 v[156:159], v[168:169], off
	global_load_dwordx4 v[160:163], v[168:169], off offset:16
	global_load_dwordx4 v[164:167], v[168:169], off offset:32
	s_nop 0
	global_load_dwordx4 v[168:171], v[168:169], off offset:48
	s_cmp_gt_i32 s60, 1
	s_cselect_b64 s[0:1], -1, 0
	s_cmp_lt_i32 s60, 2
	s_waitcnt vmcnt(0) lgkmcnt(0)
	v_pk_add_f32 v[158:159], v[158:159], v[162:163]
	v_pk_add_f32 v[156:157], v[156:157], v[160:161]
	v_pk_add_f32 v[160:161], v[166:167], v[170:171]
	v_pk_add_f32 v[162:163], v[164:165], v[168:169]
	v_pk_add_f32 v[158:159], v[158:159], v[160:161]
	v_pk_add_f32 v[156:157], v[156:157], v[162:163]
	s_nop 0
	v_pk_mov_b32 v[160:161], v[156:157], v[158:159] op_sel:[1,0]
	v_mov_b32_e32 v157, v159
	v_pk_add_f32 v[156:157], v[160:161], v[156:157]
	s_nop 0
	v_add_f32_e32 v156, v156, v157
	v_fmamk_f32 v156, v156, 0x3a800000, v244
	v_rsq_f32_e32 v173, v156
	v_add_u32_e32 v156, 0x80, v172
	v_ashrrev_i32_e32 v157, 31, v156
	v_lshlrev_b64 v[156:157], 6, v[156:157]
	v_lshl_add_u64 v[168:169], s[18:19], 0, v[156:157]
	global_load_dwordx4 v[156:159], v[168:169], off
	global_load_dwordx4 v[160:163], v[168:169], off offset:16
	global_load_dwordx4 v[164:167], v[168:169], off offset:32
	s_nop 0
	global_load_dwordx4 v[168:171], v[168:169], off offset:48
	s_waitcnt vmcnt(0) lgkmcnt(0)
	v_pk_add_f32 v[158:159], v[158:159], v[162:163]
	v_pk_add_f32 v[156:157], v[156:157], v[160:161]
	v_pk_add_f32 v[160:161], v[166:167], v[170:171]
	v_pk_add_f32 v[162:163], v[164:165], v[168:169]
	v_pk_add_f32 v[158:159], v[158:159], v[160:161]
	v_pk_add_f32 v[156:157], v[156:157], v[162:163]
	s_nop 0
	v_add_f32_e32 v156, v156, v157
	v_add_f32_e32 v157, v158, v159
	v_add_f32_e32 v156, v156, v157
	v_fmamk_f32 v156, v156, 0x3a800000, v244
	v_rsq_f32_e32 v156, v156
	v_and_or_b32 v157, v252, 64, v176
	v_lshlrev_b32_e32 v157, 2, v157
	ds_bpermute_b32 v170, v157, v173
	ds_bpermute_b32 v168, v157, v173 offset:64
	ds_bpermute_b32 v166, v157, v173 offset:128
	ds_bpermute_b32 v164, v157, v173 offset:192
	ds_bpermute_b32 v162, v157, v156
	ds_bpermute_b32 v160, v157, v156 offset:64
	ds_bpermute_b32 v158, v157, v156 offset:128
	ds_bpermute_b32 v156, v157, v156 offset:192
	s_waitcnt lgkmcnt(7)
	v_pk_mul_f32 v[126:127], v[126:127], v[170:171] op_sel_hi:[1,0]
	v_pk_mul_f32 v[124:125], v[124:125], v[170:171] op_sel_hi:[1,0]
	v_pk_mul_f32 v[122:123], v[122:123], v[170:171] op_sel_hi:[1,0]
	v_pk_mul_f32 v[172:173], v[120:121], v[170:171] op_sel_hi:[1,0]
	s_cbranch_scc1 .LBB0_278
; __device__ __forceinline__ f32x2 gelu_pk(f32x2 v) {
;     const f32x2 av = __builtin_elementwise_abs(v), d = av * 0.2316418882f + 1.0f;
;     f32x2 t; t.x = __builtin_amdgcn_rcpf(d.x); t.y = __builtin_amdgcn_rcpf(d.y);
;     f32x2 q = t * 0.5307027145f + (-0.7265760135f); q = q * t + 0.7107068705f; q = q * t + (-0.142248368f); q = q * t + 0.127414796f; q = q * t;
;     const f32x2 s = (v * v) * (-0.72134752044f);
;     f32x2 e; e.x = __builtin_amdgcn_exp2f(s.x); e.y = __builtin_amdgcn_exp2f(s.y);
;     const f32x2 m = v * (q * e), r = v - m;
;     f32x2 o; o.x = v.x < 0.f ? m.x : r.x; o.y = v.y < 0.f ? m.y : r.y; return o;
; }
;     __device__ __forceinline__ void operator()(const f32x4 (&acc)[2][2][4][2], const Unit& u, int wr, int wc, int fr, int fq) const {
;     ...
;                 for (int bj = 0; bj < 2; ++bj) { f32x4 v0 = acc[ai][bj][m][0] * sc, v1 = acc[ai][bj][m][1] * sc;
;                     if (do_gelu) { f32x2 a = gelu_pk((f32x2){v0[0], v0[1]}), b = gelu_pk((f32x2){v0[2], v0[3]}), c = gelu_pk((f32x2){v1[0], v1[1]}), d = gelu_pk((f32x2){v1[2], v1[3]});
;                         v0 = (f32x4){a.x, a.y, b.x, b.y}; v1 = (f32x4){c.x, c.y, d.x, d.y}; }
	v_and_b32_e32 v121, 0x7fffffff, v125
	v_and_b32_e32 v120, 0x7fffffff, v124
	v_pk_fma_f32 v[120:121], v[120:121], s[28:29], 1.0 op_sel_hi:[1,0,0]
	s_mov_b32 s2, 0xbf3a00e3
	v_rcp_f32_e32 v174, v120
	v_rcp_f32_e32 v175, v121
	v_mov_b64_e32 v[120:121], s[2:3]
	v_pk_mul_f32 v[182:183], v[124:125], v[124:125]
	s_mov_b32 s2, 0xbf38aa3b
	v_pk_fma_f32 v[180:181], v[174:175], s[30:31], v[120:121] op_sel_hi:[1,0,0]
	v_pk_mul_f32 v[182:183], v[182:183], s[2:3] op_sel_hi:[1,0]
	v_pk_fma_f32 v[180:181], v[174:175], v[180:181], s[36:37] op_sel_hi:[1,1,0]
	v_exp_f32_e32 v182, v182
	v_exp_f32_e32 v183, v183
	v_pk_fma_f32 v[180:181], v[174:175], v[180:181], s[80:81] op_sel_hi:[1,1,0]
	v_cmp_gt_f32_e32 vcc, 0, v124
	v_pk_fma_f32 v[180:181], v[174:175], v[180:181], s[64:65] op_sel_hi:[1,1,0]
	s_nop 0
	v_pk_mul_f32 v[174:175], v[174:175], v[180:181]
	v_pk_mul_f32 v[180:181], v[126:127], v[126:127]
	v_pk_mul_f32 v[174:175], v[182:183], v[174:175]
	v_pk_mul_f32 v[180:181], v[180:181], s[2:3] op_sel_hi:[1,0]
	v_pk_mul_f32 v[182:183], v[124:125], v[174:175]
	v_pk_fma_f32 v[174:175], v[124:125], v[174:175], v[124:125] neg_lo:[1,0,0] neg_hi:[1,0,0]
	v_exp_f32_e32 v180, v180
	v_cndmask_b32_e32 v124, v174, v182, vcc
	v_cmp_gt_f32_e32 vcc, 0, v125
	v_and_b32_e32 v174, 0x7fffffff, v126
	v_exp_f32_e32 v181, v181
	v_cndmask_b32_e32 v125, v175, v183, vcc
	v_and_b32_e32 v175, 0x7fffffff, v127
	v_pk_fma_f32 v[174:175], v[174:175], s[28:29], 1.0 op_sel_hi:[1,0,0]
	v_cmp_gt_f32_e32 vcc, 0, v126
	v_rcp_f32_e32 v174, v174
	v_rcp_f32_e32 v175, v175
	s_nop 0
	v_pk_fma_f32 v[182:183], v[174:175], s[30:31], v[120:121] op_sel_hi:[1,0,0]
	s_nop 0
	v_pk_fma_f32 v[182:183], v[174:175], v[182:183], s[36:37] op_sel_hi:[1,1,0]
	s_nop 0
	v_pk_fma_f32 v[182:183], v[174:175], v[182:183], s[80:81] op_sel_hi:[1,1,0]
	s_nop 0
	v_pk_fma_f32 v[182:183], v[174:175], v[182:183], s[64:65] op_sel_hi:[1,1,0]
	s_nop 0
	v_pk_mul_f32 v[174:175], v[174:175], v[182:183]
	v_pk_mul_f32 v[182:183], v[172:173], v[172:173]
	v_pk_mul_f32 v[174:175], v[180:181], v[174:175]
	v_pk_mul_f32 v[182:183], v[182:183], s[2:3] op_sel_hi:[1,0]
	v_pk_mul_f32 v[180:181], v[126:127], v[174:175]
	v_pk_fma_f32 v[174:175], v[126:127], v[174:175], v[126:127] neg_lo:[1,0,0] neg_hi:[1,0,0]
	v_exp_f32_e32 v182, v182
	v_cndmask_b32_e32 v126, v174, v180, vcc
	v_cmp_gt_f32_e32 vcc, 0, v127
	v_and_b32_e32 v174, 0x7fffffff, v172
	v_exp_f32_e32 v183, v183
	v_cndmask_b32_e32 v127, v175, v181, vcc
	v_and_b32_e32 v175, 0x7fffffff, v173
	v_pk_fma_f32 v[174:175], v[174:175], s[28:29], 1.0 op_sel_hi:[1,0,0]
	v_cmp_gt_f32_e32 vcc, 0, v172
	v_rcp_f32_e32 v174, v174
	v_rcp_f32_e32 v175, v175
	s_nop 0
	v_pk_fma_f32 v[180:181], v[174:175], s[30:31], v[120:121] op_sel_hi:[1,0,0]
	s_nop 0
	v_pk_fma_f32 v[180:181], v[174:175], v[180:181], s[36:37] op_sel_hi:[1,1,0]
	s_nop 0
	v_pk_fma_f32 v[180:181], v[174:175], v[180:181], s[80:81] op_sel_hi:[1,1,0]
	s_nop 0
	v_pk_fma_f32 v[180:181], v[174:175], v[180:181], s[64:65] op_sel_hi:[1,1,0]
	s_nop 0
	v_pk_mul_f32 v[174:175], v[174:175], v[180:181]
	v_pk_mul_f32 v[180:181], v[122:123], v[122:123]
	v_pk_mul_f32 v[174:175], v[182:183], v[174:175]
	s_nop 0
	v_pk_mul_f32 v[182:183], v[172:173], v[174:175]
	v_pk_fma_f32 v[174:175], v[172:173], v[174:175], v[172:173] neg_lo:[1,0,0] neg_hi:[1,0,0]
	s_nop 0
	v_cndmask_b32_e32 v172, v174, v182, vcc
	v_cmp_gt_f32_e32 vcc, 0, v173
	v_and_b32_e32 v174, 0x7fffffff, v122
	s_nop 0
	v_cndmask_b32_e32 v173, v175, v183, vcc
	v_and_b32_e32 v175, 0x7fffffff, v123
	v_pk_fma_f32 v[174:175], v[174:175], s[28:29], 1.0 op_sel_hi:[1,0,0]
	v_cmp_gt_f32_e32 vcc, 0, v122
	v_rcp_f32_e32 v174, v174
	v_rcp_f32_e32 v175, v175
	s_nop 0
	v_pk_fma_f32 v[120:121], v[174:175], s[30:31], v[120:121] op_sel_hi:[1,0,0]
	s_nop 0
	v_pk_fma_f32 v[120:121], v[174:175], v[120:121], s[36:37] op_sel_hi:[1,1,0]
	s_nop 0
	v_pk_fma_f32 v[120:121], v[174:175], v[120:121], s[80:81] op_sel_hi:[1,1,0]
	s_nop 0
	v_pk_fma_f32 v[120:121], v[174:175], v[120:121], s[64:65] op_sel_hi:[1,1,0]
	s_nop 0
	v_pk_mul_f32 v[120:121], v[174:175], v[120:121]
	v_pk_mul_f32 v[174:175], v[180:181], s[2:3] op_sel_hi:[1,0]
	s_nop 0
	v_exp_f32_e32 v174, v174
	v_exp_f32_e32 v175, v175
	s_nop 0
	v_pk_mul_f32 v[120:121], v[174:175], v[120:121]
	s_nop 0
	v_pk_mul_f32 v[174:175], v[122:123], v[120:121]
	v_pk_fma_f32 v[120:121], v[122:123], v[120:121], v[122:123] neg_lo:[1,0,0] neg_hi:[1,0,0]
	s_nop 0
	v_cndmask_b32_e32 v122, v120, v174, vcc
	v_cmp_gt_f32_e32 vcc, 0, v123
	s_nop 1
	v_cndmask_b32_e32 v123, v121, v175, vcc

; __device__ __forceinline__ unsigned cvt_pk_bf16(float lo, float hi) { unsigned r; asm volatile("v_cvt_pk_bf16_f32 %0, %1, %2" : "=v"(r) : "v"(lo), "v"(hi)); return r; }
; __device__ __forceinline__ f32x2 gelu_pk(f32x2 v) {
;     const f32x2 av = __builtin_elementwise_abs(v), d = av * 0.2316418882f + 1.0f;
;     f32x2 t; t.x = __builtin_amdgcn_rcpf(d.x); t.y = __builtin_amdgcn_rcpf(d.y);
;     f32x2 q = t * 0.5307027145f + (-0.7265760135f); q = q * t + 0.7107068705f; q = q * t + (-0.142248368f); q = q * t + 0.127414796f; q = q * t;
;     const f32x2 s = (v * v) * (-0.72134752044f);
;     f32x2 e; e.x = __builtin_amdgcn_exp2f(s.x); e.y = __builtin_amdgcn_exp2f(s.y);
;     const f32x2 m = v * (q * e), r = v - m;
;     f32x2 o; o.x = v.x < 0.f ? m.x : r.x; o.y = v.y < 0.f ? m.y : r.y; return o;
; }
;     __device__ __forceinline__ void operator()(const f32x4 (&acc)[2][2][4][2], const Unit& u, int wr, int wc, int fr, int fq) const {
;     ...
;             for (int m = 0; m < 4; ++m) { bf16_t* rowp = O + (size_t)(u.pm >> 5) * bgap + (size_t)u.pm * sm + (size_t)u.pn * sn + (size_t)(wr * 64 + fr + ai * HALF + m * 16) * ldc + wc * 32 + 8 * fq; const float sc = rs[ai][m]; float s1 = 0.f, s2 = 0.f;
; #pragma unroll
;                 for (int bj = 0; bj < 2; ++bj) { f32x4 v0 = acc[ai][bj][m][0] * sc, v1 = acc[ai][bj][m][1] * sc;
;                     if (do_gelu) { f32x2 a = gelu_pk((f32x2){v0[0], v0[1]}), b = gelu_pk((f32x2){v0[2], v0[3]}), c = gelu_pk((f32x2){v1[0], v1[1]}), d = gelu_pk((f32x2){v1[2], v1[3]});
;                         v0 = (f32x4){a.x, a.y, b.x, b.y}; v1 = (f32x4){c.x, c.y, d.x, d.y}; }
;                     if (do_stat) { s1 += ((v0[0] + v0[1]) + (v0[2] + v0[3])) + ((v1[0] + v1[1]) + (v1[2] + v1[3]));
;                         s2 += ((v0[0] * v0[0] + v0[1] * v0[1]) + (v0[2] * v0[2] + v0[3] * v0[3])) + ((v1[0] * v1[0] + v1[1] * v1[1]) + (v1[2] * v1[2] + v1[3] * v1[3])); }
;                     u32x4 w; w.x = cvt_pk_bf16(v0[0], v0[1]); w.y = cvt_pk_bf16(v0[2], v0[3]); w.z = cvt_pk_bf16(v1[0], v1[1]); w.w = cvt_pk_bf16(v1[2], v1[3]);
;                     *(u32x4*)(rowp + bj * HALF) = w; }
.LBB0_282:
	s_ashr_i32 s4, s6, 5
	s_mul_hi_i32 s5, s4, 0x1400000
	s_mul_i32 s4, s4, 0x1400000
	s_add_u32 s4, s12, s4
	s_addc_u32 s5, s13, s5
	s_mul_hi_i32 s9, s6, 0xc0000
	s_mul_i32 s6, s6, 0xc0000
	s_add_u32 s6, s4, s6
	s_addc_u32 s9, s5, s9
	s_ashr_i32 s61, s60, 31
	s_lshl_b64 s[4:5], s[60:61], 9
	s_add_u32 s16, s6, s4
	s_addc_u32 s17, s9, s5
	v_lshl_add_u64 v[174:175], s[16:17], 0, v[136:137]
	s_lshl_b32 s86, s47, 1
	v_cvt_pk_bf16_f32 v124, v124, v125
	v_cvt_pk_bf16_f32 v125, v126, v127
	v_cvt_pk_bf16_f32 v126, v172, v173
	v_cvt_pk_bf16_f32 v127, v122, v123
	v_mov_b32_e32 v122, v170
	v_mov_b32_e32 v123, v170
	v_mov_b32_e32 v171, v170
	v_lshl_add_u64 v[174:175], v[174:175], 0, s[86:87]
	v_pk_mul_f32 v[118:119], v[118:119], v[122:123]
	v_pk_mul_f32 v[114:115], v[114:115], v[122:123]
	v_cndmask_b32_e64 v122, 0, 1, s[0:1]
	v_lshl_add_u64 v[174:175], v[174:175], 0, v[192:193]
	v_pk_mul_f32 v[116:117], v[116:117], v[170:171]
	v_cmp_ne_u32_e64 s[42:43], 1, v122
	s_andn2_b64 vcc, exec, s[0:1]
	v_pk_mul_f32 v[122:123], v[112:113], v[170:171]
	global_store_dwordx4 v[174:175], v[124:127], off
	s_cbranch_vccnz .LBB0_284
	v_and_b32_e32 v113, 0x7fffffff, v117
	v_and_b32_e32 v112, 0x7fffffff, v116
	v_pk_fma_f32 v[112:113], v[112:113], s[28:29], 1.0 op_sel_hi:[1,0,0]
	s_mov_b32 s0, 0xbf3a00e3
	v_rcp_f32_e32 v124, v112
	v_rcp_f32_e32 v125, v113
	v_mov_b64_e32 v[112:113], s[0:1]
	v_pk_mul_f32 v[170:171], v[116:117], v[116:117]
	s_mov_b32 s0, 0xbf38aa3b
	v_pk_fma_f32 v[126:127], v[124:125], s[30:31], v[112:113] op_sel_hi:[1,0,0]
	v_pk_mul_f32 v[170:171], v[170:171], s[0:1] op_sel_hi:[1,0]
	v_pk_fma_f32 v[126:127], v[124:125], v[126:127], s[36:37] op_sel_hi:[1,1,0]
	v_exp_f32_e32 v170, v170
	v_exp_f32_e32 v171, v171
	v_pk_fma_f32 v[126:127], v[124:125], v[126:127], s[80:81] op_sel_hi:[1,1,0]
	v_cmp_gt_f32_e32 vcc, 0, v116
	v_pk_fma_f32 v[126:127], v[124:125], v[126:127], s[64:65] op_sel_hi:[1,1,0]
	s_nop 0
	v_pk_mul_f32 v[124:125], v[124:125], v[126:127]
	v_pk_mul_f32 v[126:127], v[118:119], v[118:119]
	v_pk_mul_f32 v[124:125], v[170:171], v[124:125]
	v_pk_mul_f32 v[126:127], v[126:127], s[0:1] op_sel_hi:[1,0]
	v_pk_mul_f32 v[170:171], v[116:117], v[124:125]
	v_pk_fma_f32 v[124:125], v[116:117], v[124:125], v[116:117] neg_lo:[1,0,0] neg_hi:[1,0,0]
	v_exp_f32_e32 v126, v126
	v_cndmask_b32_e32 v116, v124, v170, vcc
	v_cmp_gt_f32_e32 vcc, 0, v117
	v_and_b32_e32 v124, 0x7fffffff, v118
	v_exp_f32_e32 v127, v127
	v_cndmask_b32_e32 v117, v125, v171, vcc
	v_and_b32_e32 v125, 0x7fffffff, v119
	v_pk_fma_f32 v[124:125], v[124:125], s[28:29], 1.0 op_sel_hi:[1,0,0]
	v_cmp_gt_f32_e32 vcc, 0, v118
	v_rcp_f32_e32 v124, v124
	v_rcp_f32_e32 v125, v125
	s_nop 0
	v_pk_fma_f32 v[170:171], v[124:125], s[30:31], v[112:113] op_sel_hi:[1,0,0]
	s_nop 0
	v_pk_fma_f32 v[170:171], v[124:125], v[170:171], s[36:37] op_sel_hi:[1,1,0]
	s_nop 0
	v_pk_fma_f32 v[170:171], v[124:125], v[170:171], s[80:81] op_sel_hi:[1,1,0]
	s_nop 0
	v_pk_fma_f32 v[170:171], v[124:125], v[170:171], s[64:65] op_sel_hi:[1,1,0]
	s_nop 0
	v_pk_mul_f32 v[124:125], v[124:125], v[170:171]
	v_pk_mul_f32 v[170:171], v[122:123], v[122:123]
	v_pk_mul_f32 v[124:125], v[126:127], v[124:125]
	v_pk_mul_f32 v[170:171], v[170:171], s[0:1] op_sel_hi:[1,0]
	v_pk_mul_f32 v[126:127], v[118:119], v[124:125]
	v_pk_fma_f32 v[124:125], v[118:119], v[124:125], v[118:119] neg_lo:[1,0,0] neg_hi:[1,0,0]
	v_exp_f32_e32 v170, v170
	v_cndmask_b32_e32 v118, v124, v126, vcc
	v_cmp_gt_f32_e32 vcc, 0, v119
	v_and_b32_e32 v124, 0x7fffffff, v122
	v_exp_f32_e32 v171, v171
	v_cndmask_b32_e32 v119, v125, v127, vcc
	v_and_b32_e32 v125, 0x7fffffff, v123
	v_pk_fma_f32 v[124:125], v[124:125], s[28:29], 1.0 op_sel_hi:[1,0,0]
	v_cmp_gt_f32_e32 vcc, 0, v122
	v_rcp_f32_e32 v124, v124
	v_rcp_f32_e32 v125, v125
	s_nop 0
	v_pk_fma_f32 v[126:127], v[124:125], s[30:31], v[112:113] op_sel_hi:[1,0,0]
	s_nop 0
	v_pk_fma_f32 v[126:127], v[124:125], v[126:127], s[36:37] op_sel_hi:[1,1,0]
	s_nop 0
	v_pk_fma_f32 v[126:127], v[124:125], v[126:127], s[80:81] op_sel_hi:[1,1,0]
	s_nop 0
	v_pk_fma_f32 v[126:127], v[124:125], v[126:127], s[64:65] op_sel_hi:[1,1,0]
	s_nop 0
	v_pk_mul_f32 v[124:125], v[124:125], v[126:127]
	v_pk_mul_f32 v[126:127], v[114:115], v[114:115]
	v_pk_mul_f32 v[124:125], v[170:171], v[124:125]
	s_nop 0
	v_pk_mul_f32 v[170:171], v[122:123], v[124:125]
	v_pk_fma_f32 v[124:125], v[122:123], v[124:125], v[122:123] neg_lo:[1,0,0] neg_hi:[1,0,0]
	s_nop 0
	v_cndmask_b32_e32 v122, v124, v170, vcc
	v_cmp_gt_f32_e32 vcc, 0, v123
	v_and_b32_e32 v124, 0x7fffffff, v114
	s_nop 0
	v_cndmask_b32_e32 v123, v125, v171, vcc
	v_and_b32_e32 v125, 0x7fffffff, v115
	v_pk_fma_f32 v[124:125], v[124:125], s[28:29], 1.0 op_sel_hi:[1,0,0]
	v_cmp_gt_f32_e32 vcc, 0, v114
	v_rcp_f32_e32 v124, v124
	v_rcp_f32_e32 v125, v125
	s_nop 0
	v_pk_fma_f32 v[112:113], v[124:125], s[30:31], v[112:113] op_sel_hi:[1,0,0]
	s_nop 0
	v_pk_fma_f32 v[112:113], v[124:125], v[112:113], s[36:37] op_sel_hi:[1,1,0]
	s_nop 0
	v_pk_fma_f32 v[112:113], v[124:125], v[112:113], s[80:81] op_sel_hi:[1,1,0]
	s_nop 0
	v_pk_fma_f32 v[112:113], v[124:125], v[112:113], s[64:65] op_sel_hi:[1,1,0]
	s_nop 0
	v_pk_mul_f32 v[112:113], v[124:125], v[112:113]
	v_pk_mul_f32 v[124:125], v[126:127], s[0:1] op_sel_hi:[1,0]
	s_nop 0
	v_exp_f32_e32 v124, v124
	v_exp_f32_e32 v125, v125
	s_nop 0
	v_pk_mul_f32 v[112:113], v[124:125], v[112:113]
	s_nop 0
	v_pk_mul_f32 v[124:125], v[114:115], v[112:113]
	v_pk_fma_f32 v[112:113], v[114:115], v[112:113], v[114:115] neg_lo:[1,0,0] neg_hi:[1,0,0]
	s_nop 0
	v_cndmask_b32_e32 v114, v112, v124, vcc
	v_cmp_gt_f32_e32 vcc, 0, v115
	s_nop 1
	v_cndmask_b32_e32 v115, v113, v125, vcc

; __device__ __forceinline__ unsigned cvt_pk_bf16(float lo, float hi) { unsigned r; asm volatile("v_cvt_pk_bf16_f32 %0, %1, %2" : "=v"(r) : "v"(lo), "v"(hi)); return r; }
;     __device__ __forceinline__ void operator()(const f32x4 (&acc)[2][2][4][2], const Unit& u, int wr, int wc, int fr, int fq) const {
;     ...
;                     if (do_stat) { s1 += ((v0[0] + v0[1]) + (v0[2] + v0[3])) + ((v1[0] + v1[1]) + (v1[2] + v1[3]));
;                         s2 += ((v0[0] * v0[0] + v0[1] * v0[1]) + (v0[2] * v0[2] + v0[3] * v0[3])) + ((v1[0] * v1[0] + v1[1] * v1[1]) + (v1[2] * v1[2] + v1[3] * v1[3])); }
;                     u32x4 w; w.x = cvt_pk_bf16(v0[0], v0[1]); w.y = cvt_pk_bf16(v0[2], v0[3]); w.z = cvt_pk_bf16(v1[0], v1[1]); w.w = cvt_pk_bf16(v1[2], v1[3]);
;                     *(u32x4*)(rowp + bj * HALF) = w; }
;                 if (do_stat) { s1 += __shfl_xor(s1, 16); s1 += __shfl_xor(s1, 32); s2 += __shfl_xor(s2, 16); s2 += __shfl_xor(s2, 32);
;                     if (fq == 0) *(f32x2*)(vstat + ((size_t)(row0 + ai * HALF + m * 16) * 8 + (u.pn - vstat_pn0) * 4 + wc) * 2) = (f32x2){s1, s2}; }
.LBB0_288:
	v_cndmask_b32_e64 v113, 0, 1, s[92:93]
	v_cvt_pk_bf16_f32 v116, v116, v117
	v_cvt_pk_bf16_f32 v117, v118, v119
	v_cvt_pk_bf16_f32 v118, v122, v123
	v_cvt_pk_bf16_f32 v119, v114, v115
	v_cmp_ne_u32_e64 s[44:45], 1, v113
	v_and_b32_e32 v113, 64, v252
	v_or_b32_e32 v112, s8, v176
	global_store_dwordx4 v[174:175], v[116:119], off offset:256
	s_andn2_b64 vcc, exec, s[92:93]
	v_xor_b32_e32 v120, 16, v252
	v_xor_b32_e32 v118, 32, v252
	v_add_u32_e32 v119, 64, v113
	s_cbranch_vccnz .LBB0_292
	v_cmp_lt_i32_e32 vcc, v120, v119
	s_nop 1
	v_cndmask_b32_e32 v113, v252, v120, vcc
	v_lshlrev_b32_e32 v113, 2, v113
	ds_bpermute_b32 v114, v113, v124
	ds_bpermute_b32 v115, v113, v125
	v_cmp_lt_i32_e32 vcc, v118, v119
	s_waitcnt lgkmcnt(0)
	v_pk_add_f32 v[114:115], v[124:125], v[114:115]
	v_cndmask_b32_e32 v113, v252, v118, vcc
	v_lshlrev_b32_e32 v113, 2, v113
	ds_bpermute_b32 v116, v113, v114
	ds_bpermute_b32 v117, v113, v115
	s_and_saveexec_b64 s[0:1], s[38:39]
	s_cbranch_execz .LBB0_291
	s_lshl_b32 s4, s60, 2
	s_add_i32 s4, s4, -16
	s_waitcnt lgkmcnt(0)
	v_pk_add_f32 v[114:115], v[114:115], v[116:117]
	v_ashrrev_i32_e32 v113, 31, v112
	v_mov_b32_e32 v116, s4
	v_mov_b32_e32 v117, v193
	v_lshl_add_u64 v[116:117], v[112:113], 3, v[116:117]
	v_or_b32_e32 v116, s83, v116
	v_lshl_add_u64 v[116:117], v[116:117], 3, s[20:21]
	global_store_dwordx2 v[116:117], v[114:115], off

; __device__ __forceinline__ unsigned cvt_pk_bf16(float lo, float hi) { unsigned r; asm volatile("v_cvt_pk_bf16_f32 %0, %1, %2" : "=v"(r) : "v"(lo), "v"(hi)); return r; }
; __device__ __forceinline__ f32x2 gelu_pk(f32x2 v) {
;     const f32x2 av = __builtin_elementwise_abs(v), d = av * 0.2316418882f + 1.0f;
;     f32x2 t; t.x = __builtin_amdgcn_rcpf(d.x); t.y = __builtin_amdgcn_rcpf(d.y);
;     f32x2 q = t * 0.5307027145f + (-0.7265760135f); q = q * t + 0.7107068705f; q = q * t + (-0.142248368f); q = q * t + 0.127414796f; q = q * t;
;     const f32x2 s = (v * v) * (-0.72134752044f);
;     f32x2 e; e.x = __builtin_amdgcn_exp2f(s.x); e.y = __builtin_amdgcn_exp2f(s.y);
;     const f32x2 m = v * (q * e), r = v - m;
;     f32x2 o; o.x = v.x < 0.f ? m.x : r.x; o.y = v.y < 0.f ? m.y : r.y; return o;
; }
;     __device__ __forceinline__ void operator()(const f32x4 (&acc)[2][2][4][2], const Unit& u, int wr, int wc, int fr, int fq) const {
;     ...
;             for (int m = 0; m < 4; ++m) { bf16_t* rowp = O + (size_t)(u.pm >> 5) * bgap + (size_t)u.pm * sm + (size_t)u.pn * sn + (size_t)(wr * 64 + fr + ai * HALF + m * 16) * ldc + wc * 32 + 8 * fq; const float sc = rs[ai][m]; float s1 = 0.f, s2 = 0.f;
; #pragma unroll
;                 for (int bj = 0; bj < 2; ++bj) { f32x4 v0 = acc[ai][bj][m][0] * sc, v1 = acc[ai][bj][m][1] * sc;
;                     if (do_gelu) { f32x2 a = gelu_pk((f32x2){v0[0], v0[1]}), b = gelu_pk((f32x2){v0[2], v0[3]}), c = gelu_pk((f32x2){v1[0], v1[1]}), d = gelu_pk((f32x2){v1[2], v1[3]});
;                         v0 = (f32x4){a.x, a.y, b.x, b.y}; v1 = (f32x4){c.x, c.y, d.x, d.y}; }
;                     if (do_stat) { s1 += ((v0[0] + v0[1]) + (v0[2] + v0[3])) + ((v1[0] + v1[1]) + (v1[2] + v1[3]));
;                         s2 += ((v0[0] * v0[0] + v0[1] * v0[1]) + (v0[2] * v0[2] + v0[3] * v0[3])) + ((v1[0] * v1[0] + v1[1] * v1[1]) + (v1[2] * v1[2] + v1[3] * v1[3])); }
;                     u32x4 w; w.x = cvt_pk_bf16(v0[0], v0[1]); w.y = cvt_pk_bf16(v0[2], v0[3]); w.z = cvt_pk_bf16(v1[0], v1[1]); w.w = cvt_pk_bf16(v1[2], v1[3]);
;                     *(u32x4*)(rowp + bj * HALF) = w; }
.LBB0_298:
	v_lshl_add_u64 v[106:107], s[16:17], 0, v[138:139]
	v_lshl_add_u64 v[106:107], v[106:107], 0, s[86:87]
	v_lshl_add_u64 v[106:107], v[106:107], 0, v[192:193]
	v_cvt_pk_bf16_f32 v108, v108, v109
	v_cvt_pk_bf16_f32 v109, v110, v111
	v_mov_b32_e32 v169, v168
	v_cvt_pk_bf16_f32 v110, v116, v117
	v_cvt_pk_bf16_f32 v111, v114, v115
	global_store_dwordx4 v[106:107], v[108:111], off
	v_pk_mul_f32 v[100:101], v[100:101], v[168:169]
	s_and_b64 vcc, exec, s[42:43]
	v_mov_b32_e32 v108, v168
	v_mov_b32_e32 v109, v168
	v_pk_mul_f32 v[102:103], v[102:103], v[108:109]
	v_pk_mul_f32 v[98:99], v[98:99], v[108:109]
	v_pk_mul_f32 v[96:97], v[96:97], v[168:169]
	s_cbranch_vccnz .LBB0_300
	v_and_b32_e32 v109, 0x7fffffff, v101
	v_and_b32_e32 v108, 0x7fffffff, v100
	v_pk_fma_f32 v[108:109], v[108:109], s[28:29], 1.0 op_sel_hi:[1,0,0]
	s_mov_b32 s0, 0xbf3a00e3
	v_rcp_f32_e32 v110, v108
	v_rcp_f32_e32 v111, v109
	v_mov_b64_e32 v[108:109], s[0:1]
	v_pk_mul_f32 v[116:117], v[100:101], v[100:101]
	s_mov_b32 s0, 0xbf38aa3b
	v_pk_fma_f32 v[114:115], v[110:111], s[30:31], v[108:109] op_sel_hi:[1,0,0]
	v_pk_mul_f32 v[116:117], v[116:117], s[0:1] op_sel_hi:[1,0]
	v_pk_fma_f32 v[114:115], v[110:111], v[114:115], s[36:37] op_sel_hi:[1,1,0]
	v_exp_f32_e32 v116, v116
	v_exp_f32_e32 v117, v117
	v_pk_fma_f32 v[114:115], v[110:111], v[114:115], s[80:81] op_sel_hi:[1,1,0]
	v_cmp_gt_f32_e32 vcc, 0, v100
	v_pk_fma_f32 v[114:115], v[110:111], v[114:115], s[64:65] op_sel_hi:[1,1,0]
	s_nop 0
	v_pk_mul_f32 v[110:111], v[110:111], v[114:115]
	v_pk_mul_f32 v[114:115], v[102:103], v[102:103]
	v_pk_mul_f32 v[110:111], v[116:117], v[110:111]
	v_pk_mul_f32 v[114:115], v[114:115], s[0:1] op_sel_hi:[1,0]
	v_pk_mul_f32 v[116:117], v[100:101], v[110:111]
	v_pk_fma_f32 v[110:111], v[100:101], v[110:111], v[100:101] neg_lo:[1,0,0] neg_hi:[1,0,0]
	v_exp_f32_e32 v114, v114
	v_cndmask_b32_e32 v100, v110, v116, vcc
	v_cmp_gt_f32_e32 vcc, 0, v101
	v_and_b32_e32 v110, 0x7fffffff, v102
	v_exp_f32_e32 v115, v115
	v_cndmask_b32_e32 v101, v111, v117, vcc
	v_and_b32_e32 v111, 0x7fffffff, v103
	v_pk_fma_f32 v[110:111], v[110:111], s[28:29], 1.0 op_sel_hi:[1,0,0]
	v_cmp_gt_f32_e32 vcc, 0, v102
	v_rcp_f32_e32 v110, v110
	v_rcp_f32_e32 v111, v111
	s_nop 0
	v_pk_fma_f32 v[116:117], v[110:111], s[30:31], v[108:109] op_sel_hi:[1,0,0]
	s_nop 0
	v_pk_fma_f32 v[116:117], v[110:111], v[116:117], s[36:37] op_sel_hi:[1,1,0]
	s_nop 0
	v_pk_fma_f32 v[116:117], v[110:111], v[116:117], s[80:81] op_sel_hi:[1,1,0]
	s_nop 0
	v_pk_fma_f32 v[116:117], v[110:111], v[116:117], s[64:65] op_sel_hi:[1,1,0]
	s_nop 0
	v_pk_mul_f32 v[110:111], v[110:111], v[116:117]
	v_pk_mul_f32 v[116:117], v[96:97], v[96:97]
	v_pk_mul_f32 v[110:111], v[114:115], v[110:111]
	v_pk_mul_f32 v[116:117], v[116:117], s[0:1] op_sel_hi:[1,0]
	v_pk_mul_f32 v[114:115], v[102:103], v[110:111]
	v_pk_fma_f32 v[110:111], v[102:103], v[110:111], v[102:103] neg_lo:[1,0,0] neg_hi:[1,0,0]
	v_exp_f32_e32 v116, v116
	v_cndmask_b32_e32 v102, v110, v114, vcc
	v_cmp_gt_f32_e32 vcc, 0, v103
	v_and_b32_e32 v110, 0x7fffffff, v96
	v_exp_f32_e32 v117, v117
	v_cndmask_b32_e32 v103, v111, v115, vcc
	v_and_b32_e32 v111, 0x7fffffff, v97
	v_pk_fma_f32 v[110:111], v[110:111], s[28:29], 1.0 op_sel_hi:[1,0,0]
	v_cmp_gt_f32_e32 vcc, 0, v96
	v_rcp_f32_e32 v110, v110
	v_rcp_f32_e32 v111, v111
	s_nop 0
	v_pk_fma_f32 v[114:115], v[110:111], s[30:31], v[108:109] op_sel_hi:[1,0,0]
	s_nop 0
	v_pk_fma_f32 v[114:115], v[110:111], v[114:115], s[36:37] op_sel_hi:[1,1,0]
	s_nop 0
	v_pk_fma_f32 v[114:115], v[110:111], v[114:115], s[80:81] op_sel_hi:[1,1,0]
	s_nop 0
	v_pk_fma_f32 v[114:115], v[110:111], v[114:115], s[64:65] op_sel_hi:[1,1,0]
	s_nop 0
	v_pk_mul_f32 v[110:111], v[110:111], v[114:115]
	v_pk_mul_f32 v[114:115], v[98:99], v[98:99]
	v_pk_mul_f32 v[110:111], v[116:117], v[110:111]
	s_nop 0
	v_pk_mul_f32 v[116:117], v[96:97], v[110:111]
	v_pk_fma_f32 v[110:111], v[96:97], v[110:111], v[96:97] neg_lo:[1,0,0] neg_hi:[1,0,0]
	s_nop 0
	v_cndmask_b32_e32 v96, v110, v116, vcc
	v_cmp_gt_f32_e32 vcc, 0, v97
	v_and_b32_e32 v110, 0x7fffffff, v98
	s_nop 0
	v_cndmask_b32_e32 v97, v111, v117, vcc
	v_and_b32_e32 v111, 0x7fffffff, v99
	v_pk_fma_f32 v[110:111], v[110:111], s[28:29], 1.0 op_sel_hi:[1,0,0]
	v_cmp_gt_f32_e32 vcc, 0, v98
	v_rcp_f32_e32 v110, v110
	v_rcp_f32_e32 v111, v111
	s_nop 0
	v_pk_fma_f32 v[108:109], v[110:111], s[30:31], v[108:109] op_sel_hi:[1,0,0]
	s_nop 0
	v_pk_fma_f32 v[108:109], v[110:111], v[108:109], s[36:37] op_sel_hi:[1,1,0]
	s_nop 0
	v_pk_fma_f32 v[108:109], v[110:111], v[108:109], s[80:81] op_sel_hi:[1,1,0]
	s_nop 0
	v_pk_fma_f32 v[108:109], v[110:111], v[108:109], s[64:65] op_sel_hi:[1,1,0]
	s_nop 0
	v_pk_mul_f32 v[108:109], v[110:111], v[108:109]
	v_pk_mul_f32 v[110:111], v[114:115], s[0:1] op_sel_hi:[1,0]
	s_nop 0
	v_exp_f32_e32 v110, v110
	v_exp_f32_e32 v111, v111
	s_nop 0
	v_pk_mul_f32 v[108:109], v[110:111], v[108:109]
	s_nop 0
	v_pk_mul_f32 v[110:111], v[98:99], v[108:109]
	v_pk_fma_f32 v[108:109], v[98:99], v[108:109], v[98:99] neg_lo:[1,0,0] neg_hi:[1,0,0]
	s_nop 0
	v_cndmask_b32_e32 v98, v108, v110, vcc
	v_cmp_gt_f32_e32 vcc, 0, v99
	s_nop 1
	v_cndmask_b32_e32 v99, v109, v111, vcc

; __device__ __forceinline__ unsigned cvt_pk_bf16(float lo, float hi) { unsigned r; asm volatile("v_cvt_pk_bf16_f32 %0, %1, %2" : "=v"(r) : "v"(lo), "v"(hi)); return r; }
;     __device__ __forceinline__ void operator()(const f32x4 (&acc)[2][2][4][2], const Unit& u, int wr, int wc, int fr, int fq) const {
;     ...
;                     if (do_stat) { s1 += ((v0[0] + v0[1]) + (v0[2] + v0[3])) + ((v1[0] + v1[1]) + (v1[2] + v1[3]));
;                         s2 += ((v0[0] * v0[0] + v0[1] * v0[1]) + (v0[2] * v0[2] + v0[3] * v0[3])) + ((v1[0] * v1[0] + v1[1] * v1[1]) + (v1[2] * v1[2] + v1[3] * v1[3])); }
;                     u32x4 w; w.x = cvt_pk_bf16(v0[0], v0[1]); w.y = cvt_pk_bf16(v0[2], v0[3]); w.z = cvt_pk_bf16(v1[0], v1[1]); w.w = cvt_pk_bf16(v1[2], v1[3]);
;                     *(u32x4*)(rowp + bj * HALF) = w; }
;                 if (do_stat) { s1 += __shfl_xor(s1, 16); s1 += __shfl_xor(s1, 32); s2 += __shfl_xor(s2, 16); s2 += __shfl_xor(s2, 32);
;                     if (fq == 0) *(f32x2*)(vstat + ((size_t)(row0 + ai * HALF + m * 16) * 8 + (u.pn - vstat_pn0) * 4 + wc) * 2) = (f32x2){s1, s2}; }
.LBB0_304:
	s_and_b64 vcc, exec, s[44:45]
	v_cvt_pk_bf16_f32 v100, v100, v101
	v_cvt_pk_bf16_f32 v101, v102, v103
	v_cvt_pk_bf16_f32 v102, v96, v97
	v_cvt_pk_bf16_f32 v103, v98, v99
	global_store_dwordx4 v[106:107], v[100:103], off offset:256
	s_cbranch_vccnz .LBB0_308
	v_cmp_lt_i32_e32 vcc, v120, v119
	s_nop 1
	v_cndmask_b32_e32 v96, v252, v120, vcc
	v_lshlrev_b32_e32 v97, 2, v96
	ds_bpermute_b32 v96, v97, v108
	ds_bpermute_b32 v97, v97, v109
	v_cmp_lt_i32_e32 vcc, v118, v119
	s_waitcnt lgkmcnt(0)
	v_pk_add_f32 v[96:97], v[108:109], v[96:97]
	v_cndmask_b32_e32 v98, v252, v118, vcc
	v_lshlrev_b32_e32 v99, 2, v98
	ds_bpermute_b32 v98, v99, v96
	ds_bpermute_b32 v99, v99, v97
	s_and_saveexec_b64 s[0:1], s[38:39]
	s_cbranch_execz .LBB0_307
	s_lshl_b32 s4, s60, 2
	s_waitcnt lgkmcnt(0)
	v_pk_add_f32 v[96:97], v[96:97], v[98:99]
	v_or_b32_e32 v98, 16, v112
	s_add_i32 s4, s4, -16
	v_ashrrev_i32_e32 v99, 31, v98
	v_mov_b32_e32 v100, s4
	v_mov_b32_e32 v101, v193
	v_lshl_add_u64 v[98:99], v[98:99], 3, v[100:101]
	v_or_b32_e32 v98, s83, v98
	v_lshl_add_u64 v[98:99], v[98:99], 3, s[20:21]
	global_store_dwordx2 v[98:99], v[96:97], off

; __device__ __forceinline__ unsigned cvt_pk_bf16(float lo, float hi) { unsigned r; asm volatile("v_cvt_pk_bf16_f32 %0, %1, %2" : "=v"(r) : "v"(lo), "v"(hi)); return r; }
; __device__ __forceinline__ f32x2 gelu_pk(f32x2 v) {
;     const f32x2 av = __builtin_elementwise_abs(v), d = av * 0.2316418882f + 1.0f;
;     f32x2 t; t.x = __builtin_amdgcn_rcpf(d.x); t.y = __builtin_amdgcn_rcpf(d.y);
;     f32x2 q = t * 0.5307027145f + (-0.7265760135f); q = q * t + 0.7107068705f; q = q * t + (-0.142248368f); q = q * t + 0.127414796f; q = q * t;
;     const f32x2 s = (v * v) * (-0.72134752044f);
;     f32x2 e; e.x = __builtin_amdgcn_exp2f(s.x); e.y = __builtin_amdgcn_exp2f(s.y);
;     const f32x2 m = v * (q * e), r = v - m;
;     f32x2 o; o.x = v.x < 0.f ? m.x : r.x; o.y = v.y < 0.f ? m.y : r.y; return o;
; }
;     __device__ __forceinline__ void operator()(const f32x4 (&acc)[2][2][4][2], const Unit& u, int wr, int wc, int fr, int fq) const {
;     ...
;             for (int m = 0; m < 4; ++m) { bf16_t* rowp = O + (size_t)(u.pm >> 5) * bgap + (size_t)u.pm * sm + (size_t)u.pn * sn + (size_t)(wr * 64 + fr + ai * HALF + m * 16) * ldc + wc * 32 + 8 * fq; const float sc = rs[ai][m]; float s1 = 0.f, s2 = 0.f;
; #pragma unroll
;                 for (int bj = 0; bj < 2; ++bj) { f32x4 v0 = acc[ai][bj][m][0] * sc, v1 = acc[ai][bj][m][1] * sc;
;                     if (do_gelu) { f32x2 a = gelu_pk((f32x2){v0[0], v0[1]}), b = gelu_pk((f32x2){v0[2], v0[3]}), c = gelu_pk((f32x2){v1[0], v1[1]}), d = gelu_pk((f32x2){v1[2], v1[3]});
;                         v0 = (f32x4){a.x, a.y, b.x, b.y}; v1 = (f32x4){c.x, c.y, d.x, d.y}; }
;                     if (do_stat) { s1 += ((v0[0] + v0[1]) + (v0[2] + v0[3])) + ((v1[0] + v1[1]) + (v1[2] + v1[3]));
;                         s2 += ((v0[0] * v0[0] + v0[1] * v0[1]) + (v0[2] * v0[2] + v0[3] * v0[3])) + ((v1[0] * v1[0] + v1[1] * v1[1]) + (v1[2] * v1[2] + v1[3] * v1[3])); }
;                     u32x4 w; w.x = cvt_pk_bf16(v0[0], v0[1]); w.y = cvt_pk_bf16(v0[2], v0[3]); w.z = cvt_pk_bf16(v1[0], v1[1]); w.w = cvt_pk_bf16(v1[2], v1[3]);
;                     *(u32x4*)(rowp + bj * HALF) = w; }
.LBB0_314:
	v_lshl_add_u64 v[90:91], s[16:17], 0, v[140:141]
	v_lshl_add_u64 v[90:91], v[90:91], 0, s[86:87]
	v_lshl_add_u64 v[90:91], v[90:91], 0, v[192:193]
	v_cvt_pk_bf16_f32 v92, v92, v93
	v_cvt_pk_bf16_f32 v93, v94, v95
	v_mov_b32_e32 v167, v166
	v_cvt_pk_bf16_f32 v94, v98, v99
	v_cvt_pk_bf16_f32 v95, v96, v97
	global_store_dwordx4 v[90:91], v[92:95], off
	v_pk_mul_f32 v[84:85], v[84:85], v[166:167]
	s_and_b64 vcc, exec, s[42:43]
	v_mov_b32_e32 v92, v166
	v_mov_b32_e32 v93, v166
	v_pk_mul_f32 v[86:87], v[86:87], v[92:93]
	v_pk_mul_f32 v[82:83], v[82:83], v[92:93]
	v_pk_mul_f32 v[80:81], v[80:81], v[166:167]
	s_cbranch_vccnz .LBB0_316
	v_and_b32_e32 v93, 0x7fffffff, v85
	v_and_b32_e32 v92, 0x7fffffff, v84
	v_pk_fma_f32 v[92:93], v[92:93], s[28:29], 1.0 op_sel_hi:[1,0,0]
	s_mov_b32 s0, 0xbf3a00e3
	v_rcp_f32_e32 v94, v92
	v_rcp_f32_e32 v95, v93
	v_mov_b64_e32 v[92:93], s[0:1]
	v_pk_mul_f32 v[98:99], v[84:85], v[84:85]
	s_mov_b32 s0, 0xbf38aa3b
	v_pk_fma_f32 v[96:97], v[94:95], s[30:31], v[92:93] op_sel_hi:[1,0,0]
	v_pk_mul_f32 v[98:99], v[98:99], s[0:1] op_sel_hi:[1,0]
	v_pk_fma_f32 v[96:97], v[94:95], v[96:97], s[36:37] op_sel_hi:[1,1,0]
	v_exp_f32_e32 v98, v98
	v_exp_f32_e32 v99, v99
	v_pk_fma_f32 v[96:97], v[94:95], v[96:97], s[80:81] op_sel_hi:[1,1,0]
	v_cmp_gt_f32_e32 vcc, 0, v84
	v_pk_fma_f32 v[96:97], v[94:95], v[96:97], s[64:65] op_sel_hi:[1,1,0]
	s_nop 0
	v_pk_mul_f32 v[94:95], v[94:95], v[96:97]
	v_pk_mul_f32 v[96:97], v[86:87], v[86:87]
	v_pk_mul_f32 v[94:95], v[98:99], v[94:95]
	v_pk_mul_f32 v[96:97], v[96:97], s[0:1] op_sel_hi:[1,0]
	v_pk_mul_f32 v[98:99], v[84:85], v[94:95]
	v_pk_fma_f32 v[94:95], v[84:85], v[94:95], v[84:85] neg_lo:[1,0,0] neg_hi:[1,0,0]
	v_exp_f32_e32 v96, v96
	v_cndmask_b32_e32 v84, v94, v98, vcc
	v_cmp_gt_f32_e32 vcc, 0, v85
	v_and_b32_e32 v94, 0x7fffffff, v86
	v_exp_f32_e32 v97, v97
	v_cndmask_b32_e32 v85, v95, v99, vcc
	v_and_b32_e32 v95, 0x7fffffff, v87
	v_pk_fma_f32 v[94:95], v[94:95], s[28:29], 1.0 op_sel_hi:[1,0,0]
	v_cmp_gt_f32_e32 vcc, 0, v86
	v_rcp_f32_e32 v94, v94
	v_rcp_f32_e32 v95, v95
	s_nop 0
	v_pk_fma_f32 v[98:99], v[94:95], s[30:31], v[92:93] op_sel_hi:[1,0,0]
	s_nop 0
	v_pk_fma_f32 v[98:99], v[94:95], v[98:99], s[36:37] op_sel_hi:[1,1,0]
	s_nop 0
	v_pk_fma_f32 v[98:99], v[94:95], v[98:99], s[80:81] op_sel_hi:[1,1,0]
	s_nop 0
	v_pk_fma_f32 v[98:99], v[94:95], v[98:99], s[64:65] op_sel_hi:[1,1,0]
	s_nop 0
	v_pk_mul_f32 v[94:95], v[94:95], v[98:99]
	v_pk_mul_f32 v[98:99], v[80:81], v[80:81]
	v_pk_mul_f32 v[94:95], v[96:97], v[94:95]
	v_pk_mul_f32 v[98:99], v[98:99], s[0:1] op_sel_hi:[1,0]
	v_pk_mul_f32 v[96:97], v[86:87], v[94:95]
	v_pk_fma_f32 v[94:95], v[86:87], v[94:95], v[86:87] neg_lo:[1,0,0] neg_hi:[1,0,0]
	v_exp_f32_e32 v98, v98
	v_cndmask_b32_e32 v86, v94, v96, vcc
	v_cmp_gt_f32_e32 vcc, 0, v87
	v_and_b32_e32 v94, 0x7fffffff, v80
	v_exp_f32_e32 v99, v99
	v_cndmask_b32_e32 v87, v95, v97, vcc
	v_and_b32_e32 v95, 0x7fffffff, v81
	v_pk_fma_f32 v[94:95], v[94:95], s[28:29], 1.0 op_sel_hi:[1,0,0]
	v_cmp_gt_f32_e32 vcc, 0, v80
	v_rcp_f32_e32 v94, v94
	v_rcp_f32_e32 v95, v95
	s_nop 0
	v_pk_fma_f32 v[96:97], v[94:95], s[30:31], v[92:93] op_sel_hi:[1,0,0]
	s_nop 0
	v_pk_fma_f32 v[96:97], v[94:95], v[96:97], s[36:37] op_sel_hi:[1,1,0]
	s_nop 0
	v_pk_fma_f32 v[96:97], v[94:95], v[96:97], s[80:81] op_sel_hi:[1,1,0]
	s_nop 0
	v_pk_fma_f32 v[96:97], v[94:95], v[96:97], s[64:65] op_sel_hi:[1,1,0]
	s_nop 0
	v_pk_mul_f32 v[94:95], v[94:95], v[96:97]
	v_pk_mul_f32 v[96:97], v[82:83], v[82:83]
	v_pk_mul_f32 v[94:95], v[98:99], v[94:95]
	s_nop 0
	v_pk_mul_f32 v[98:99], v[80:81], v[94:95]
	v_pk_fma_f32 v[94:95], v[80:81], v[94:95], v[80:81] neg_lo:[1,0,0] neg_hi:[1,0,0]
	s_nop 0
	v_cndmask_b32_e32 v80, v94, v98, vcc
	v_cmp_gt_f32_e32 vcc, 0, v81
	v_and_b32_e32 v94, 0x7fffffff, v82
	s_nop 0
	v_cndmask_b32_e32 v81, v95, v99, vcc
	v_and_b32_e32 v95, 0x7fffffff, v83
	v_pk_fma_f32 v[94:95], v[94:95], s[28:29], 1.0 op_sel_hi:[1,0,0]
	v_cmp_gt_f32_e32 vcc, 0, v82
	v_rcp_f32_e32 v94, v94
	v_rcp_f32_e32 v95, v95
	s_nop 0
	v_pk_fma_f32 v[92:93], v[94:95], s[30:31], v[92:93] op_sel_hi:[1,0,0]
	s_nop 0
	v_pk_fma_f32 v[92:93], v[94:95], v[92:93], s[36:37] op_sel_hi:[1,1,0]
	s_nop 0
	v_pk_fma_f32 v[92:93], v[94:95], v[92:93], s[80:81] op_sel_hi:[1,1,0]
	s_nop 0
	v_pk_fma_f32 v[92:93], v[94:95], v[92:93], s[64:65] op_sel_hi:[1,1,0]
	s_nop 0
	v_pk_mul_f32 v[92:93], v[94:95], v[92:93]
	v_pk_mul_f32 v[94:95], v[96:97], s[0:1] op_sel_hi:[1,0]
	s_nop 0
	v_exp_f32_e32 v94, v94
	v_exp_f32_e32 v95, v95
	s_nop 0
	v_pk_mul_f32 v[92:93], v[94:95], v[92:93]
	s_nop 0
	v_pk_mul_f32 v[94:95], v[82:83], v[92:93]
	v_pk_fma_f32 v[92:93], v[82:83], v[92:93], v[82:83] neg_lo:[1,0,0] neg_hi:[1,0,0]
	s_nop 0
	v_cndmask_b32_e32 v82, v92, v94, vcc
	v_cmp_gt_f32_e32 vcc, 0, v83
	s_nop 1
	v_cndmask_b32_e32 v83, v93, v95, vcc

; __device__ __forceinline__ unsigned cvt_pk_bf16(float lo, float hi) { unsigned r; asm volatile("v_cvt_pk_bf16_f32 %0, %1, %2" : "=v"(r) : "v"(lo), "v"(hi)); return r; }
;     __device__ __forceinline__ void operator()(const f32x4 (&acc)[2][2][4][2], const Unit& u, int wr, int wc, int fr, int fq) const {
;     ...
;                     if (do_stat) { s1 += ((v0[0] + v0[1]) + (v0[2] + v0[3])) + ((v1[0] + v1[1]) + (v1[2] + v1[3]));
;                         s2 += ((v0[0] * v0[0] + v0[1] * v0[1]) + (v0[2] * v0[2] + v0[3] * v0[3])) + ((v1[0] * v1[0] + v1[1] * v1[1]) + (v1[2] * v1[2] + v1[3] * v1[3])); }
;                     u32x4 w; w.x = cvt_pk_bf16(v0[0], v0[1]); w.y = cvt_pk_bf16(v0[2], v0[3]); w.z = cvt_pk_bf16(v1[0], v1[1]); w.w = cvt_pk_bf16(v1[2], v1[3]);
;                     *(u32x4*)(rowp + bj * HALF) = w; }
;                 if (do_stat) { s1 += __shfl_xor(s1, 16); s1 += __shfl_xor(s1, 32); s2 += __shfl_xor(s2, 16); s2 += __shfl_xor(s2, 32);
;                     if (fq == 0) *(f32x2*)(vstat + ((size_t)(row0 + ai * HALF + m * 16) * 8 + (u.pn - vstat_pn0) * 4 + wc) * 2) = (f32x2){s1, s2}; }
.LBB0_320:
	s_and_b64 vcc, exec, s[44:45]
	v_cvt_pk_bf16_f32 v84, v84, v85
	v_cvt_pk_bf16_f32 v85, v86, v87
	v_cvt_pk_bf16_f32 v86, v80, v81
	v_cvt_pk_bf16_f32 v87, v82, v83
	global_store_dwordx4 v[90:91], v[84:87], off offset:256
	s_cbranch_vccnz .LBB0_324
	v_cmp_lt_i32_e32 vcc, v120, v119
	s_nop 1
	v_cndmask_b32_e32 v80, v252, v120, vcc
	v_lshlrev_b32_e32 v81, 2, v80
	ds_bpermute_b32 v80, v81, v92
	ds_bpermute_b32 v81, v81, v93
	v_cmp_lt_i32_e32 vcc, v118, v119
	s_waitcnt lgkmcnt(0)
	v_pk_add_f32 v[80:81], v[92:93], v[80:81]
	v_cndmask_b32_e32 v82, v252, v118, vcc
	v_lshlrev_b32_e32 v83, 2, v82
	ds_bpermute_b32 v82, v83, v80
	ds_bpermute_b32 v83, v83, v81
	s_and_saveexec_b64 s[0:1], s[38:39]
	s_cbranch_execz .LBB0_323
	s_lshl_b32 s4, s60, 2
	s_waitcnt lgkmcnt(0)
	v_pk_add_f32 v[80:81], v[80:81], v[82:83]
	v_or_b32_e32 v82, 32, v112
	s_add_i32 s4, s4, -16
	v_ashrrev_i32_e32 v83, 31, v82
	v_mov_b32_e32 v84, s4
	v_mov_b32_e32 v85, v193
	v_lshl_add_u64 v[82:83], v[82:83], 3, v[84:85]
	v_or_b32_e32 v82, s83, v82
	v_lshl_add_u64 v[82:83], v[82:83], 3, s[20:21]
	global_store_dwordx2 v[82:83], v[80:81], off

; __device__ __forceinline__ unsigned cvt_pk_bf16(float lo, float hi) { unsigned r; asm volatile("v_cvt_pk_bf16_f32 %0, %1, %2" : "=v"(r) : "v"(lo), "v"(hi)); return r; }
; __device__ __forceinline__ f32x2 gelu_pk(f32x2 v) {
;     const f32x2 av = __builtin_elementwise_abs(v), d = av * 0.2316418882f + 1.0f;
;     f32x2 t; t.x = __builtin_amdgcn_rcpf(d.x); t.y = __builtin_amdgcn_rcpf(d.y);
;     f32x2 q = t * 0.5307027145f + (-0.7265760135f); q = q * t + 0.7107068705f; q = q * t + (-0.142248368f); q = q * t + 0.127414796f; q = q * t;
;     const f32x2 s = (v * v) * (-0.72134752044f);
;     f32x2 e; e.x = __builtin_amdgcn_exp2f(s.x); e.y = __builtin_amdgcn_exp2f(s.y);
;     const f32x2 m = v * (q * e), r = v - m;
;     f32x2 o; o.x = v.x < 0.f ? m.x : r.x; o.y = v.y < 0.f ? m.y : r.y; return o;
; }
;     __device__ __forceinline__ void operator()(const f32x4 (&acc)[2][2][4][2], const Unit& u, int wr, int wc, int fr, int fq) const {
;     ...
;             for (int m = 0; m < 4; ++m) { bf16_t* rowp = O + (size_t)(u.pm >> 5) * bgap + (size_t)u.pm * sm + (size_t)u.pn * sn + (size_t)(wr * 64 + fr + ai * HALF + m * 16) * ldc + wc * 32 + 8 * fq; const float sc = rs[ai][m]; float s1 = 0.f, s2 = 0.f;
; #pragma unroll
;                 for (int bj = 0; bj < 2; ++bj) { f32x4 v0 = acc[ai][bj][m][0] * sc, v1 = acc[ai][bj][m][1] * sc;
;                     if (do_gelu) { f32x2 a = gelu_pk((f32x2){v0[0], v0[1]}), b = gelu_pk((f32x2){v0[2], v0[3]}), c = gelu_pk((f32x2){v1[0], v1[1]}), d = gelu_pk((f32x2){v1[2], v1[3]});
;                         v0 = (f32x4){a.x, a.y, b.x, b.y}; v1 = (f32x4){c.x, c.y, d.x, d.y}; }
;                     if (do_stat) { s1 += ((v0[0] + v0[1]) + (v0[2] + v0[3])) + ((v1[0] + v1[1]) + (v1[2] + v1[3]));
;                         s2 += ((v0[0] * v0[0] + v0[1] * v0[1]) + (v0[2] * v0[2] + v0[3] * v0[3])) + ((v1[0] * v1[0] + v1[1] * v1[1]) + (v1[2] * v1[2] + v1[3] * v1[3])); }
;                     u32x4 w; w.x = cvt_pk_bf16(v0[0], v0[1]); w.y = cvt_pk_bf16(v0[2], v0[3]); w.z = cvt_pk_bf16(v1[0], v1[1]); w.w = cvt_pk_bf16(v1[2], v1[3]);
;                     *(u32x4*)(rowp + bj * HALF) = w; }
.LBB0_330:
	v_lshl_add_u64 v[74:75], s[16:17], 0, v[142:143]
	v_lshl_add_u64 v[74:75], v[74:75], 0, s[86:87]
	v_lshl_add_u64 v[74:75], v[74:75], 0, v[192:193]
	v_cvt_pk_bf16_f32 v76, v76, v77
	v_cvt_pk_bf16_f32 v77, v78, v79
	v_mov_b32_e32 v165, v164
	v_cvt_pk_bf16_f32 v78, v82, v83
	v_cvt_pk_bf16_f32 v79, v80, v81
	global_store_dwordx4 v[74:75], v[76:79], off
	v_pk_mul_f32 v[68:69], v[68:69], v[164:165]
	s_and_b64 vcc, exec, s[42:43]
	v_mov_b32_e32 v76, v164
	v_mov_b32_e32 v77, v164
	v_pk_mul_f32 v[70:71], v[70:71], v[76:77]
	v_pk_mul_f32 v[66:67], v[66:67], v[76:77]
	v_pk_mul_f32 v[64:65], v[64:65], v[164:165]
	s_cbranch_vccnz .LBB0_332
	v_and_b32_e32 v77, 0x7fffffff, v69
	v_and_b32_e32 v76, 0x7fffffff, v68
	v_pk_fma_f32 v[76:77], v[76:77], s[28:29], 1.0 op_sel_hi:[1,0,0]
	s_mov_b32 s0, 0xbf3a00e3
	v_rcp_f32_e32 v78, v76
	v_rcp_f32_e32 v79, v77
	v_mov_b64_e32 v[76:77], s[0:1]
	v_pk_mul_f32 v[82:83], v[68:69], v[68:69]
	s_mov_b32 s0, 0xbf38aa3b
	v_pk_fma_f32 v[80:81], v[78:79], s[30:31], v[76:77] op_sel_hi:[1,0,0]
	v_pk_mul_f32 v[82:83], v[82:83], s[0:1] op_sel_hi:[1,0]
	v_pk_fma_f32 v[80:81], v[78:79], v[80:81], s[36:37] op_sel_hi:[1,1,0]
	v_exp_f32_e32 v82, v82
	v_exp_f32_e32 v83, v83
	v_pk_fma_f32 v[80:81], v[78:79], v[80:81], s[80:81] op_sel_hi:[1,1,0]
	v_cmp_gt_f32_e32 vcc, 0, v68
	v_pk_fma_f32 v[80:81], v[78:79], v[80:81], s[64:65] op_sel_hi:[1,1,0]
	s_nop 0
	v_pk_mul_f32 v[78:79], v[78:79], v[80:81]
	v_pk_mul_f32 v[80:81], v[70:71], v[70:71]
	v_pk_mul_f32 v[78:79], v[82:83], v[78:79]
	v_pk_mul_f32 v[80:81], v[80:81], s[0:1] op_sel_hi:[1,0]
	v_pk_mul_f32 v[82:83], v[68:69], v[78:79]
	v_pk_fma_f32 v[78:79], v[68:69], v[78:79], v[68:69] neg_lo:[1,0,0] neg_hi:[1,0,0]
	v_exp_f32_e32 v80, v80
	v_cndmask_b32_e32 v68, v78, v82, vcc
	v_cmp_gt_f32_e32 vcc, 0, v69
	v_and_b32_e32 v78, 0x7fffffff, v70
	v_exp_f32_e32 v81, v81
	v_cndmask_b32_e32 v69, v79, v83, vcc
	v_and_b32_e32 v79, 0x7fffffff, v71
	v_pk_fma_f32 v[78:79], v[78:79], s[28:29], 1.0 op_sel_hi:[1,0,0]
	v_cmp_gt_f32_e32 vcc, 0, v70
	v_rcp_f32_e32 v78, v78
	v_rcp_f32_e32 v79, v79
	s_nop 0
	v_pk_fma_f32 v[82:83], v[78:79], s[30:31], v[76:77] op_sel_hi:[1,0,0]
	s_nop 0
	v_pk_fma_f32 v[82:83], v[78:79], v[82:83], s[36:37] op_sel_hi:[1,1,0]
	s_nop 0
	v_pk_fma_f32 v[82:83], v[78:79], v[82:83], s[80:81] op_sel_hi:[1,1,0]
	s_nop 0
	v_pk_fma_f32 v[82:83], v[78:79], v[82:83], s[64:65] op_sel_hi:[1,1,0]
	s_nop 0
	v_pk_mul_f32 v[78:79], v[78:79], v[82:83]
	v_pk_mul_f32 v[82:83], v[64:65], v[64:65]
	v_pk_mul_f32 v[78:79], v[80:81], v[78:79]
	v_pk_mul_f32 v[82:83], v[82:83], s[0:1] op_sel_hi:[1,0]
	v_pk_mul_f32 v[80:81], v[70:71], v[78:79]
	v_pk_fma_f32 v[78:79], v[70:71], v[78:79], v[70:71] neg_lo:[1,0,0] neg_hi:[1,0,0]
	v_exp_f32_e32 v82, v82
	v_cndmask_b32_e32 v70, v78, v80, vcc
	v_cmp_gt_f32_e32 vcc, 0, v71
	v_and_b32_e32 v78, 0x7fffffff, v64
	v_exp_f32_e32 v83, v83
	v_cndmask_b32_e32 v71, v79, v81, vcc
	v_and_b32_e32 v79, 0x7fffffff, v65
	v_pk_fma_f32 v[78:79], v[78:79], s[28:29], 1.0 op_sel_hi:[1,0,0]
	v_cmp_gt_f32_e32 vcc, 0, v64
	v_rcp_f32_e32 v78, v78
	v_rcp_f32_e32 v79, v79
	s_nop 0
	v_pk_fma_f32 v[80:81], v[78:79], s[30:31], v[76:77] op_sel_hi:[1,0,0]
	s_nop 0
	v_pk_fma_f32 v[80:81], v[78:79], v[80:81], s[36:37] op_sel_hi:[1,1,0]
	s_nop 0
	v_pk_fma_f32 v[80:81], v[78:79], v[80:81], s[80:81] op_sel_hi:[1,1,0]
	s_nop 0
	v_pk_fma_f32 v[80:81], v[78:79], v[80:81], s[64:65] op_sel_hi:[1,1,0]
	s_nop 0
	v_pk_mul_f32 v[78:79], v[78:79], v[80:81]
	v_pk_mul_f32 v[80:81], v[66:67], v[66:67]
	v_pk_mul_f32 v[78:79], v[82:83], v[78:79]
	s_nop 0
	v_pk_mul_f32 v[82:83], v[64:65], v[78:79]
	v_pk_fma_f32 v[78:79], v[64:65], v[78:79], v[64:65] neg_lo:[1,0,0] neg_hi:[1,0,0]
	s_nop 0
	v_cndmask_b32_e32 v64, v78, v82, vcc
	v_cmp_gt_f32_e32 vcc, 0, v65
	v_and_b32_e32 v78, 0x7fffffff, v66
	s_nop 0
	v_cndmask_b32_e32 v65, v79, v83, vcc
	v_and_b32_e32 v79, 0x7fffffff, v67
	v_pk_fma_f32 v[78:79], v[78:79], s[28:29], 1.0 op_sel_hi:[1,0,0]
	v_cmp_gt_f32_e32 vcc, 0, v66
	v_rcp_f32_e32 v78, v78
	v_rcp_f32_e32 v79, v79
	s_nop 0
	v_pk_fma_f32 v[76:77], v[78:79], s[30:31], v[76:77] op_sel_hi:[1,0,0]
	s_nop 0
	v_pk_fma_f32 v[76:77], v[78:79], v[76:77], s[36:37] op_sel_hi:[1,1,0]
	s_nop 0
	v_pk_fma_f32 v[76:77], v[78:79], v[76:77], s[80:81] op_sel_hi:[1,1,0]
	s_nop 0
	v_pk_fma_f32 v[76:77], v[78:79], v[76:77], s[64:65] op_sel_hi:[1,1,0]
	s_nop 0
	v_pk_mul_f32 v[76:77], v[78:79], v[76:77]
	v_pk_mul_f32 v[78:79], v[80:81], s[0:1] op_sel_hi:[1,0]
	s_nop 0
	v_exp_f32_e32 v78, v78
	v_exp_f32_e32 v79, v79
	s_nop 0
	v_pk_mul_f32 v[76:77], v[78:79], v[76:77]
	s_nop 0
	v_pk_mul_f32 v[78:79], v[66:67], v[76:77]
	v_pk_fma_f32 v[76:77], v[66:67], v[76:77], v[66:67] neg_lo:[1,0,0] neg_hi:[1,0,0]
	s_nop 0
	v_cndmask_b32_e32 v66, v76, v78, vcc
	v_cmp_gt_f32_e32 vcc, 0, v67
	s_nop 1
	v_cndmask_b32_e32 v67, v77, v79, vcc

; __device__ __forceinline__ unsigned cvt_pk_bf16(float lo, float hi) { unsigned r; asm volatile("v_cvt_pk_bf16_f32 %0, %1, %2" : "=v"(r) : "v"(lo), "v"(hi)); return r; }
;     __device__ __forceinline__ void operator()(const f32x4 (&acc)[2][2][4][2], const Unit& u, int wr, int wc, int fr, int fq) const {
;     ...
;                     if (do_stat) { s1 += ((v0[0] + v0[1]) + (v0[2] + v0[3])) + ((v1[0] + v1[1]) + (v1[2] + v1[3]));
;                         s2 += ((v0[0] * v0[0] + v0[1] * v0[1]) + (v0[2] * v0[2] + v0[3] * v0[3])) + ((v1[0] * v1[0] + v1[1] * v1[1]) + (v1[2] * v1[2] + v1[3] * v1[3])); }
;                     u32x4 w; w.x = cvt_pk_bf16(v0[0], v0[1]); w.y = cvt_pk_bf16(v0[2], v0[3]); w.z = cvt_pk_bf16(v1[0], v1[1]); w.w = cvt_pk_bf16(v1[2], v1[3]);
;                     *(u32x4*)(rowp + bj * HALF) = w; }
;                 if (do_stat) { s1 += __shfl_xor(s1, 16); s1 += __shfl_xor(s1, 32); s2 += __shfl_xor(s2, 16); s2 += __shfl_xor(s2, 32);
;                     if (fq == 0) *(f32x2*)(vstat + ((size_t)(row0 + ai * HALF + m * 16) * 8 + (u.pn - vstat_pn0) * 4 + wc) * 2) = (f32x2){s1, s2}; }
.LBB0_336:
	s_and_b64 vcc, exec, s[44:45]
	v_cvt_pk_bf16_f32 v68, v68, v69
	v_cvt_pk_bf16_f32 v69, v70, v71
	v_cvt_pk_bf16_f32 v70, v64, v65
	v_cvt_pk_bf16_f32 v71, v66, v67
	global_store_dwordx4 v[74:75], v[68:71], off offset:256
	s_cbranch_vccnz .LBB0_340
	v_cmp_lt_i32_e32 vcc, v120, v119
	s_nop 1
	v_cndmask_b32_e32 v64, v252, v120, vcc
	v_lshlrev_b32_e32 v65, 2, v64
	ds_bpermute_b32 v64, v65, v76
	ds_bpermute_b32 v65, v65, v77
	v_cmp_lt_i32_e32 vcc, v118, v119
	s_waitcnt lgkmcnt(0)
	v_pk_add_f32 v[64:65], v[76:77], v[64:65]
	v_cndmask_b32_e32 v66, v252, v118, vcc
	v_lshlrev_b32_e32 v67, 2, v66
	ds_bpermute_b32 v66, v67, v64
	ds_bpermute_b32 v67, v67, v65
	s_and_saveexec_b64 s[0:1], s[38:39]
	s_cbranch_execz .LBB0_339
	s_lshl_b32 s4, s60, 2
	s_waitcnt lgkmcnt(0)
	v_pk_add_f32 v[64:65], v[64:65], v[66:67]
	v_or_b32_e32 v66, 48, v112
	s_add_i32 s4, s4, -16
	v_ashrrev_i32_e32 v67, 31, v66
	v_mov_b32_e32 v68, s4
	v_mov_b32_e32 v69, v193
	v_lshl_add_u64 v[66:67], v[66:67], 3, v[68:69]
	v_or_b32_e32 v66, s83, v66
	v_lshl_add_u64 v[66:67], v[66:67], 3, s[20:21]
	global_store_dwordx2 v[66:67], v[64:65], off

; __device__ __forceinline__ unsigned cvt_pk_bf16(float lo, float hi) { unsigned r; asm volatile("v_cvt_pk_bf16_f32 %0, %1, %2" : "=v"(r) : "v"(lo), "v"(hi)); return r; }
; __device__ __forceinline__ f32x2 gelu_pk(f32x2 v) {
;     const f32x2 av = __builtin_elementwise_abs(v), d = av * 0.2316418882f + 1.0f;
;     f32x2 t; t.x = __builtin_amdgcn_rcpf(d.x); t.y = __builtin_amdgcn_rcpf(d.y);
;     f32x2 q = t * 0.5307027145f + (-0.7265760135f); q = q * t + 0.7107068705f; q = q * t + (-0.142248368f); q = q * t + 0.127414796f; q = q * t;
;     const f32x2 s = (v * v) * (-0.72134752044f);
;     f32x2 e; e.x = __builtin_amdgcn_exp2f(s.x); e.y = __builtin_amdgcn_exp2f(s.y);
;     const f32x2 m = v * (q * e), r = v - m;
;     f32x2 o; o.x = v.x < 0.f ? m.x : r.x; o.y = v.y < 0.f ? m.y : r.y; return o;
; }
;     __device__ __forceinline__ void operator()(const f32x4 (&acc)[2][2][4][2], const Unit& u, int wr, int wc, int fr, int fq) const {
;     ...
;             for (int m = 0; m < 4; ++m) { bf16_t* rowp = O + (size_t)(u.pm >> 5) * bgap + (size_t)u.pm * sm + (size_t)u.pn * sn + (size_t)(wr * 64 + fr + ai * HALF + m * 16) * ldc + wc * 32 + 8 * fq; const float sc = rs[ai][m]; float s1 = 0.f, s2 = 0.f;
; #pragma unroll
;                 for (int bj = 0; bj < 2; ++bj) { f32x4 v0 = acc[ai][bj][m][0] * sc, v1 = acc[ai][bj][m][1] * sc;
;                     if (do_gelu) { f32x2 a = gelu_pk((f32x2){v0[0], v0[1]}), b = gelu_pk((f32x2){v0[2], v0[3]}), c = gelu_pk((f32x2){v1[0], v1[1]}), d = gelu_pk((f32x2){v1[2], v1[3]});
;                         v0 = (f32x4){a.x, a.y, b.x, b.y}; v1 = (f32x4){c.x, c.y, d.x, d.y}; }
;                     if (do_stat) { s1 += ((v0[0] + v0[1]) + (v0[2] + v0[3])) + ((v1[0] + v1[1]) + (v1[2] + v1[3]));
;                         s2 += ((v0[0] * v0[0] + v0[1] * v0[1]) + (v0[2] * v0[2] + v0[3] * v0[3])) + ((v1[0] * v1[0] + v1[1] * v1[1]) + (v1[2] * v1[2] + v1[3] * v1[3])); }
;                     u32x4 w; w.x = cvt_pk_bf16(v0[0], v0[1]); w.y = cvt_pk_bf16(v0[2], v0[3]); w.z = cvt_pk_bf16(v1[0], v1[1]); w.w = cvt_pk_bf16(v1[2], v1[3]);
;                     *(u32x4*)(rowp + bj * HALF) = w; }
.LBB0_346:
	v_lshl_add_u64 v[58:59], s[16:17], 0, v[144:145]
	v_lshl_add_u64 v[58:59], v[58:59], 0, s[86:87]
	v_lshl_add_u64 v[58:59], v[58:59], 0, v[192:193]
	v_cvt_pk_bf16_f32 v60, v60, v61
	v_cvt_pk_bf16_f32 v61, v62, v63
	v_mov_b32_e32 v163, v162
	v_cvt_pk_bf16_f32 v62, v66, v67
	v_cvt_pk_bf16_f32 v63, v64, v65
	global_store_dwordx4 v[58:59], v[60:63], off
	v_pk_mul_f32 v[52:53], v[52:53], v[162:163]
	s_and_b64 vcc, exec, s[42:43]
	v_mov_b32_e32 v60, v162
	v_mov_b32_e32 v61, v162
	v_pk_mul_f32 v[54:55], v[54:55], v[60:61]
	v_pk_mul_f32 v[50:51], v[50:51], v[60:61]
	v_pk_mul_f32 v[48:49], v[48:49], v[162:163]
	s_cbranch_vccnz .LBB0_348
	v_and_b32_e32 v61, 0x7fffffff, v53
	v_and_b32_e32 v60, 0x7fffffff, v52
	v_pk_fma_f32 v[60:61], v[60:61], s[28:29], 1.0 op_sel_hi:[1,0,0]
	s_mov_b32 s0, 0xbf3a00e3
	v_rcp_f32_e32 v62, v60
	v_rcp_f32_e32 v63, v61
	v_mov_b64_e32 v[60:61], s[0:1]
	v_pk_mul_f32 v[66:67], v[52:53], v[52:53]
	s_mov_b32 s0, 0xbf38aa3b
	v_pk_fma_f32 v[64:65], v[62:63], s[30:31], v[60:61] op_sel_hi:[1,0,0]
	v_pk_mul_f32 v[66:67], v[66:67], s[0:1] op_sel_hi:[1,0]
	v_pk_fma_f32 v[64:65], v[62:63], v[64:65], s[36:37] op_sel_hi:[1,1,0]
	v_exp_f32_e32 v66, v66
	v_exp_f32_e32 v67, v67
	v_pk_fma_f32 v[64:65], v[62:63], v[64:65], s[80:81] op_sel_hi:[1,1,0]
	v_cmp_gt_f32_e32 vcc, 0, v52
	v_pk_fma_f32 v[64:65], v[62:63], v[64:65], s[64:65] op_sel_hi:[1,1,0]
	s_nop 0
	v_pk_mul_f32 v[62:63], v[62:63], v[64:65]
	v_pk_mul_f32 v[64:65], v[54:55], v[54:55]
	v_pk_mul_f32 v[62:63], v[66:67], v[62:63]
	v_pk_mul_f32 v[64:65], v[64:65], s[0:1] op_sel_hi:[1,0]
	v_pk_mul_f32 v[66:67], v[52:53], v[62:63]
	v_pk_fma_f32 v[62:63], v[52:53], v[62:63], v[52:53] neg_lo:[1,0,0] neg_hi:[1,0,0]
	v_exp_f32_e32 v64, v64
	v_cndmask_b32_e32 v52, v62, v66, vcc
	v_cmp_gt_f32_e32 vcc, 0, v53
	v_and_b32_e32 v62, 0x7fffffff, v54
	v_exp_f32_e32 v65, v65
	v_cndmask_b32_e32 v53, v63, v67, vcc
	v_and_b32_e32 v63, 0x7fffffff, v55
	v_pk_fma_f32 v[62:63], v[62:63], s[28:29], 1.0 op_sel_hi:[1,0,0]
	v_cmp_gt_f32_e32 vcc, 0, v54
	v_rcp_f32_e32 v62, v62
	v_rcp_f32_e32 v63, v63
	s_nop 0
	v_pk_fma_f32 v[66:67], v[62:63], s[30:31], v[60:61] op_sel_hi:[1,0,0]
	s_nop 0
	v_pk_fma_f32 v[66:67], v[62:63], v[66:67], s[36:37] op_sel_hi:[1,1,0]
	s_nop 0
	v_pk_fma_f32 v[66:67], v[62:63], v[66:67], s[80:81] op_sel_hi:[1,1,0]
	s_nop 0
	v_pk_fma_f32 v[66:67], v[62:63], v[66:67], s[64:65] op_sel_hi:[1,1,0]
	s_nop 0
	v_pk_mul_f32 v[62:63], v[62:63], v[66:67]
	v_pk_mul_f32 v[66:67], v[48:49], v[48:49]
	v_pk_mul_f32 v[62:63], v[64:65], v[62:63]
	v_pk_mul_f32 v[66:67], v[66:67], s[0:1] op_sel_hi:[1,0]
	v_pk_mul_f32 v[64:65], v[54:55], v[62:63]
	v_pk_fma_f32 v[62:63], v[54:55], v[62:63], v[54:55] neg_lo:[1,0,0] neg_hi:[1,0,0]
	v_exp_f32_e32 v66, v66
	v_cndmask_b32_e32 v54, v62, v64, vcc
	v_cmp_gt_f32_e32 vcc, 0, v55
	v_and_b32_e32 v62, 0x7fffffff, v48
	v_exp_f32_e32 v67, v67
	v_cndmask_b32_e32 v55, v63, v65, vcc
	v_and_b32_e32 v63, 0x7fffffff, v49
	v_pk_fma_f32 v[62:63], v[62:63], s[28:29], 1.0 op_sel_hi:[1,0,0]
	v_cmp_gt_f32_e32 vcc, 0, v48
	v_rcp_f32_e32 v62, v62
	v_rcp_f32_e32 v63, v63
	s_nop 0
	v_pk_fma_f32 v[64:65], v[62:63], s[30:31], v[60:61] op_sel_hi:[1,0,0]
	s_nop 0
	v_pk_fma_f32 v[64:65], v[62:63], v[64:65], s[36:37] op_sel_hi:[1,1,0]
	s_nop 0
	v_pk_fma_f32 v[64:65], v[62:63], v[64:65], s[80:81] op_sel_hi:[1,1,0]
	s_nop 0
	v_pk_fma_f32 v[64:65], v[62:63], v[64:65], s[64:65] op_sel_hi:[1,1,0]
	s_nop 0
	v_pk_mul_f32 v[62:63], v[62:63], v[64:65]
	v_pk_mul_f32 v[64:65], v[50:51], v[50:51]
	v_pk_mul_f32 v[62:63], v[66:67], v[62:63]
	s_nop 0
	v_pk_mul_f32 v[66:67], v[48:49], v[62:63]
	v_pk_fma_f32 v[62:63], v[48:49], v[62:63], v[48:49] neg_lo:[1,0,0] neg_hi:[1,0,0]
	s_nop 0
	v_cndmask_b32_e32 v48, v62, v66, vcc
	v_cmp_gt_f32_e32 vcc, 0, v49
	v_and_b32_e32 v62, 0x7fffffff, v50
	s_nop 0
	v_cndmask_b32_e32 v49, v63, v67, vcc
	v_and_b32_e32 v63, 0x7fffffff, v51
	v_pk_fma_f32 v[62:63], v[62:63], s[28:29], 1.0 op_sel_hi:[1,0,0]
	v_cmp_gt_f32_e32 vcc, 0, v50
	v_rcp_f32_e32 v62, v62
	v_rcp_f32_e32 v63, v63
	s_nop 0
	v_pk_fma_f32 v[60:61], v[62:63], s[30:31], v[60:61] op_sel_hi:[1,0,0]
	s_nop 0
	v_pk_fma_f32 v[60:61], v[62:63], v[60:61], s[36:37] op_sel_hi:[1,1,0]
	s_nop 0
	v_pk_fma_f32 v[60:61], v[62:63], v[60:61], s[80:81] op_sel_hi:[1,1,0]
	s_nop 0
	v_pk_fma_f32 v[60:61], v[62:63], v[60:61], s[64:65] op_sel_hi:[1,1,0]
	s_nop 0
	v_pk_mul_f32 v[60:61], v[62:63], v[60:61]
	v_pk_mul_f32 v[62:63], v[64:65], s[0:1] op_sel_hi:[1,0]
	s_nop 0
	v_exp_f32_e32 v62, v62
	v_exp_f32_e32 v63, v63
	s_nop 0
	v_pk_mul_f32 v[60:61], v[62:63], v[60:61]
	s_nop 0
	v_pk_mul_f32 v[62:63], v[50:51], v[60:61]
	v_pk_fma_f32 v[60:61], v[50:51], v[60:61], v[50:51] neg_lo:[1,0,0] neg_hi:[1,0,0]
	s_nop 0
	v_cndmask_b32_e32 v50, v60, v62, vcc
	v_cmp_gt_f32_e32 vcc, 0, v51
	s_nop 1
	v_cndmask_b32_e32 v51, v61, v63, vcc

; __device__ __forceinline__ unsigned cvt_pk_bf16(float lo, float hi) { unsigned r; asm volatile("v_cvt_pk_bf16_f32 %0, %1, %2" : "=v"(r) : "v"(lo), "v"(hi)); return r; }
;     __device__ __forceinline__ void operator()(const f32x4 (&acc)[2][2][4][2], const Unit& u, int wr, int wc, int fr, int fq) const {
;     ...
;                     if (do_stat) { s1 += ((v0[0] + v0[1]) + (v0[2] + v0[3])) + ((v1[0] + v1[1]) + (v1[2] + v1[3]));
;                         s2 += ((v0[0] * v0[0] + v0[1] * v0[1]) + (v0[2] * v0[2] + v0[3] * v0[3])) + ((v1[0] * v1[0] + v1[1] * v1[1]) + (v1[2] * v1[2] + v1[3] * v1[3])); }
;                     u32x4 w; w.x = cvt_pk_bf16(v0[0], v0[1]); w.y = cvt_pk_bf16(v0[2], v0[3]); w.z = cvt_pk_bf16(v1[0], v1[1]); w.w = cvt_pk_bf16(v1[2], v1[3]);
;                     *(u32x4*)(rowp + bj * HALF) = w; }
;                 if (do_stat) { s1 += __shfl_xor(s1, 16); s1 += __shfl_xor(s1, 32); s2 += __shfl_xor(s2, 16); s2 += __shfl_xor(s2, 32);
;                     if (fq == 0) *(f32x2*)(vstat + ((size_t)(row0 + ai * HALF + m * 16) * 8 + (u.pn - vstat_pn0) * 4 + wc) * 2) = (f32x2){s1, s2}; }
.LBB0_352:
	s_and_b64 vcc, exec, s[44:45]
	v_cvt_pk_bf16_f32 v52, v52, v53
	v_cvt_pk_bf16_f32 v53, v54, v55
	v_cvt_pk_bf16_f32 v54, v48, v49
	v_cvt_pk_bf16_f32 v55, v50, v51
	global_store_dwordx4 v[58:59], v[52:55], off offset:256
	s_cbranch_vccnz .LBB0_356
	v_cmp_lt_i32_e32 vcc, v120, v119
	s_nop 1
	v_cndmask_b32_e32 v48, v252, v120, vcc
	v_lshlrev_b32_e32 v49, 2, v48
	ds_bpermute_b32 v48, v49, v60
	ds_bpermute_b32 v49, v49, v61
	v_cmp_lt_i32_e32 vcc, v118, v119
	s_waitcnt lgkmcnt(0)
	v_pk_add_f32 v[48:49], v[60:61], v[48:49]
	v_cndmask_b32_e32 v50, v252, v118, vcc
	v_lshlrev_b32_e32 v51, 2, v50
	ds_bpermute_b32 v50, v51, v48
	ds_bpermute_b32 v51, v51, v49
	s_and_saveexec_b64 s[0:1], s[38:39]
	s_cbranch_execz .LBB0_355
	s_lshl_b32 s4, s60, 2
	s_add_i32 s4, s4, -16
	s_waitcnt lgkmcnt(0)
	v_pk_add_f32 v[48:49], v[48:49], v[50:51]
	v_ashrrev_i32_e32 v113, 31, v112
	v_mov_b32_e32 v50, s4
	v_mov_b32_e32 v51, v193
	v_lshl_add_u64 v[50:51], v[112:113], 3, v[50:51]
	v_or_b32_e32 v50, s83, v50
	v_lshl_add_u64 v[50:51], v[50:51], 3, s[20:21]
	v_add_co_u32_e32 v50, vcc, 0x2000, v50
	s_nop 1
	v_addc_co_u32_e32 v51, vcc, 0, v51, vcc
	global_store_dwordx2 v[50:51], v[48:49], off

; __device__ __forceinline__ unsigned cvt_pk_bf16(float lo, float hi) { unsigned r; asm volatile("v_cvt_pk_bf16_f32 %0, %1, %2" : "=v"(r) : "v"(lo), "v"(hi)); return r; }
; __device__ __forceinline__ f32x2 gelu_pk(f32x2 v) {
;     const f32x2 av = __builtin_elementwise_abs(v), d = av * 0.2316418882f + 1.0f;
;     f32x2 t; t.x = __builtin_amdgcn_rcpf(d.x); t.y = __builtin_amdgcn_rcpf(d.y);
;     f32x2 q = t * 0.5307027145f + (-0.7265760135f); q = q * t + 0.7107068705f; q = q * t + (-0.142248368f); q = q * t + 0.127414796f; q = q * t;
;     const f32x2 s = (v * v) * (-0.72134752044f);
;     f32x2 e; e.x = __builtin_amdgcn_exp2f(s.x); e.y = __builtin_amdgcn_exp2f(s.y);
;     const f32x2 m = v * (q * e), r = v - m;
;     f32x2 o; o.x = v.x < 0.f ? m.x : r.x; o.y = v.y < 0.f ? m.y : r.y; return o;
; }
;     __device__ __forceinline__ void operator()(const f32x4 (&acc)[2][2][4][2], const Unit& u, int wr, int wc, int fr, int fq) const {
;     ...
;             for (int m = 0; m < 4; ++m) { bf16_t* rowp = O + (size_t)(u.pm >> 5) * bgap + (size_t)u.pm * sm + (size_t)u.pn * sn + (size_t)(wr * 64 + fr + ai * HALF + m * 16) * ldc + wc * 32 + 8 * fq; const float sc = rs[ai][m]; float s1 = 0.f, s2 = 0.f;
; #pragma unroll
;                 for (int bj = 0; bj < 2; ++bj) { f32x4 v0 = acc[ai][bj][m][0] * sc, v1 = acc[ai][bj][m][1] * sc;
;                     if (do_gelu) { f32x2 a = gelu_pk((f32x2){v0[0], v0[1]}), b = gelu_pk((f32x2){v0[2], v0[3]}), c = gelu_pk((f32x2){v1[0], v1[1]}), d = gelu_pk((f32x2){v1[2], v1[3]});
;                         v0 = (f32x4){a.x, a.y, b.x, b.y}; v1 = (f32x4){c.x, c.y, d.x, d.y}; }
;                     if (do_stat) { s1 += ((v0[0] + v0[1]) + (v0[2] + v0[3])) + ((v1[0] + v1[1]) + (v1[2] + v1[3]));
;                         s2 += ((v0[0] * v0[0] + v0[1] * v0[1]) + (v0[2] * v0[2] + v0[3] * v0[3])) + ((v1[0] * v1[0] + v1[1] * v1[1]) + (v1[2] * v1[2] + v1[3] * v1[3])); }
;                     u32x4 w; w.x = cvt_pk_bf16(v0[0], v0[1]); w.y = cvt_pk_bf16(v0[2], v0[3]); w.z = cvt_pk_bf16(v1[0], v1[1]); w.w = cvt_pk_bf16(v1[2], v1[3]);
;                     *(u32x4*)(rowp + bj * HALF) = w; }
.LBB0_362:
	v_lshl_add_u64 v[42:43], s[16:17], 0, v[146:147]
	v_lshl_add_u64 v[42:43], v[42:43], 0, s[86:87]
	v_lshl_add_u64 v[42:43], v[42:43], 0, v[192:193]
	v_cvt_pk_bf16_f32 v44, v44, v45
	v_cvt_pk_bf16_f32 v45, v46, v47
	v_mov_b32_e32 v161, v160
	v_cvt_pk_bf16_f32 v46, v50, v51
	v_cvt_pk_bf16_f32 v47, v48, v49
	global_store_dwordx4 v[42:43], v[44:47], off
	v_pk_mul_f32 v[36:37], v[36:37], v[160:161]
	s_and_b64 vcc, exec, s[42:43]
	v_mov_b32_e32 v44, v160
	v_mov_b32_e32 v45, v160
	v_pk_mul_f32 v[38:39], v[38:39], v[44:45]
	v_pk_mul_f32 v[34:35], v[34:35], v[44:45]
	v_pk_mul_f32 v[32:33], v[32:33], v[160:161]
	s_cbranch_vccnz .LBB0_364
	v_and_b32_e32 v45, 0x7fffffff, v37
	v_and_b32_e32 v44, 0x7fffffff, v36
	v_pk_fma_f32 v[44:45], v[44:45], s[28:29], 1.0 op_sel_hi:[1,0,0]
	s_mov_b32 s0, 0xbf3a00e3
	v_rcp_f32_e32 v46, v44
	v_rcp_f32_e32 v47, v45
	v_mov_b64_e32 v[44:45], s[0:1]
	v_pk_mul_f32 v[50:51], v[36:37], v[36:37]
	s_mov_b32 s0, 0xbf38aa3b
	v_pk_fma_f32 v[48:49], v[46:47], s[30:31], v[44:45] op_sel_hi:[1,0,0]
	v_pk_mul_f32 v[50:51], v[50:51], s[0:1] op_sel_hi:[1,0]
	v_pk_fma_f32 v[48:49], v[46:47], v[48:49], s[36:37] op_sel_hi:[1,1,0]
	v_exp_f32_e32 v50, v50
	v_exp_f32_e32 v51, v51
	v_pk_fma_f32 v[48:49], v[46:47], v[48:49], s[80:81] op_sel_hi:[1,1,0]
	v_cmp_gt_f32_e32 vcc, 0, v36
	v_pk_fma_f32 v[48:49], v[46:47], v[48:49], s[64:65] op_sel_hi:[1,1,0]
	s_nop 0
	v_pk_mul_f32 v[46:47], v[46:47], v[48:49]
	v_pk_mul_f32 v[48:49], v[38:39], v[38:39]
	v_pk_mul_f32 v[46:47], v[50:51], v[46:47]
	v_pk_mul_f32 v[48:49], v[48:49], s[0:1] op_sel_hi:[1,0]
	v_pk_mul_f32 v[50:51], v[36:37], v[46:47]
	v_pk_fma_f32 v[46:47], v[36:37], v[46:47], v[36:37] neg_lo:[1,0,0] neg_hi:[1,0,0]
	v_exp_f32_e32 v48, v48
	v_cndmask_b32_e32 v36, v46, v50, vcc
	v_cmp_gt_f32_e32 vcc, 0, v37
	v_and_b32_e32 v46, 0x7fffffff, v38
	v_exp_f32_e32 v49, v49
	v_cndmask_b32_e32 v37, v47, v51, vcc
	v_and_b32_e32 v47, 0x7fffffff, v39
	v_pk_fma_f32 v[46:47], v[46:47], s[28:29], 1.0 op_sel_hi:[1,0,0]
	v_cmp_gt_f32_e32 vcc, 0, v38
	v_rcp_f32_e32 v46, v46
	v_rcp_f32_e32 v47, v47
	s_nop 0
	v_pk_fma_f32 v[50:51], v[46:47], s[30:31], v[44:45] op_sel_hi:[1,0,0]
	s_nop 0
	v_pk_fma_f32 v[50:51], v[46:47], v[50:51], s[36:37] op_sel_hi:[1,1,0]
	s_nop 0
	v_pk_fma_f32 v[50:51], v[46:47], v[50:51], s[80:81] op_sel_hi:[1,1,0]
	s_nop 0
	v_pk_fma_f32 v[50:51], v[46:47], v[50:51], s[64:65] op_sel_hi:[1,1,0]
	s_nop 0
	v_pk_mul_f32 v[46:47], v[46:47], v[50:51]
	v_pk_mul_f32 v[50:51], v[32:33], v[32:33]
	v_pk_mul_f32 v[46:47], v[48:49], v[46:47]
	v_pk_mul_f32 v[50:51], v[50:51], s[0:1] op_sel_hi:[1,0]
	v_pk_mul_f32 v[48:49], v[38:39], v[46:47]
	v_pk_fma_f32 v[46:47], v[38:39], v[46:47], v[38:39] neg_lo:[1,0,0] neg_hi:[1,0,0]
	v_exp_f32_e32 v50, v50
	v_cndmask_b32_e32 v38, v46, v48, vcc
	v_cmp_gt_f32_e32 vcc, 0, v39
	v_and_b32_e32 v46, 0x7fffffff, v32
	v_exp_f32_e32 v51, v51
	v_cndmask_b32_e32 v39, v47, v49, vcc
	v_and_b32_e32 v47, 0x7fffffff, v33
	v_pk_fma_f32 v[46:47], v[46:47], s[28:29], 1.0 op_sel_hi:[1,0,0]
	v_cmp_gt_f32_e32 vcc, 0, v32
	v_rcp_f32_e32 v46, v46
	v_rcp_f32_e32 v47, v47
	s_nop 0
	v_pk_fma_f32 v[48:49], v[46:47], s[30:31], v[44:45] op_sel_hi:[1,0,0]
	s_nop 0
	v_pk_fma_f32 v[48:49], v[46:47], v[48:49], s[36:37] op_sel_hi:[1,1,0]
	s_nop 0
	v_pk_fma_f32 v[48:49], v[46:47], v[48:49], s[80:81] op_sel_hi:[1,1,0]
	s_nop 0
	v_pk_fma_f32 v[48:49], v[46:47], v[48:49], s[64:65] op_sel_hi:[1,1,0]
	s_nop 0
	v_pk_mul_f32 v[46:47], v[46:47], v[48:49]
	v_pk_mul_f32 v[48:49], v[34:35], v[34:35]
	v_pk_mul_f32 v[46:47], v[50:51], v[46:47]
	s_nop 0
	v_pk_mul_f32 v[50:51], v[32:33], v[46:47]
	v_pk_fma_f32 v[46:47], v[32:33], v[46:47], v[32:33] neg_lo:[1,0,0] neg_hi:[1,0,0]
	s_nop 0
	v_cndmask_b32_e32 v32, v46, v50, vcc
	v_cmp_gt_f32_e32 vcc, 0, v33
	v_and_b32_e32 v46, 0x7fffffff, v34
	s_nop 0
	v_cndmask_b32_e32 v33, v47, v51, vcc
	v_and_b32_e32 v47, 0x7fffffff, v35
	v_pk_fma_f32 v[46:47], v[46:47], s[28:29], 1.0 op_sel_hi:[1,0,0]
	v_cmp_gt_f32_e32 vcc, 0, v34
	v_rcp_f32_e32 v46, v46
	v_rcp_f32_e32 v47, v47
	s_nop 0
	v_pk_fma_f32 v[44:45], v[46:47], s[30:31], v[44:45] op_sel_hi:[1,0,0]
	s_nop 0
	v_pk_fma_f32 v[44:45], v[46:47], v[44:45], s[36:37] op_sel_hi:[1,1,0]
	s_nop 0
	v_pk_fma_f32 v[44:45], v[46:47], v[44:45], s[80:81] op_sel_hi:[1,1,0]
	s_nop 0
	v_pk_fma_f32 v[44:45], v[46:47], v[44:45], s[64:65] op_sel_hi:[1,1,0]
	s_nop 0
	v_pk_mul_f32 v[44:45], v[46:47], v[44:45]
	v_pk_mul_f32 v[46:47], v[48:49], s[0:1] op_sel_hi:[1,0]
	s_nop 0
	v_exp_f32_e32 v46, v46
	v_exp_f32_e32 v47, v47
	s_nop 0
	v_pk_mul_f32 v[44:45], v[46:47], v[44:45]
	s_nop 0
	v_pk_mul_f32 v[46:47], v[34:35], v[44:45]
	v_pk_fma_f32 v[44:45], v[34:35], v[44:45], v[34:35] neg_lo:[1,0,0] neg_hi:[1,0,0]
	s_nop 0
	v_cndmask_b32_e32 v34, v44, v46, vcc
	v_cmp_gt_f32_e32 vcc, 0, v35
	s_nop 1
	v_cndmask_b32_e32 v35, v45, v47, vcc

; __device__ __forceinline__ unsigned cvt_pk_bf16(float lo, float hi) { unsigned r; asm volatile("v_cvt_pk_bf16_f32 %0, %1, %2" : "=v"(r) : "v"(lo), "v"(hi)); return r; }
;     __device__ __forceinline__ void operator()(const f32x4 (&acc)[2][2][4][2], const Unit& u, int wr, int wc, int fr, int fq) const {
;     ...
;                     if (do_stat) { s1 += ((v0[0] + v0[1]) + (v0[2] + v0[3])) + ((v1[0] + v1[1]) + (v1[2] + v1[3]));
;                         s2 += ((v0[0] * v0[0] + v0[1] * v0[1]) + (v0[2] * v0[2] + v0[3] * v0[3])) + ((v1[0] * v1[0] + v1[1] * v1[1]) + (v1[2] * v1[2] + v1[3] * v1[3])); }
;                     u32x4 w; w.x = cvt_pk_bf16(v0[0], v0[1]); w.y = cvt_pk_bf16(v0[2], v0[3]); w.z = cvt_pk_bf16(v1[0], v1[1]); w.w = cvt_pk_bf16(v1[2], v1[3]);
;                     *(u32x4*)(rowp + bj * HALF) = w; }
;                 if (do_stat) { s1 += __shfl_xor(s1, 16); s1 += __shfl_xor(s1, 32); s2 += __shfl_xor(s2, 16); s2 += __shfl_xor(s2, 32);
;                     if (fq == 0) *(f32x2*)(vstat + ((size_t)(row0 + ai * HALF + m * 16) * 8 + (u.pn - vstat_pn0) * 4 + wc) * 2) = (f32x2){s1, s2}; }
.LBB0_368:
	s_and_b64 vcc, exec, s[44:45]
	v_cvt_pk_bf16_f32 v36, v36, v37
	v_cvt_pk_bf16_f32 v37, v38, v39
	v_cvt_pk_bf16_f32 v38, v32, v33
	v_cvt_pk_bf16_f32 v39, v34, v35
	global_store_dwordx4 v[42:43], v[36:39], off offset:256
	s_cbranch_vccnz .LBB0_372
	v_cmp_lt_i32_e32 vcc, v120, v119
	s_nop 1
	v_cndmask_b32_e32 v32, v252, v120, vcc
	v_lshlrev_b32_e32 v33, 2, v32
	ds_bpermute_b32 v32, v33, v44
	ds_bpermute_b32 v33, v33, v45
	v_cmp_lt_i32_e32 vcc, v118, v119
	s_waitcnt lgkmcnt(0)
	v_pk_add_f32 v[32:33], v[44:45], v[32:33]
	v_cndmask_b32_e32 v34, v252, v118, vcc
	v_lshlrev_b32_e32 v35, 2, v34
	ds_bpermute_b32 v34, v35, v32
	ds_bpermute_b32 v35, v35, v33
	s_and_saveexec_b64 s[0:1], s[38:39]
	s_cbranch_execz .LBB0_371
	s_lshl_b32 s4, s60, 2
	s_add_i32 s4, s4, -16
	s_waitcnt lgkmcnt(0)
	v_pk_add_f32 v[32:33], v[32:33], v[34:35]
	v_ashrrev_i32_e32 v113, 31, v112
	v_mov_b32_e32 v34, s4
	v_mov_b32_e32 v35, v193
	v_lshl_add_u64 v[34:35], v[112:113], 3, v[34:35]
	v_or_b32_e32 v34, s83, v34
	v_lshl_add_u64 v[34:35], v[34:35], 3, s[20:21]
	v_add_co_u32_e32 v34, vcc, 0x2000, v34
	s_nop 1
	v_addc_co_u32_e32 v35, vcc, 0, v35, vcc
	global_store_dwordx2 v[34:35], v[32:33], off offset:1024

; __device__ __forceinline__ unsigned cvt_pk_bf16(float lo, float hi) { unsigned r; asm volatile("v_cvt_pk_bf16_f32 %0, %1, %2" : "=v"(r) : "v"(lo), "v"(hi)); return r; }
; __device__ __forceinline__ f32x2 gelu_pk(f32x2 v) {
;     const f32x2 av = __builtin_elementwise_abs(v), d = av * 0.2316418882f + 1.0f;
;     f32x2 t; t.x = __builtin_amdgcn_rcpf(d.x); t.y = __builtin_amdgcn_rcpf(d.y);
;     f32x2 q = t * 0.5307027145f + (-0.7265760135f); q = q * t + 0.7107068705f; q = q * t + (-0.142248368f); q = q * t + 0.127414796f; q = q * t;
;     const f32x2 s = (v * v) * (-0.72134752044f);
;     f32x2 e; e.x = __builtin_amdgcn_exp2f(s.x); e.y = __builtin_amdgcn_exp2f(s.y);
;     const f32x2 m = v * (q * e), r = v - m;
;     f32x2 o; o.x = v.x < 0.f ? m.x : r.x; o.y = v.y < 0.f ? m.y : r.y; return o;
; }
;     __device__ __forceinline__ void operator()(const f32x4 (&acc)[2][2][4][2], const Unit& u, int wr, int wc, int fr, int fq) const {
;     ...
;             for (int m = 0; m < 4; ++m) { bf16_t* rowp = O + (size_t)(u.pm >> 5) * bgap + (size_t)u.pm * sm + (size_t)u.pn * sn + (size_t)(wr * 64 + fr + ai * HALF + m * 16) * ldc + wc * 32 + 8 * fq; const float sc = rs[ai][m]; float s1 = 0.f, s2 = 0.f;
; #pragma unroll
;                 for (int bj = 0; bj < 2; ++bj) { f32x4 v0 = acc[ai][bj][m][0] * sc, v1 = acc[ai][bj][m][1] * sc;
;                     if (do_gelu) { f32x2 a = gelu_pk((f32x2){v0[0], v0[1]}), b = gelu_pk((f32x2){v0[2], v0[3]}), c = gelu_pk((f32x2){v1[0], v1[1]}), d = gelu_pk((f32x2){v1[2], v1[3]});
;                         v0 = (f32x4){a.x, a.y, b.x, b.y}; v1 = (f32x4){c.x, c.y, d.x, d.y}; }
;                     if (do_stat) { s1 += ((v0[0] + v0[1]) + (v0[2] + v0[3])) + ((v1[0] + v1[1]) + (v1[2] + v1[3]));
;                         s2 += ((v0[0] * v0[0] + v0[1] * v0[1]) + (v0[2] * v0[2] + v0[3] * v0[3])) + ((v1[0] * v1[0] + v1[1] * v1[1]) + (v1[2] * v1[2] + v1[3] * v1[3])); }
;                     u32x4 w; w.x = cvt_pk_bf16(v0[0], v0[1]); w.y = cvt_pk_bf16(v0[2], v0[3]); w.z = cvt_pk_bf16(v1[0], v1[1]); w.w = cvt_pk_bf16(v1[2], v1[3]);
;                     *(u32x4*)(rowp + bj * HALF) = w; }
.LBB0_378:
	v_lshl_add_u64 v[26:27], s[16:17], 0, v[148:149]
	v_lshl_add_u64 v[26:27], v[26:27], 0, s[86:87]
	v_lshl_add_u64 v[26:27], v[26:27], 0, v[192:193]
	v_cvt_pk_bf16_f32 v28, v28, v29
	v_cvt_pk_bf16_f32 v29, v30, v31
	v_mov_b32_e32 v159, v158
	v_cvt_pk_bf16_f32 v30, v34, v35
	v_cvt_pk_bf16_f32 v31, v32, v33
	global_store_dwordx4 v[26:27], v[28:31], off
	v_pk_mul_f32 v[20:21], v[20:21], v[158:159]
	s_and_b64 vcc, exec, s[42:43]
	v_mov_b32_e32 v28, v158
	v_mov_b32_e32 v29, v158
	v_pk_mul_f32 v[22:23], v[22:23], v[28:29]
	v_pk_mul_f32 v[18:19], v[18:19], v[28:29]
	v_pk_mul_f32 v[16:17], v[16:17], v[158:159]
	s_cbranch_vccnz .LBB0_380
	v_and_b32_e32 v29, 0x7fffffff, v21
	v_and_b32_e32 v28, 0x7fffffff, v20
	v_pk_fma_f32 v[28:29], v[28:29], s[28:29], 1.0 op_sel_hi:[1,0,0]
	s_mov_b32 s0, 0xbf3a00e3
	v_rcp_f32_e32 v30, v28
	v_rcp_f32_e32 v31, v29
	v_mov_b64_e32 v[28:29], s[0:1]
	v_pk_mul_f32 v[34:35], v[20:21], v[20:21]
	s_mov_b32 s0, 0xbf38aa3b
	v_pk_fma_f32 v[32:33], v[30:31], s[30:31], v[28:29] op_sel_hi:[1,0,0]
	v_pk_mul_f32 v[34:35], v[34:35], s[0:1] op_sel_hi:[1,0]
	v_pk_fma_f32 v[32:33], v[30:31], v[32:33], s[36:37] op_sel_hi:[1,1,0]
	v_exp_f32_e32 v34, v34
	v_exp_f32_e32 v35, v35
	v_pk_fma_f32 v[32:33], v[30:31], v[32:33], s[80:81] op_sel_hi:[1,1,0]
	v_cmp_gt_f32_e32 vcc, 0, v20
	v_pk_fma_f32 v[32:33], v[30:31], v[32:33], s[64:65] op_sel_hi:[1,1,0]
	s_nop 0
	v_pk_mul_f32 v[30:31], v[30:31], v[32:33]
	v_pk_mul_f32 v[32:33], v[22:23], v[22:23]
	v_pk_mul_f32 v[30:31], v[34:35], v[30:31]
	v_pk_mul_f32 v[32:33], v[32:33], s[0:1] op_sel_hi:[1,0]
	v_pk_mul_f32 v[34:35], v[20:21], v[30:31]
	v_pk_fma_f32 v[30:31], v[20:21], v[30:31], v[20:21] neg_lo:[1,0,0] neg_hi:[1,0,0]
	v_exp_f32_e32 v32, v32
	v_cndmask_b32_e32 v20, v30, v34, vcc
	v_cmp_gt_f32_e32 vcc, 0, v21
	v_and_b32_e32 v30, 0x7fffffff, v22
	v_exp_f32_e32 v33, v33
	v_cndmask_b32_e32 v21, v31, v35, vcc
	v_and_b32_e32 v31, 0x7fffffff, v23
	v_pk_fma_f32 v[30:31], v[30:31], s[28:29], 1.0 op_sel_hi:[1,0,0]
	v_cmp_gt_f32_e32 vcc, 0, v22
	v_rcp_f32_e32 v30, v30
	v_rcp_f32_e32 v31, v31
	s_nop 0
	v_pk_fma_f32 v[34:35], v[30:31], s[30:31], v[28:29] op_sel_hi:[1,0,0]
	s_nop 0
	v_pk_fma_f32 v[34:35], v[30:31], v[34:35], s[36:37] op_sel_hi:[1,1,0]
	s_nop 0
	v_pk_fma_f32 v[34:35], v[30:31], v[34:35], s[80:81] op_sel_hi:[1,1,0]
	s_nop 0
	v_pk_fma_f32 v[34:35], v[30:31], v[34:35], s[64:65] op_sel_hi:[1,1,0]
	s_nop 0
	v_pk_mul_f32 v[30:31], v[30:31], v[34:35]
	v_pk_mul_f32 v[34:35], v[16:17], v[16:17]
	v_pk_mul_f32 v[30:31], v[32:33], v[30:31]
	v_pk_mul_f32 v[34:35], v[34:35], s[0:1] op_sel_hi:[1,0]
	v_pk_mul_f32 v[32:33], v[22:23], v[30:31]
	v_pk_fma_f32 v[30:31], v[22:23], v[30:31], v[22:23] neg_lo:[1,0,0] neg_hi:[1,0,0]
	v_exp_f32_e32 v34, v34
	v_cndmask_b32_e32 v22, v30, v32, vcc
	v_cmp_gt_f32_e32 vcc, 0, v23
	v_and_b32_e32 v30, 0x7fffffff, v16
	v_exp_f32_e32 v35, v35
	v_cndmask_b32_e32 v23, v31, v33, vcc
	v_and_b32_e32 v31, 0x7fffffff, v17
	v_pk_fma_f32 v[30:31], v[30:31], s[28:29], 1.0 op_sel_hi:[1,0,0]
	v_cmp_gt_f32_e32 vcc, 0, v16
	v_rcp_f32_e32 v30, v30
	v_rcp_f32_e32 v31, v31
	s_nop 0
	v_pk_fma_f32 v[32:33], v[30:31], s[30:31], v[28:29] op_sel_hi:[1,0,0]
	s_nop 0
	v_pk_fma_f32 v[32:33], v[30:31], v[32:33], s[36:37] op_sel_hi:[1,1,0]
	s_nop 0
	v_pk_fma_f32 v[32:33], v[30:31], v[32:33], s[80:81] op_sel_hi:[1,1,0]
	s_nop 0
	v_pk_fma_f32 v[32:33], v[30:31], v[32:33], s[64:65] op_sel_hi:[1,1,0]
	s_nop 0
	v_pk_mul_f32 v[30:31], v[30:31], v[32:33]
	v_pk_mul_f32 v[32:33], v[18:19], v[18:19]
	v_pk_mul_f32 v[30:31], v[34:35], v[30:31]
	s_nop 0
	v_pk_mul_f32 v[34:35], v[16:17], v[30:31]
	v_pk_fma_f32 v[30:31], v[16:17], v[30:31], v[16:17] neg_lo:[1,0,0] neg_hi:[1,0,0]
	s_nop 0
	v_cndmask_b32_e32 v16, v30, v34, vcc
	v_cmp_gt_f32_e32 vcc, 0, v17
	v_and_b32_e32 v30, 0x7fffffff, v18
	s_nop 0
	v_cndmask_b32_e32 v17, v31, v35, vcc
	v_and_b32_e32 v31, 0x7fffffff, v19
	v_pk_fma_f32 v[30:31], v[30:31], s[28:29], 1.0 op_sel_hi:[1,0,0]
	v_cmp_gt_f32_e32 vcc, 0, v18
	v_rcp_f32_e32 v30, v30
	v_rcp_f32_e32 v31, v31
	s_nop 0
	v_pk_fma_f32 v[28:29], v[30:31], s[30:31], v[28:29] op_sel_hi:[1,0,0]
	s_nop 0
	v_pk_fma_f32 v[28:29], v[30:31], v[28:29], s[36:37] op_sel_hi:[1,1,0]
	s_nop 0
	v_pk_fma_f32 v[28:29], v[30:31], v[28:29], s[80:81] op_sel_hi:[1,1,0]
	s_nop 0
	v_pk_fma_f32 v[28:29], v[30:31], v[28:29], s[64:65] op_sel_hi:[1,1,0]
	s_nop 0
	v_pk_mul_f32 v[28:29], v[30:31], v[28:29]
	v_pk_mul_f32 v[30:31], v[32:33], s[0:1] op_sel_hi:[1,0]
	s_nop 0
	v_exp_f32_e32 v30, v30
	v_exp_f32_e32 v31, v31
	s_nop 0
	v_pk_mul_f32 v[28:29], v[30:31], v[28:29]
	s_nop 0
	v_pk_mul_f32 v[30:31], v[18:19], v[28:29]
	v_pk_fma_f32 v[28:29], v[18:19], v[28:29], v[18:19] neg_lo:[1,0,0] neg_hi:[1,0,0]
	s_nop 0
	v_cndmask_b32_e32 v18, v28, v30, vcc
	v_cmp_gt_f32_e32 vcc, 0, v19
	s_nop 1
	v_cndmask_b32_e32 v19, v29, v31, vcc

; __device__ __forceinline__ unsigned cvt_pk_bf16(float lo, float hi) { unsigned r; asm volatile("v_cvt_pk_bf16_f32 %0, %1, %2" : "=v"(r) : "v"(lo), "v"(hi)); return r; }
;     __device__ __forceinline__ void operator()(const f32x4 (&acc)[2][2][4][2], const Unit& u, int wr, int wc, int fr, int fq) const {
;     ...
;                     if (do_stat) { s1 += ((v0[0] + v0[1]) + (v0[2] + v0[3])) + ((v1[0] + v1[1]) + (v1[2] + v1[3]));
;                         s2 += ((v0[0] * v0[0] + v0[1] * v0[1]) + (v0[2] * v0[2] + v0[3] * v0[3])) + ((v1[0] * v1[0] + v1[1] * v1[1]) + (v1[2] * v1[2] + v1[3] * v1[3])); }
;                     u32x4 w; w.x = cvt_pk_bf16(v0[0], v0[1]); w.y = cvt_pk_bf16(v0[2], v0[3]); w.z = cvt_pk_bf16(v1[0], v1[1]); w.w = cvt_pk_bf16(v1[2], v1[3]);
;                     *(u32x4*)(rowp + bj * HALF) = w; }
;                 if (do_stat) { s1 += __shfl_xor(s1, 16); s1 += __shfl_xor(s1, 32); s2 += __shfl_xor(s2, 16); s2 += __shfl_xor(s2, 32);
;                     if (fq == 0) *(f32x2*)(vstat + ((size_t)(row0 + ai * HALF + m * 16) * 8 + (u.pn - vstat_pn0) * 4 + wc) * 2) = (f32x2){s1, s2}; }
.LBB0_384:
	s_and_b64 vcc, exec, s[44:45]
	v_cvt_pk_bf16_f32 v20, v20, v21
	v_cvt_pk_bf16_f32 v21, v22, v23
	v_cvt_pk_bf16_f32 v22, v16, v17
	v_cvt_pk_bf16_f32 v23, v18, v19
	global_store_dwordx4 v[26:27], v[20:23], off offset:256
	s_cbranch_vccnz .LBB0_388
	v_cmp_lt_i32_e32 vcc, v120, v119
	s_nop 1
	v_cndmask_b32_e32 v16, v252, v120, vcc
	v_lshlrev_b32_e32 v17, 2, v16
	ds_bpermute_b32 v16, v17, v28
	ds_bpermute_b32 v17, v17, v29
	v_cmp_lt_i32_e32 vcc, v118, v119
	s_waitcnt lgkmcnt(0)
	v_pk_add_f32 v[16:17], v[28:29], v[16:17]
	v_cndmask_b32_e32 v18, v252, v118, vcc
	v_lshlrev_b32_e32 v19, 2, v18
	ds_bpermute_b32 v18, v19, v16
	ds_bpermute_b32 v19, v19, v17
	s_and_saveexec_b64 s[0:1], s[38:39]
	s_cbranch_execz .LBB0_387
	s_lshl_b32 s4, s60, 2
	s_add_i32 s4, s4, -16
	s_waitcnt lgkmcnt(0)
	v_pk_add_f32 v[16:17], v[16:17], v[18:19]
	v_ashrrev_i32_e32 v113, 31, v112
	v_mov_b32_e32 v18, s4
	v_mov_b32_e32 v19, v193
	v_lshl_add_u64 v[18:19], v[112:113], 3, v[18:19]
	v_or_b32_e32 v18, s83, v18
	v_lshl_add_u64 v[18:19], v[18:19], 3, s[20:21]
	v_add_co_u32_e32 v18, vcc, 0x2000, v18
	s_nop 1
	v_addc_co_u32_e32 v19, vcc, 0, v19, vcc
	global_store_dwordx2 v[18:19], v[16:17], off offset:2048

; __device__ __forceinline__ unsigned cvt_pk_bf16(float lo, float hi) { unsigned r; asm volatile("v_cvt_pk_bf16_f32 %0, %1, %2" : "=v"(r) : "v"(lo), "v"(hi)); return r; }
; __device__ __forceinline__ f32x2 gelu_pk(f32x2 v) {
;     const f32x2 av = __builtin_elementwise_abs(v), d = av * 0.2316418882f + 1.0f;
;     f32x2 t; t.x = __builtin_amdgcn_rcpf(d.x); t.y = __builtin_amdgcn_rcpf(d.y);
;     f32x2 q = t * 0.5307027145f + (-0.7265760135f); q = q * t + 0.7107068705f; q = q * t + (-0.142248368f); q = q * t + 0.127414796f; q = q * t;
;     const f32x2 s = (v * v) * (-0.72134752044f);
;     f32x2 e; e.x = __builtin_amdgcn_exp2f(s.x); e.y = __builtin_amdgcn_exp2f(s.y);
;     const f32x2 m = v * (q * e), r = v - m;
;     f32x2 o; o.x = v.x < 0.f ? m.x : r.x; o.y = v.y < 0.f ? m.y : r.y; return o;
; }
;     __device__ __forceinline__ void operator()(const f32x4 (&acc)[2][2][4][2], const Unit& u, int wr, int wc, int fr, int fq) const {
;     ...
;             for (int m = 0; m < 4; ++m) { bf16_t* rowp = O + (size_t)(u.pm >> 5) * bgap + (size_t)u.pm * sm + (size_t)u.pn * sn + (size_t)(wr * 64 + fr + ai * HALF + m * 16) * ldc + wc * 32 + 8 * fq; const float sc = rs[ai][m]; float s1 = 0.f, s2 = 0.f;
; #pragma unroll
;                 for (int bj = 0; bj < 2; ++bj) { f32x4 v0 = acc[ai][bj][m][0] * sc, v1 = acc[ai][bj][m][1] * sc;
;                     if (do_gelu) { f32x2 a = gelu_pk((f32x2){v0[0], v0[1]}), b = gelu_pk((f32x2){v0[2], v0[3]}), c = gelu_pk((f32x2){v1[0], v1[1]}), d = gelu_pk((f32x2){v1[2], v1[3]});
;                         v0 = (f32x4){a.x, a.y, b.x, b.y}; v1 = (f32x4){c.x, c.y, d.x, d.y}; }
;                     if (do_stat) { s1 += ((v0[0] + v0[1]) + (v0[2] + v0[3])) + ((v1[0] + v1[1]) + (v1[2] + v1[3]));
;                         s2 += ((v0[0] * v0[0] + v0[1] * v0[1]) + (v0[2] * v0[2] + v0[3] * v0[3])) + ((v1[0] * v1[0] + v1[1] * v1[1]) + (v1[2] * v1[2] + v1[3] * v1[3])); }
;                     u32x4 w; w.x = cvt_pk_bf16(v0[0], v0[1]); w.y = cvt_pk_bf16(v0[2], v0[3]); w.z = cvt_pk_bf16(v1[0], v1[1]); w.w = cvt_pk_bf16(v1[2], v1[3]);
;                     *(u32x4*)(rowp + bj * HALF) = w; }
.LBB0_394:
	v_lshl_add_u64 v[10:11], s[16:17], 0, v[150:151]
	v_lshl_add_u64 v[10:11], v[10:11], 0, s[86:87]
	v_lshl_add_u64 v[10:11], v[10:11], 0, v[192:193]
	v_cvt_pk_bf16_f32 v12, v12, v13
	v_cvt_pk_bf16_f32 v13, v14, v15
	v_mov_b32_e32 v157, v156
	v_cvt_pk_bf16_f32 v14, v18, v19
	v_cvt_pk_bf16_f32 v15, v16, v17
	global_store_dwordx4 v[10:11], v[12:15], off
	v_pk_mul_f32 v[4:5], v[4:5], v[156:157]
	s_and_b64 vcc, exec, s[42:43]
	v_mov_b32_e32 v12, v156
	v_mov_b32_e32 v13, v156
	v_pk_mul_f32 v[6:7], v[6:7], v[12:13]
	v_pk_mul_f32 v[2:3], v[2:3], v[12:13]
	v_pk_mul_f32 v[0:1], v[0:1], v[156:157]
	s_cbranch_vccnz .LBB0_396
	v_and_b32_e32 v13, 0x7fffffff, v5
	v_and_b32_e32 v12, 0x7fffffff, v4
	v_pk_fma_f32 v[12:13], v[12:13], s[28:29], 1.0 op_sel_hi:[1,0,0]
	s_mov_b32 s0, 0xbf3a00e3
	v_rcp_f32_e32 v14, v12
	v_rcp_f32_e32 v15, v13
	v_mov_b64_e32 v[12:13], s[0:1]
	v_pk_mul_f32 v[18:19], v[4:5], v[4:5]
	s_mov_b32 s0, 0xbf38aa3b
	v_pk_fma_f32 v[16:17], v[14:15], s[30:31], v[12:13] op_sel_hi:[1,0,0]
	v_pk_mul_f32 v[18:19], v[18:19], s[0:1] op_sel_hi:[1,0]
	v_pk_fma_f32 v[16:17], v[14:15], v[16:17], s[36:37] op_sel_hi:[1,1,0]
	v_exp_f32_e32 v18, v18
	v_exp_f32_e32 v19, v19
	v_pk_fma_f32 v[16:17], v[14:15], v[16:17], s[80:81] op_sel_hi:[1,1,0]
	v_cmp_gt_f32_e32 vcc, 0, v4
	v_pk_fma_f32 v[16:17], v[14:15], v[16:17], s[64:65] op_sel_hi:[1,1,0]
	s_nop 0
	v_pk_mul_f32 v[14:15], v[14:15], v[16:17]
	v_pk_mul_f32 v[16:17], v[6:7], v[6:7]
	v_pk_mul_f32 v[14:15], v[18:19], v[14:15]
	v_pk_mul_f32 v[16:17], v[16:17], s[0:1] op_sel_hi:[1,0]
	v_pk_mul_f32 v[18:19], v[4:5], v[14:15]
	v_pk_fma_f32 v[14:15], v[4:5], v[14:15], v[4:5] neg_lo:[1,0,0] neg_hi:[1,0,0]
	v_exp_f32_e32 v16, v16
	v_cndmask_b32_e32 v4, v14, v18, vcc
	v_cmp_gt_f32_e32 vcc, 0, v5
	v_and_b32_e32 v14, 0x7fffffff, v6
	v_exp_f32_e32 v17, v17
	v_cndmask_b32_e32 v5, v15, v19, vcc
	v_and_b32_e32 v15, 0x7fffffff, v7
	v_pk_fma_f32 v[14:15], v[14:15], s[28:29], 1.0 op_sel_hi:[1,0,0]
	v_cmp_gt_f32_e32 vcc, 0, v6
	v_rcp_f32_e32 v14, v14
	v_rcp_f32_e32 v15, v15
	s_nop 0
	v_pk_fma_f32 v[18:19], v[14:15], s[30:31], v[12:13] op_sel_hi:[1,0,0]
	s_nop 0
	v_pk_fma_f32 v[18:19], v[14:15], v[18:19], s[36:37] op_sel_hi:[1,1,0]
	s_nop 0
	v_pk_fma_f32 v[18:19], v[14:15], v[18:19], s[80:81] op_sel_hi:[1,1,0]
	s_nop 0
	v_pk_fma_f32 v[18:19], v[14:15], v[18:19], s[64:65] op_sel_hi:[1,1,0]
	s_nop 0
	v_pk_mul_f32 v[14:15], v[14:15], v[18:19]
	v_pk_mul_f32 v[18:19], v[0:1], v[0:1]
	v_pk_mul_f32 v[14:15], v[16:17], v[14:15]
	v_pk_mul_f32 v[18:19], v[18:19], s[0:1] op_sel_hi:[1,0]
	v_pk_mul_f32 v[16:17], v[6:7], v[14:15]
	v_pk_fma_f32 v[14:15], v[6:7], v[14:15], v[6:7] neg_lo:[1,0,0] neg_hi:[1,0,0]
	v_exp_f32_e32 v18, v18
	v_cndmask_b32_e32 v6, v14, v16, vcc
	v_cmp_gt_f32_e32 vcc, 0, v7
	v_and_b32_e32 v14, 0x7fffffff, v0
	v_exp_f32_e32 v19, v19
	v_cndmask_b32_e32 v7, v15, v17, vcc
	v_and_b32_e32 v15, 0x7fffffff, v1
	v_pk_fma_f32 v[14:15], v[14:15], s[28:29], 1.0 op_sel_hi:[1,0,0]
	v_cmp_gt_f32_e32 vcc, 0, v0
	v_rcp_f32_e32 v14, v14
	v_rcp_f32_e32 v15, v15
	s_nop 0
	v_pk_fma_f32 v[16:17], v[14:15], s[30:31], v[12:13] op_sel_hi:[1,0,0]
	s_nop 0
	v_pk_fma_f32 v[16:17], v[14:15], v[16:17], s[36:37] op_sel_hi:[1,1,0]
	s_nop 0
	v_pk_fma_f32 v[16:17], v[14:15], v[16:17], s[80:81] op_sel_hi:[1,1,0]
	s_nop 0
	v_pk_fma_f32 v[16:17], v[14:15], v[16:17], s[64:65] op_sel_hi:[1,1,0]
	s_nop 0
	v_pk_mul_f32 v[14:15], v[14:15], v[16:17]
	v_pk_mul_f32 v[16:17], v[2:3], v[2:3]
	v_pk_mul_f32 v[14:15], v[18:19], v[14:15]
	s_nop 0
	v_pk_mul_f32 v[18:19], v[0:1], v[14:15]
	v_pk_fma_f32 v[14:15], v[0:1], v[14:15], v[0:1] neg_lo:[1,0,0] neg_hi:[1,0,0]
	s_nop 0
	v_cndmask_b32_e32 v0, v14, v18, vcc
	v_cmp_gt_f32_e32 vcc, 0, v1
	v_and_b32_e32 v14, 0x7fffffff, v2
	s_nop 0
	v_cndmask_b32_e32 v1, v15, v19, vcc
	v_and_b32_e32 v15, 0x7fffffff, v3
	v_pk_fma_f32 v[14:15], v[14:15], s[28:29], 1.0 op_sel_hi:[1,0,0]
	v_cmp_gt_f32_e32 vcc, 0, v2
	v_rcp_f32_e32 v14, v14
	v_rcp_f32_e32 v15, v15
	s_nop 0
	v_pk_fma_f32 v[12:13], v[14:15], s[30:31], v[12:13] op_sel_hi:[1,0,0]
	s_nop 0
	v_pk_fma_f32 v[12:13], v[14:15], v[12:13], s[36:37] op_sel_hi:[1,1,0]
	s_nop 0
	v_pk_fma_f32 v[12:13], v[14:15], v[12:13], s[80:81] op_sel_hi:[1,1,0]
	s_nop 0
	v_pk_fma_f32 v[12:13], v[14:15], v[12:13], s[64:65] op_sel_hi:[1,1,0]
	s_nop 0
	v_pk_mul_f32 v[12:13], v[14:15], v[12:13]
	v_pk_mul_f32 v[14:15], v[16:17], s[0:1] op_sel_hi:[1,0]
	s_nop 0
	v_exp_f32_e32 v14, v14
	v_exp_f32_e32 v15, v15
	s_nop 0
	v_pk_mul_f32 v[12:13], v[14:15], v[12:13]
	s_nop 0
	v_pk_mul_f32 v[14:15], v[2:3], v[12:13]
	v_pk_fma_f32 v[12:13], v[2:3], v[12:13], v[2:3] neg_lo:[1,0,0] neg_hi:[1,0,0]
	s_nop 0
	v_cndmask_b32_e32 v2, v12, v14, vcc
	v_cmp_gt_f32_e32 vcc, 0, v3
	s_nop 1
	v_cndmask_b32_e32 v3, v13, v15, vcc

; __device__ __forceinline__ unsigned cvt_pk_bf16(float lo, float hi) { unsigned r; asm volatile("v_cvt_pk_bf16_f32 %0, %1, %2" : "=v"(r) : "v"(lo), "v"(hi)); return r; }
;     __device__ __forceinline__ void operator()(const f32x4 (&acc)[2][2][4][2], const Unit& u, int wr, int wc, int fr, int fq) const {
;     ...
;                     if (do_stat) { s1 += ((v0[0] + v0[1]) + (v0[2] + v0[3])) + ((v1[0] + v1[1]) + (v1[2] + v1[3]));
;                         s2 += ((v0[0] * v0[0] + v0[1] * v0[1]) + (v0[2] * v0[2] + v0[3] * v0[3])) + ((v1[0] * v1[0] + v1[1] * v1[1]) + (v1[2] * v1[2] + v1[3] * v1[3])); }
;                     u32x4 w; w.x = cvt_pk_bf16(v0[0], v0[1]); w.y = cvt_pk_bf16(v0[2], v0[3]); w.z = cvt_pk_bf16(v1[0], v1[1]); w.w = cvt_pk_bf16(v1[2], v1[3]);
;                     *(u32x4*)(rowp + bj * HALF) = w; }
;                 if (do_stat) { s1 += __shfl_xor(s1, 16); s1 += __shfl_xor(s1, 32); s2 += __shfl_xor(s2, 16); s2 += __shfl_xor(s2, 32);
;                     if (fq == 0) *(f32x2*)(vstat + ((size_t)(row0 + ai * HALF + m * 16) * 8 + (u.pn - vstat_pn0) * 4 + wc) * 2) = (f32x2){s1, s2}; }
.LBB0_401:
	s_and_b64 vcc, exec, s[44:45]
	v_cvt_pk_bf16_f32 v4, v4, v5
	v_cvt_pk_bf16_f32 v5, v6, v7
	v_cvt_pk_bf16_f32 v6, v0, v1
	v_cvt_pk_bf16_f32 v7, v2, v3
	global_store_dwordx4 v[10:11], v[4:7], off offset:256
	s_cbranch_vccnz .LBB0_405
	v_cmp_lt_i32_e32 vcc, v120, v119
	s_nop 1
	v_cndmask_b32_e32 v0, v252, v120, vcc
	v_lshlrev_b32_e32 v1, 2, v0
	ds_bpermute_b32 v0, v1, v12
	ds_bpermute_b32 v1, v1, v13
	v_cmp_lt_i32_e32 vcc, v118, v119
	s_waitcnt lgkmcnt(0)
	v_pk_add_f32 v[0:1], v[12:13], v[0:1]
	v_cndmask_b32_e32 v2, v252, v118, vcc
	v_lshlrev_b32_e32 v3, 2, v2
	ds_bpermute_b32 v2, v3, v0
	ds_bpermute_b32 v3, v3, v1
	s_and_saveexec_b64 s[0:1], s[38:39]
	s_cbranch_execz .LBB0_404
	s_lshl_b32 s4, s60, 2
	s_add_i32 s4, s4, -16
	s_waitcnt lgkmcnt(0)
	v_pk_add_f32 v[0:1], v[0:1], v[2:3]
	v_ashrrev_i32_e32 v113, 31, v112
	v_mov_b32_e32 v2, s4
	v_mov_b32_e32 v3, v193
	v_lshl_add_u64 v[2:3], v[112:113], 3, v[2:3]
	v_or_b32_e32 v2, s83, v2
	v_lshl_add_u64 v[2:3], v[2:3], 3, s[20:21]
	v_add_co_u32_e32 v2, vcc, 0x2000, v2
	s_nop 1
	v_addc_co_u32_e32 v3, vcc, 0, v3, vcc
	global_store_dwordx2 v[2:3], v[0:1], off offset:3072

; __device__ __forceinline__ unsigned cvt_pk_bf16(float lo, float hi) { unsigned r; asm volatile("v_cvt_pk_bf16_f32 %0, %1, %2" : "=v"(r) : "v"(lo), "v"(hi)); return r; }
;     __device__ __forceinline__ void operator()(const f32x4 (&acc)[2][2][4][2], const Unit& u, int wr, int wc, int fr, int fq) const {
;     ...
;             for (int m = 0; m < 4; ++m) { bf16_t* rowp = O + (size_t)(u.pm >> 5) * bgap + (size_t)u.pm * sm + (size_t)u.pn * sn + (size_t)(wr * 64 + fr + ai * HALF + m * 16) * ldc + wc * 32 + 8 * fq; const float sc = rs[ai][m]; float s1 = 0.f, s2 = 0.f;
; #pragma unroll
;                 for (int bj = 0; bj < 2; ++bj) { f32x4 v0 = acc[ai][bj][m][0] * sc, v1 = acc[ai][bj][m][1] * sc;
;                     if (do_gelu) { f32x2 a = gelu_pk((f32x2){v0[0], v0[1]}), b = gelu_pk((f32x2){v0[2], v0[3]}), c = gelu_pk((f32x2){v1[0], v1[1]}), d = gelu_pk((f32x2){v1[2], v1[3]});
;                         v0 = (f32x4){a.x, a.y, b.x, b.y}; v1 = (f32x4){c.x, c.y, d.x, d.y}; }
;                     if (do_stat) { s1 += ((v0[0] + v0[1]) + (v0[2] + v0[3])) + ((v1[0] + v1[1]) + (v1[2] + v1[3]));
;                         s2 += ((v0[0] * v0[0] + v0[1] * v0[1]) + (v0[2] * v0[2] + v0[3] * v0[3])) + ((v1[0] * v1[0] + v1[1] * v1[1]) + (v1[2] * v1[2] + v1[3] * v1[3])); }
;                     u32x4 w; w.x = cvt_pk_bf16(v0[0], v0[1]); w.y = cvt_pk_bf16(v0[2], v0[3]); w.z = cvt_pk_bf16(v1[0], v1[1]); w.w = cvt_pk_bf16(v1[2], v1[3]);
;                     *(u32x4*)(rowp + bj * HALF) = w; }
;                 if (do_stat) { s1 += __shfl_xor(s1, 16); s1 += __shfl_xor(s1, 32); s2 += __shfl_xor(s2, 16); s2 += __shfl_xor(s2, 32);
;                     if (fq == 0) *(f32x2*)(vstat + ((size_t)(row0 + ai * HALF + m * 16) * 8 + (u.pn - vstat_pn0) * 4 + wc) * 2) = (f32x2){s1, s2}; }
;                 asm volatile("" ::: "memory"); }
.LBB0_488:
	s_ashr_i32 s21, s20, 31
	s_lshl_b64 s[20:21], s[20:21], 19
	s_add_u32 s13, s83, s20
	s_addc_u32 s15, s84, s21
	s_ashr_i32 s27, s26, 31
	s_lshl_b64 s[20:21], s[26:27], 9
	s_add_u32 s20, s13, s20
	s_addc_u32 s21, s15, s21
	v_lshl_add_u64 v[154:155], s[20:21], 0, v[136:137]
	v_lshl_add_u64 v[154:155], v[154:155], 0, s[86:87]
	v_lshl_add_u64 v[154:155], v[154:155], 0, v[192:193]
	v_cvt_pk_bf16_f32 v124, v124, v125
	v_cvt_pk_bf16_f32 v125, v126, v127
	v_cvt_pk_bf16_f32 v126, v120, v121
	v_cvt_pk_bf16_f32 v127, v122, v123
	global_store_dwordx4 v[154:155], v[124:127], off
	v_cvt_pk_bf16_f32 v112, v112, v113
	v_cvt_pk_bf16_f32 v113, v114, v115
	v_cvt_pk_bf16_f32 v114, v104, v105
	v_lshl_add_u64 v[104:105], s[20:21], 0, v[146:147]
	v_lshl_add_u64 v[104:105], v[104:105], 0, s[86:87]
	v_cvt_pk_bf16_f32 v115, v106, v107
	global_store_dwordx4 v[154:155], v[112:115], off offset:256
	s_andn2_b64 vcc, exec, s[10:11]
	s_mov_b64 s[10:11], -1
	v_lshl_add_u64 v[112:113], v[104:105], 0, v[192:193]
	v_cvt_pk_bf16_f32 v104, v116, v117
	v_cvt_pk_bf16_f32 v105, v118, v119
	v_cvt_pk_bf16_f32 v106, v108, v109
	v_cvt_pk_bf16_f32 v107, v110, v111
	global_store_dwordx4 v[112:113], v[104:107], off
	v_cvt_pk_bf16_f32 v96, v96, v97
	v_cvt_pk_bf16_f32 v97, v98, v99
	v_cvt_pk_bf16_f32 v98, v88, v89
	v_lshl_add_u64 v[88:89], s[20:21], 0, v[148:149]
	v_lshl_add_u64 v[88:89], v[88:89], 0, s[86:87]
	v_cvt_pk_bf16_f32 v99, v90, v91
	global_store_dwordx4 v[112:113], v[96:99], off offset:256
	s_nop 1
	v_lshl_add_u64 v[96:97], v[88:89], 0, v[192:193]
	v_cvt_pk_bf16_f32 v88, v100, v101
	v_cvt_pk_bf16_f32 v89, v102, v103
	v_cvt_pk_bf16_f32 v90, v92, v93
	v_cvt_pk_bf16_f32 v91, v94, v95
	global_store_dwordx4 v[96:97], v[88:91], off
	v_cvt_pk_bf16_f32 v80, v80, v81
	v_cvt_pk_bf16_f32 v81, v82, v83
	v_cvt_pk_bf16_f32 v82, v72, v73
	v_lshl_add_u64 v[72:73], s[20:21], 0, v[150:151]
	v_lshl_add_u64 v[72:73], v[72:73], 0, s[86:87]
	v_cvt_pk_bf16_f32 v83, v74, v75
	global_store_dwordx4 v[96:97], v[80:83], off offset:256
	s_nop 1
	v_lshl_add_u64 v[80:81], v[72:73], 0, v[192:193]
	v_cvt_pk_bf16_f32 v72, v84, v85
	v_cvt_pk_bf16_f32 v73, v86, v87
	v_cvt_pk_bf16_f32 v74, v76, v77
	v_cvt_pk_bf16_f32 v75, v78, v79
	global_store_dwordx4 v[80:81], v[72:75], off
	v_cvt_pk_bf16_f32 v68, v68, v69
	v_cvt_pk_bf16_f32 v69, v70, v71
	v_cvt_pk_bf16_f32 v70, v64, v65
	v_lshl_add_u64 v[64:65], s[20:21], 0, v[138:139]
	v_lshl_add_u64 v[64:65], v[64:65], 0, s[86:87]
	v_cvt_pk_bf16_f32 v71, v66, v67
	global_store_dwordx4 v[80:81], v[68:71], off offset:256
	v_lshl_add_u64 v[64:65], v[64:65], 0, v[192:193]
	v_cvt_pk_bf16_f32 v60, v60, v61
	v_cvt_pk_bf16_f32 v61, v62, v63
	v_cvt_pk_bf16_f32 v62, v56, v57
	v_cvt_pk_bf16_f32 v63, v58, v59
	global_store_dwordx4 v[64:65], v[60:63], off
	v_cvt_pk_bf16_f32 v48, v48, v49
	v_cvt_pk_bf16_f32 v49, v50, v51
	v_cvt_pk_bf16_f32 v50, v40, v41
	v_lshl_add_u64 v[40:41], s[20:21], 0, v[140:141]
	v_lshl_add_u64 v[40:41], v[40:41], 0, s[86:87]
	v_cvt_pk_bf16_f32 v51, v42, v43
	global_store_dwordx4 v[64:65], v[48:51], off offset:256
	s_nop 1
	v_lshl_add_u64 v[48:49], v[40:41], 0, v[192:193]
	v_cvt_pk_bf16_f32 v40, v52, v53
	v_cvt_pk_bf16_f32 v41, v54, v55
	v_cvt_pk_bf16_f32 v42, v44, v45
	v_cvt_pk_bf16_f32 v43, v46, v47
	global_store_dwordx4 v[48:49], v[40:43], off
	v_cvt_pk_bf16_f32 v32, v32, v33
	v_cvt_pk_bf16_f32 v33, v34, v35
	v_cvt_pk_bf16_f32 v34, v24, v25
	v_lshl_add_u64 v[24:25], s[20:21], 0, v[142:143]
	v_lshl_add_u64 v[24:25], v[24:25], 0, s[86:87]
	v_cvt_pk_bf16_f32 v35, v26, v27
	global_store_dwordx4 v[48:49], v[32:35], off offset:256
	s_nop 1
	v_lshl_add_u64 v[32:33], v[24:25], 0, v[192:193]
	v_cvt_pk_bf16_f32 v24, v36, v37
	v_cvt_pk_bf16_f32 v25, v38, v39
	v_cvt_pk_bf16_f32 v26, v28, v29
	v_cvt_pk_bf16_f32 v27, v30, v31
	global_store_dwordx4 v[32:33], v[24:27], off
	v_cvt_pk_bf16_f32 v16, v16, v17
	v_cvt_pk_bf16_f32 v17, v18, v19
	v_cvt_pk_bf16_f32 v18, v8, v9
	v_lshl_add_u64 v[8:9], s[20:21], 0, v[144:145]
	v_lshl_add_u64 v[8:9], v[8:9], 0, s[86:87]
	v_cvt_pk_bf16_f32 v19, v10, v11
	global_store_dwordx4 v[32:33], v[16:19], off offset:256
	s_nop 1
	v_lshl_add_u64 v[16:17], v[8:9], 0, v[192:193]
	v_cvt_pk_bf16_f32 v8, v20, v21
	v_cvt_pk_bf16_f32 v9, v22, v23
	v_cvt_pk_bf16_f32 v10, v12, v13
	v_cvt_pk_bf16_f32 v11, v14, v15
	global_store_dwordx4 v[16:17], v[8:11], off
	v_cvt_pk_bf16_f32 v4, v4, v5
	v_cvt_pk_bf16_f32 v5, v6, v7
	v_cvt_pk_bf16_f32 v6, v0, v1
	v_cvt_pk_bf16_f32 v7, v2, v3
	global_store_dwordx4 v[16:17], v[4:7], off offset:256
	s_cbranch_vccnz .LBB0_481
	s_andn2_b64 vcc, exec, s[0:1]
	s_cbranch_vccnz .LBB0_480
	s_barrier
	s_branch .LBB0_480

; #define LAS __attribute__((address_space(3)))
; #define tid  (fresh_tid_w(wave_s))
; #define lane (hw_lane())
; __device__ __forceinline__ void pool_load(const bf16* proj, int it, int lane, v4u (&raw)[12]) {
;     const int chunk = it >> 4, g = (it >> 2) & 3, rq = it & 3; proj += (size_t)(chunk >> 6) * GAP_P;
;     const size_t R0 = (size_t)chunk * 128 + rq * 32; const int tseq = (int)(R0 & (SEQ - 1)), r = lane & 15, q = lane >> 4;
; #pragma unroll
;     for (int i = 0; i < 12; ++i) { const int row = q + 4 * i; raw[i] = (v4u){0u, 0u, 0u, 0u};
;         if (row >= 16 || tseq != 0) raw[i] = __builtin_nontemporal_load((const v4u*)(proj + (R0 + row - 16) * DIN + g * 128 + r * 8)); }
; }
; __device__ __forceinline__ void mixer_phase(LAS unsigned char* lds, const bf16* proj, bf16* ymix, const float* vstat, const bf16* WpT, const float* pscale, const float* sgu_g, const bf16* Wm, const float* sgu_b, int pool_first, int pool_step, int pool_limit, int sgu_first, int sgu_step, int sgu_limi ...
;     int tid = tid_in; asm volatile("" : "+v"(tid));
;     const int lane = tid & 63, wave = __builtin_amdgcn_readfirstlane(tid >> 6);
;     LAS unsigned char* wl = lds + wave * MIXW;
;     { v4u raw[12]; if (pool_first < pool_limit) pool_load(proj, pool_first, lane, raw);
.LBB0_492:
	s_mov_b64 s[26:27], s[58:59]
	s_mov_b64 s[20:21], s[58:59]
	s_mov_b64 s[38:39], s[58:59]
	v_mbcnt_lo_u32_b32 v0, -1, 0
	v_mbcnt_hi_u32_b32 v0, -1, v0
	s_nop 0
	v_or_b32_e32 v81, s93, v0
	s_nop 0
	s_nop 0
	v_readfirstlane_b32 s0, v81
	s_lshr_b32 s10, s0, 6
	v_readlane_b32 s0, v254, 42
	v_and_b32_e32 v140, 63, v81
	s_mulk_i32 s10, 0x3300
	v_readlane_b32 s1, v254, 43
	s_add_i32 s2, s10, 0x100
	s_andn2_b64 vcc, exec, s[0:1]
	v_lshlrev_b32_e32 v83, 3, v140
	s_cbranch_vccnz .LBB0_508
	s_add_u32 s9, s26, 0xf100000
	s_addc_u32 s12, s27, 0
	v_readlane_b32 s0, v255, 19
	v_readlane_b32 s6, v254, 46
	s_add_u32 s0, s9, s0
	v_readlane_b32 s1, v255, 18
	v_and_b32_e32 v0, 0x78, v83
	v_readlane_b32 s7, v254, 47
	s_addc_u32 s1, s12, s1
	v_lshrrev_b32_e32 v80, 4, v140
	s_andn2_b64 vcc, exec, s[6:7]
	s_mul_i32 s11, s5, 0xc00
	v_lshlrev_b32_e32 v192, 1, v0
	s_cbranch_vccnz .LBB0_495
	v_or_b32_e32 v4, s4, v80
	v_mov_b64_e32 v[0:1], s[0:1]
	s_movk_i32 s7, 0xc00
	v_mad_u64_u32 v[2:3], s[4:5], v4, s7, v[0:1]
	v_readlane_b32 s4, v254, 48
	v_add_u32_e32 v3, s11, v3
	s_lshl_b32 s86, s4, 1
	v_or_b32_e32 v4, 4, v4
	v_lshl_add_u64 v[2:3], v[2:3], 0, s[86:87]
	v_mad_u64_u32 v[0:1], s[4:5], v4, s7, v[0:1]
	v_lshl_add_u64 v[2:3], v[2:3], 0, v[192:193]
	v_add_u32_e32 v1, s11, v1
	v_add_co_u32_e32 v2, vcc, s83, v2
	v_lshl_add_u64 v[0:1], v[0:1], 0, s[86:87]
	s_nop 0
	v_addc_co_u32_e32 v3, vcc, -1, v3, vcc
	v_lshl_add_u64 v[0:1], v[0:1], 0, v[192:193]
	v_add_co_u32_e32 v4, vcc, 0xffff4000, v0
	s_nop 1
	v_addc_co_u32_e32 v5, vcc, -1, v1, vcc
	global_load_dwordx4 v[0:3], v[2:3], off nt
	s_nop 0
	global_load_dwordx4 v[4:7], v[4:5], off nt
	s_branch .LBB0_496

; #define lane (hw_lane())
; __device__ __forceinline__ void pool_load(const bf16* proj, int it, int lane, v4u (&raw)[12]) {
;     const int chunk = it >> 4, g = (it >> 2) & 3, rq = it & 3; proj += (size_t)(chunk >> 6) * GAP_P;
;     const size_t R0 = (size_t)chunk * 128 + rq * 32; const int tseq = (int)(R0 & (SEQ - 1)), r = lane & 15, q = lane >> 4;
; #pragma unroll
;     for (int i = 0; i < 12; ++i) { const int row = q + 4 * i; raw[i] = (v4u){0u, 0u, 0u, 0u};
;         if (row >= 16 || tseq != 0) raw[i] = __builtin_nontemporal_load((const v4u*)(proj + (R0 + row - 16) * DIN + g * 128 + r * 8)); }
; }
.LBB0_496:
	v_readlane_b32 s4, v254, 46
	v_readlane_b32 s5, v254, 47
	v_or_b32_e32 v82, 8, v80
	s_and_b64 vcc, exec, s[4:5]
	v_or_b32_e32 v16, 12, v80
	s_cbranch_vccz .LBB0_525
	v_readlane_b32 s6, v254, 44
	v_readlane_b32 s7, v254, 45
	s_movk_i32 s7, 0xc00
	v_or_b32_e32 v10, s6, v82
	v_mov_b64_e32 v[8:9], s[0:1]
	v_mad_u64_u32 v[10:11], s[4:5], v10, s7, v[8:9]
	v_readlane_b32 s4, v254, 48
	v_or_b32_e32 v48, 12, v80
	v_add_u32_e32 v11, s11, v11
	s_lshl_b32 s86, s4, 1
	v_or_b32_e32 v12, s6, v48
	v_lshl_add_u64 v[10:11], v[10:11], 0, s[86:87]
	v_mad_u64_u32 v[8:9], s[4:5], v12, s7, v[8:9]
	v_lshl_add_u64 v[10:11], v[10:11], 0, v[192:193]
	v_add_u32_e32 v9, s11, v9
	v_add_co_u32_e32 v10, vcc, s83, v10
	v_lshl_add_u64 v[8:9], v[8:9], 0, s[86:87]
	s_nop 0
	v_addc_co_u32_e32 v11, vcc, -1, v11, vcc
	v_lshl_add_u64 v[8:9], v[8:9], 0, v[192:193]
	v_add_co_u32_e32 v12, vcc, 0xffff4000, v8
	v_mov_b32_e32 v49, v193
	s_nop 0
	v_addc_co_u32_e32 v13, vcc, -1, v9, vcc
	global_load_dwordx4 v[8:11], v[10:11], off nt
	s_nop 0
	global_load_dwordx4 v[12:15], v[12:13], off nt
	v_mov_b64_e32 v[84:85], v[48:49]
	s_cbranch_execnz .LBB0_499

; #define LAS __attribute__((address_space(3)))
; #define LDS_WAIT() asm volatile("s_waitcnt lgkmcnt(0)" ::: "memory")
; #define lane (hw_lane())
; __device__ __forceinline__ void pool_load(const bf16* proj, int it, int lane, v4u (&raw)[12]) {
;     const int chunk = it >> 4, g = (it >> 2) & 3, rq = it & 3; proj += (size_t)(chunk >> 6) * GAP_P;
;     const size_t R0 = (size_t)chunk * 128 + rq * 32; const int tseq = (int)(R0 & (SEQ - 1)), r = lane & 15, q = lane >> 4;
; #pragma unroll
;     for (int i = 0; i < 12; ++i) { const int row = q + 4 * i; raw[i] = (v4u){0u, 0u, 0u, 0u};
;         if (row >= 16 || tseq != 0) raw[i] = __builtin_nontemporal_load((const v4u*)(proj + (R0 + row - 16) * DIN + g * 128 + r * 8)); }
; }
; __device__ __forceinline__ void pool_item(LAS unsigned char* wl, const bf16* proj, bf16* ymix, const bf16* WpT, const float* pscale, int chunk, int g, int rq, int lane, v4u (&raw)[12], int nxt_it) {
;     ymix += (size_t)(chunk >> 6) * GAP_Y;
;     const size_t R0 = (size_t)chunk * 128 + rq * 32; const int tseq = (int)(R0 & (SEQ - 1));
;     const int r = lane & 15, q = lane >> 4, win = 2 << g;
; #pragma unroll
;     for (int i = 0; i < 12; ++i) *(LAS v4u*)(wl + (q + 4 * i) * PP + r * 16) = raw[i];
;     LDS_WAIT();
;     if (nxt_it >= 0) pool_load(proj, nxt_it, lane, raw);
.LBB0_499:
	v_readlane_b32 s4, v254, 44
	v_or_b32_e32 v86, 44, v80
	v_mov_b32_e32 v87, v193
	v_readlane_b32 s5, v254, 45
	v_mov_b64_e32 v[40:41], s[0:1]
	s_add_u32 s13, s20, 0x10900000
	v_lshl_add_u64 v[16:17], s[4:5], 0, v[86:87]
	v_mad_u64_u32 v[18:19], s[0:1], v16, s7, v[40:41]
	v_mov_b32_e32 v16, v19
	v_mad_u64_u32 v[16:17], s[0:1], v17, s7, v[16:17]
	v_readlane_b32 s0, v254, 48
	v_or_b32_e32 v90, 36, v80
	v_mov_b32_e32 v91, v193
	s_addc_u32 s14, s21, 0
	v_mov_b32_e32 v19, v16
	s_lshl_b32 s86, s0, 1
	v_or_b32_e32 v88, 40, v80
	v_mov_b32_e32 v89, v193
	v_lshl_add_u64 v[24:25], s[4:5], 0, v[90:91]
	v_lshl_add_u64 v[16:17], v[18:19], 0, s[86:87]
	v_lshl_add_u64 v[18:19], s[4:5], 0, v[88:89]
	v_mad_u64_u32 v[26:27], s[0:1], v24, s7, v[40:41]
	v_mad_u64_u32 v[20:21], s[0:1], v18, s7, v[40:41]
	v_mov_b32_e32 v24, v27
	v_mov_b32_e32 v18, v21
	v_mad_u64_u32 v[24:25], s[0:1], v25, s7, v[24:25]
	v_mad_u64_u32 v[18:19], s[0:1], v19, s7, v[18:19]
	v_mov_b32_e32 v27, v24
	v_or_b32_e32 v92, 32, v80
	v_mov_b32_e32 v93, v193
	v_lshl_add_u64 v[16:17], v[16:17], 0, v[192:193]
	v_mov_b32_e32 v21, v18
	v_lshl_add_u64 v[24:25], v[26:27], 0, s[86:87]
	v_lshl_add_u64 v[26:27], s[4:5], 0, v[92:93]
	v_add_co_u32_e32 v16, vcc, s83, v16
	v_lshl_add_u64 v[18:19], v[20:21], 0, s[86:87]
	v_mad_u64_u32 v[28:29], s[0:1], v26, s7, v[40:41]
	v_addc_co_u32_e32 v17, vcc, -1, v17, vcc
	v_lshl_add_u64 v[18:19], v[18:19], 0, v[192:193]
	v_mov_b32_e32 v26, v29
	v_add_co_u32_e32 v18, vcc, s83, v18
	v_mad_u64_u32 v[26:27], s[0:1], v27, s7, v[26:27]
	s_nop 0
	v_addc_co_u32_e32 v19, vcc, -1, v19, vcc
	v_lshl_add_u64 v[24:25], v[24:25], 0, v[192:193]
	v_mov_b32_e32 v29, v26
	v_add_co_u32_e32 v24, vcc, s83, v24
	v_lshl_add_u64 v[26:27], v[28:29], 0, s[86:87]
	s_nop 0
	v_addc_co_u32_e32 v25, vcc, -1, v25, vcc
	v_lshl_add_u64 v[26:27], v[26:27], 0, v[192:193]
	v_add_co_u32_e32 v26, vcc, s83, v26
	v_or_b32_e32 v94, 28, v80
	global_load_dwordx4 v[20:23], v[16:17], off nt
	s_nop 0
	global_load_dwordx4 v[16:19], v[18:19], off nt
	v_addc_co_u32_e32 v27, vcc, -1, v27, vcc
	global_load_dwordx4 v[36:39], v[24:25], off nt
	global_load_dwordx4 v[32:35], v[26:27], off nt
	v_or_b32_e32 v24, s4, v94
	v_mad_u64_u32 v[24:25], s[0:1], v24, s7, v[40:41]
	v_or_b32_e32 v96, 24, v80
	v_add_u32_e32 v25, s11, v25
	v_or_b32_e32 v26, s4, v96
	v_lshl_add_u64 v[24:25], v[24:25], 0, s[86:87]
	v_mad_u64_u32 v[26:27], s[0:1], v26, s7, v[40:41]
	v_or_b32_e32 v98, 20, v80
	v_lshl_add_u64 v[24:25], v[24:25], 0, v[192:193]
	v_add_u32_e32 v27, s11, v27
	v_or_b32_e32 v42, s4, v98
	v_add_co_u32_e32 v24, vcc, s83, v24
	v_lshl_add_u64 v[26:27], v[26:27], 0, s[86:87]
	v_mad_u64_u32 v[42:43], s[0:1], v42, s7, v[40:41]
	v_or_b32_e32 v100, 16, v80
	v_addc_co_u32_e32 v25, vcc, -1, v25, vcc
	v_lshl_add_u64 v[26:27], v[26:27], 0, v[192:193]
	v_add_u32_e32 v43, s11, v43
	v_or_b32_e32 v44, s4, v100
	v_add_co_u32_e32 v26, vcc, s83, v26
	v_lshl_add_u64 v[42:43], v[42:43], 0, s[86:87]
	v_mad_u64_u32 v[40:41], s[0:1], v44, s7, v[40:41]
	v_addc_co_u32_e32 v27, vcc, -1, v27, vcc
	v_lshl_add_u64 v[42:43], v[42:43], 0, v[192:193]
	v_add_u32_e32 v41, s11, v41
	v_add_co_u32_e32 v42, vcc, s83, v42
	v_lshl_add_u64 v[40:41], v[40:41], 0, s[86:87]
	s_nop 0
	v_addc_co_u32_e32 v43, vcc, -1, v43, vcc
	v_lshl_add_u64 v[40:41], v[40:41], 0, v[192:193]
	v_add_co_u32_e32 v40, vcc, s83, v40
	global_load_dwordx4 v[28:31], v[24:25], off nt
	s_nop 0
	global_load_dwordx4 v[24:27], v[26:27], off nt
	v_addc_co_u32_e32 v41, vcc, -1, v41, vcc
	global_load_dwordx4 v[44:47], v[42:43], off nt
	s_nop 0
	global_load_dwordx4 v[40:43], v[40:41], off nt
	v_and_b32_e32 v49, 15, v81
	v_lshlrev_b32_e32 v104, 3, v80
	v_lshlrev_b32_e32 v50, 4, v49
	v_mul_i32_i24_e32 v52, 0x110, v48
	v_or_b32_e32 v106, 1, v104
	v_lshlrev_b32_e32 v48, 3, v49
	v_mov_b32_e32 v49, s10
	s_movk_i32 s0, 0x880
	v_add_u32_e32 v95, s2, v50
	v_mul_u32_u24_e32 v51, 0x110, v80
	v_mul_u32_u24_e32 v53, 0x880, v80
	v_mul_u32_u24_e32 v54, 0x110, v106
	v_mad_u32_u24 v49, v80, s0, v49
	v_readlane_b32 s0, v255, 23
	v_or_b32_e32 v102, 4, v80
	v_or_b32_e32 v108, 2, v104
	v_or_b32_e32 v110, 3, v104
	v_or_b32_e32 v112, 4, v104
	v_or_b32_e32 v114, 5, v104
	v_or_b32_e32 v116, 6, v104
	v_or_b32_e32 v118, 7, v104
	v_add3_u32 v97, v49, v50, s0
	v_add_u32_e32 v99, v95, v51
	v_add_u32_e32 v101, v95, v52
	v_add_u32_e32 v103, v95, v53
	v_add_u32_e32 v105, v95, v54
	v_lshlrev_b32_e32 v120, 1, v48
	v_readlane_b32 s22, v254, 60
.LBB0_500:
	s_add_i32 s15, s22, s77
	v_readlane_b32 s4, v254, 41
	s_cmp_ge_i32 s15, s4
	s_waitcnt vmcnt(0) lgkmcnt(0)
	ds_write_b128 v99, v[0:3]
	ds_write_b128 v99, v[4:7] offset:1088
	ds_write_b128 v99, v[8:11] offset:2176
	ds_write_b128 v101, v[12:15]
	ds_write_b128 v99, v[40:43] offset:4352
	ds_write_b128 v99, v[44:47] offset:5440
	ds_write_b128 v99, v[24:27] offset:6528
	ds_write_b128 v99, v[28:31] offset:7616
	ds_write_b128 v99, v[32:35] offset:8704
	ds_write_b128 v99, v[36:39] offset:9792
	ds_write_b128 v99, v[16:19] offset:10880
	ds_write_b128 v99, v[20:23] offset:11968
	s_cselect_b64 s[0:1], -1, 0
	s_cmp_lt_i32 s15, s4
	s_waitcnt lgkmcnt(0)
	s_cselect_b32 s23, s15, -1
	s_cmp_lt_i32 s23, 0
	s_cbranch_scc1 .LBB0_505
	s_lshr_b32 s4, s23, 10
	s_lshr_b32 s86, s23, 4
	s_mul_hi_u32 s5, s4, 0x1400000
	s_mul_i32 s4, s4, 0x1400000
	s_add_u32 s10, s9, s4
	s_addc_u32 s11, s12, s5
	s_lshl_b32 s23, s23, 5
	s_lshl_b64 s[4:5], s[86:87], 7
	s_and_b32 s6, s23, 0x60
	s_or_b32 s4, s4, s6
	s_and_b32 s86, s4, 0x1fe0
	s_and_b32 s23, s23, 0x180
	s_cmp_eq_u64 s[86:87], 0
	s_cbranch_scc1 .LBB0_503
	v_or_b32_e32 v0, s4, v80
	v_mov_b64_e32 v[8:9], s[10:11]
	v_mad_u64_u32 v[0:1], s[24:25], v0, s7, v[8:9]
	v_mad_u32_u24 v1, s5, v242, v1
	s_lshl_b32 s86, s23, 1
	v_or_b32_e32 v2, s4, v102
	v_lshl_add_u64 v[0:1], v[0:1], 0, s[86:87]
	v_mad_u64_u32 v[2:3], s[24:25], v2, s7, v[8:9]
	v_lshl_add_u64 v[0:1], v[0:1], 0, v[192:193]
	v_mad_u32_u24 v3, s5, v242, v3
	v_or_b32_e32 v10, s4, v82
	v_or_b32_e32 v12, s4, v84
	v_add_co_u32_e32 v0, vcc, s83, v0
	v_lshl_add_u64 v[2:3], v[2:3], 0, s[86:87]
	v_mad_u64_u32 v[10:11], s[24:25], v10, s7, v[8:9]
	v_mad_u64_u32 v[8:9], s[24:25], v12, s7, v[8:9]
	v_addc_co_u32_e32 v1, vcc, -1, v1, vcc
	v_lshl_add_u64 v[2:3], v[2:3], 0, v[192:193]
	v_mad_u32_u24 v11, s5, v242, v11
	v_or_b32_e32 v13, s5, v85
	v_mov_b32_e32 v12, v9
	v_add_co_u32_e32 v4, vcc, s83, v2
	v_lshl_add_u64 v[10:11], v[10:11], 0, s[86:87]
	v_mad_u64_u32 v[12:13], s[24:25], v13, s7, v[12:13]
	v_addc_co_u32_e32 v5, vcc, -1, v3, vcc
	v_lshl_add_u64 v[10:11], v[10:11], 0, v[192:193]
	v_mov_b32_e32 v9, v12
	v_add_co_u32_e32 v10, vcc, s83, v10
	v_lshl_add_u64 v[8:9], v[8:9], 0, s[86:87]
	s_nop 0
	v_addc_co_u32_e32 v11, vcc, -1, v11, vcc
	v_lshl_add_u64 v[8:9], v[8:9], 0, v[192:193]
	v_add_co_u32_e32 v12, vcc, 0xffff4000, v8
	global_load_dwordx4 v[0:3], v[0:1], off nt
	s_nop 0
	global_load_dwordx4 v[4:7], v[4:5], off nt
	v_addc_co_u32_e32 v13, vcc, -1, v9, vcc
	global_load_dwordx4 v[8:11], v[10:11], off nt
	s_nop 0
	global_load_dwordx4 v[12:15], v[12:13], off nt
	s_branch .LBB0_504

; #define lane (hw_lane())
; __device__ __forceinline__ void pool_load(const bf16* proj, int it, int lane, v4u (&raw)[12]) {
;     const int chunk = it >> 4, g = (it >> 2) & 3, rq = it & 3; proj += (size_t)(chunk >> 6) * GAP_P;
;     const size_t R0 = (size_t)chunk * 128 + rq * 32; const int tseq = (int)(R0 & (SEQ - 1)), r = lane & 15, q = lane >> 4;
; #pragma unroll
;     for (int i = 0; i < 12; ++i) { const int row = q + 4 * i; raw[i] = (v4u){0u, 0u, 0u, 0u};
;         if (row >= 16 || tseq != 0) raw[i] = __builtin_nontemporal_load((const v4u*)(proj + (R0 + row - 16) * DIN + g * 128 + r * 8)); }
; }
.LBB0_504:
	v_or_b32_e32 v18, s4, v100
	v_mov_b64_e32 v[16:17], s[10:11]
	v_mad_u64_u32 v[18:19], s[10:11], v18, s7, v[16:17]
	v_mad_u32_u24 v19, s5, v242, v19
	s_lshl_b32 s86, s23, 1
	v_or_b32_e32 v20, s4, v98
	v_lshl_add_u64 v[18:19], v[18:19], 0, s[86:87]
	v_mad_u64_u32 v[20:21], s[10:11], v20, s7, v[16:17]
	v_lshl_add_u64 v[18:19], v[18:19], 0, v[192:193]
	v_mad_u32_u24 v21, s5, v242, v21
	v_add_co_u32_e32 v18, vcc, s83, v18
	v_lshl_add_u64 v[20:21], v[20:21], 0, s[86:87]
	s_nop 0
	v_addc_co_u32_e32 v19, vcc, -1, v19, vcc
	v_lshl_add_u64 v[20:21], v[20:21], 0, v[192:193]
	v_add_co_u32_e32 v20, vcc, s83, v20
	s_nop 1
	v_addc_co_u32_e32 v21, vcc, -1, v21, vcc
	global_load_dwordx4 v[40:43], v[18:19], off nt
	global_load_dwordx4 v[44:47], v[20:21], off nt
	v_or_b32_e32 v18, s4, v96
	v_mad_u64_u32 v[18:19], s[10:11], v18, s7, v[16:17]
	v_mad_u32_u24 v19, s5, v242, v19
	v_or_b32_e32 v20, s4, v94
	v_lshl_add_u64 v[18:19], v[18:19], 0, s[86:87]
	v_mad_u64_u32 v[20:21], s[10:11], v20, s7, v[16:17]
	v_lshl_add_u64 v[18:19], v[18:19], 0, v[192:193]
	v_mad_u32_u24 v21, s5, v242, v21
	v_add_co_u32_e32 v18, vcc, s83, v18
	v_lshl_add_u64 v[20:21], v[20:21], 0, s[86:87]
	s_nop 0
	v_addc_co_u32_e32 v19, vcc, -1, v19, vcc
	v_lshl_add_u64 v[20:21], v[20:21], 0, v[192:193]
	v_add_co_u32_e32 v20, vcc, s83, v20
	s_nop 1
	v_addc_co_u32_e32 v21, vcc, -1, v21, vcc
	global_load_dwordx4 v[24:27], v[18:19], off nt
	global_load_dwordx4 v[28:31], v[20:21], off nt
	v_lshl_add_u64 v[18:19], s[4:5], 0, v[92:93]
	v_mad_u64_u32 v[20:21], s[10:11], v18, s7, v[16:17]
	v_mad_u32_u24 v21, v19, s7, v21
	v_lshl_add_u64 v[18:19], v[20:21], 0, s[86:87]
	v_lshl_add_u64 v[20:21], s[4:5], 0, v[90:91]
	v_mad_u64_u32 v[22:23], s[10:11], v20, s7, v[16:17]
	v_lshl_add_u64 v[18:19], v[18:19], 0, v[192:193]
	v_mad_u32_u24 v23, v21, s7, v23
	v_add_co_u32_e32 v18, vcc, s83, v18
	v_lshl_add_u64 v[20:21], v[22:23], 0, s[86:87]
	s_nop 0
	v_addc_co_u32_e32 v19, vcc, -1, v19, vcc
	v_lshl_add_u64 v[20:21], v[20:21], 0, v[192:193]
	v_add_co_u32_e32 v20, vcc, s83, v20
	s_nop 1
	v_addc_co_u32_e32 v21, vcc, -1, v21, vcc
	global_load_dwordx4 v[32:35], v[18:19], off nt
	global_load_dwordx4 v[36:39], v[20:21], off nt
	v_lshl_add_u64 v[18:19], s[4:5], 0, v[88:89]
	v_mad_u64_u32 v[20:21], s[10:11], v18, s7, v[16:17]
	v_mad_u32_u24 v21, v19, s7, v21
	v_lshl_add_u64 v[18:19], v[20:21], 0, s[86:87]
	v_lshl_add_u64 v[20:21], s[4:5], 0, v[86:87]
	v_mad_u64_u32 v[16:17], s[4:5], v20, s7, v[16:17]
	v_lshl_add_u64 v[18:19], v[18:19], 0, v[192:193]
	v_mad_u32_u24 v17, v21, s7, v17
	v_add_co_u32_e32 v18, vcc, s83, v18
	v_lshl_add_u64 v[16:17], v[16:17], 0, s[86:87]
	s_nop 0
	v_addc_co_u32_e32 v19, vcc, -1, v19, vcc
	v_lshl_add_u64 v[16:17], v[16:17], 0, v[192:193]
	v_add_co_u32_e32 v20, vcc, 0xffff4000, v16
	s_nop 1
	v_addc_co_u32_e32 v21, vcc, -1, v17, vcc
	global_load_dwordx4 v[16:19], v[18:19], off nt
	s_nop 0
	global_load_dwordx4 v[20:23], v[20:21], off nt

; #define LAS __attribute__((address_space(3)))
; __device__ __forceinline__ unsigned pk2(float lo, float hi) { return f2bf(lo) | (f2bf(hi) << 16); }
; __device__ __forceinline__ float bflo(unsigned w) { return __uint_as_float(w << 16); }
; __device__ __forceinline__ float bfhi(unsigned w) { return __uint_as_float(w & 0xffff0000u); }
; __device__ __forceinline__ void pool_item(LAS unsigned char* wl, const bf16* proj, bf16* ymix, const bf16* WpT, const float* pscale, int chunk, int g, int rq, int lane, v4u (&raw)[12], int nxt_it) {
;     ...
;         for (int k = 1; k < win; ++k) { const v4u v = *(const LAS v4u*)(wl + (8 * q + 16 - k) * PP + r * 16);
;             s8[0] += bflo(v.x); s8[1] += bfhi(v.x); s8[2] += bflo(v.y); s8[3] += bfhi(v.y); s8[4] += bflo(v.z); s8[5] += bfhi(v.z); s8[6] += bflo(v.w); s8[7] += bfhi(v.w); }
; #pragma unroll
;         for (int i = 0; i < 8; ++i) { const int t = 8 * q + i;
;             const v4u cur = *(const LAS v4u*)(wl + (t + 16) * PP + r * 16);
;             s8[0] += bflo(cur.x); s8[1] += bfhi(cur.x); s8[2] += bflo(cur.y); s8[3] += bfhi(cur.y); s8[4] += bflo(cur.z); s8[5] += bfhi(cur.z); s8[6] += bflo(cur.w); s8[7] += bfhi(cur.w);
;             const int cnt = min(tseq + t + 1, win); const float inv = 1.0f / (float)cnt;
;             dv[i].x = pk2(s8[0] * inv - bflo(cur.x), s8[1] * inv - bfhi(cur.x)); dv[i].y = pk2(s8[2] * inv - bflo(cur.y), s8[3] * inv - bfhi(cur.y));
;             dv[i].z = pk2(s8[4] * inv - bflo(cur.z), s8[5] * inv - bfhi(cur.z)); dv[i].w = pk2(s8[6] * inv - bflo(cur.w), s8[7] * inv - bfhi(cur.w));
;             const v4u old = *(const LAS v4u*)(wl + (t + 16 - (win - 1)) * PP + r * 16);
;             s8[0] -= bflo(old.x); s8[1] -= bfhi(old.x); s8[2] -= bflo(old.y); s8[3] -= bfhi(old.y); s8[4] -= bflo(old.z); s8[5] -= bfhi(old.z); s8[6] -= bflo(old.w); s8[7] -= bfhi(old.w); }
.LBB0_506:
	ds_read_b128 v[58:61], v56
	s_add_i32 s4, s4, -1
	v_add_u32_e32 v56, 0xfffffef0, v56
	s_cmp_lg_u32 s4, 0
	s_waitcnt lgkmcnt(0)
	v_lshlrev_b32_e32 v63, 16, v59
	v_lshlrev_b32_e32 v62, 16, v58
	v_and_b32_e32 v59, 0xffff0000, v59
	v_and_b32_e32 v58, 0xffff0000, v58
	v_pk_add_f32 v[52:53], v[52:53], v[58:59]
	v_lshlrev_b32_e32 v59, 16, v61
	v_lshlrev_b32_e32 v58, 16, v60
	v_and_b32_e32 v61, 0xffff0000, v61
	v_and_b32_e32 v60, 0xffff0000, v60
	v_pk_add_f32 v[54:55], v[54:55], v[62:63]
	v_pk_add_f32 v[48:49], v[48:49], v[58:59]
	v_pk_add_f32 v[50:51], v[50:51], v[60:61]
	s_cbranch_scc1 .LBB0_506
	s_ashr_i32 s4, s22, 4
	s_ashr_i32 s5, s4, 31
	s_lshl_b32 s11, s22, 5
	s_lshl_b64 s[4:5], s[4:5], 7
	s_and_b32 s11, s11, 0x60
	ds_read_b128 v[56:59], v103 offset:4352
	s_or_b32 s4, s4, s11
	s_ashr_i32 s11, s22, 10
	s_and_b32 s23, s4, 0x1fe0
	s_mul_hi_i32 s22, s11, 0x1c00000
	s_mul_i32 s11, s11, 0x1c00000
	s_add_u32 s11, s13, s11
	s_addc_u32 s22, s14, s22
	s_or_b32 s23, s23, 1
	s_waitcnt lgkmcnt(0)
	v_lshlrev_b32_e32 v68, 16, v58
	v_and_b32_e32 v70, 0xffff0000, v58
	v_or_b32_e32 v58, s23, v104
	v_min_u32_e32 v58, s10, v58
	v_cvt_f32_ubyte0_e32 v58, v58
	v_lshlrev_b32_e32 v69, 16, v59
	v_and_b32_e32 v71, 0xffff0000, v59
	v_div_scale_f32 v59, s[24:25], v58, v58, 1.0
	v_rcp_f32_e32 v60, v59
	v_add_u32_e32 v73, s23, v106
	v_min_u32_e32 v73, s10, v73
	v_cvt_f32_ubyte0_e32 v73, v73
	v_fma_f32 v61, -v59, v60, 1.0
	v_fmac_f32_e32 v60, v61, v60
	v_div_scale_f32 v61, vcc, 1.0, v58, 1.0
	v_mul_f32_e32 v62, v61, v60
	v_div_scale_f32 v74, s[24:25], v73, v73, 1.0
	v_fma_f32 v63, -v59, v62, v61
	v_rcp_f32_e32 v75, v74
	v_fmac_f32_e32 v62, v63, v60
	v_fma_f32 v59, -v59, v62, v61
	v_div_fmas_f32 v59, v59, v60, v62
	v_div_fixup_f32 v72, v59, v58, 1.0
	v_subrev_u32_e32 v58, s10, v104
	s_movk_i32 s8, 0x110
	v_fma_f32 v76, -v74, v75, 1.0
	v_mad_i32_i24 v58, v58, s8, v95
	v_fmac_f32_e32 v75, v76, v75
	v_div_scale_f32 v76, vcc, 1.0, v73, 1.0
	ds_read_b128 v[58:61], v58 offset:4624
	ds_read_b128 v[62:65], v105 offset:4352
	v_mul_f32_e32 v77, v76, v75
	v_fma_f32 v78, -v74, v77, v76
	v_lshlrev_b32_e32 v66, 16, v56
	v_and_b32_e32 v56, 0xffff0000, v56
	v_lshlrev_b32_e32 v67, 16, v57
	v_and_b32_e32 v57, 0xffff0000, v57
	v_fmac_f32_e32 v77, v78, v75
	v_fma_f32 v74, -v74, v77, v76
	v_pk_add_f32 v[52:53], v[52:53], v[56:57]
	v_div_fmas_f32 v74, v74, v75, v77
	v_pk_add_f32 v[54:55], v[54:55], v[66:67]
	v_pk_fma_f32 v[76:77], v[72:73], v[52:53], v[56:57] op_sel_hi:[0,1,1] neg_lo:[0,0,1] neg_hi:[0,0,1]
	s_waitcnt lgkmcnt(0)
	v_lshlrev_b32_e32 v57, 16, v59
	v_lshlrev_b32_e32 v56, 16, v58
	v_pk_fma_f32 v[66:67], v[72:73], v[54:55], v[66:67] op_sel_hi:[0,1,1] neg_lo:[0,0,1] neg_hi:[0,0,1]
	v_pk_add_f32 v[54:55], v[54:55], v[56:57] neg_lo:[0,1] neg_hi:[0,1]
	v_and_b32_e32 v57, 0xffff0000, v59
	v_and_b32_e32 v56, 0xffff0000, v58
	v_pk_add_f32 v[52:53], v[52:53], v[56:57] neg_lo:[0,1] neg_hi:[0,1]
	v_lshlrev_b32_e32 v57, 16, v63
	v_lshlrev_b32_e32 v56, 16, v62
	v_div_fixup_f32 v74, v74, v73, 1.0
	v_pk_add_f32 v[58:59], v[54:55], v[56:57]
	v_and_b32_e32 v55, 0xffff0000, v63
	v_and_b32_e32 v54, 0xffff0000, v62
	v_pk_add_f32 v[62:63], v[52:53], v[54:55]
	v_pk_fma_f32 v[52:53], v[74:75], v[58:59], v[56:57] op_sel_hi:[0,1,1] neg_lo:[0,0,1] neg_hi:[0,0,1]
	v_pk_add_f32 v[48:49], v[48:49], v[68:69]
	v_lshlrev_b32_e32 v57, 16, v61
	v_lshlrev_b32_e32 v56, 16, v60
	v_pk_add_f32 v[50:51], v[50:51], v[70:71]
	v_pk_fma_f32 v[68:69], v[72:73], v[48:49], v[68:69] op_sel_hi:[0,1,1] neg_lo:[0,0,1] neg_hi:[0,0,1]
	v_pk_add_f32 v[48:49], v[48:49], v[56:57] neg_lo:[0,1] neg_hi:[0,1]
	v_and_b32_e32 v57, 0xffff0000, v61
	v_and_b32_e32 v56, 0xffff0000, v60
	v_pk_fma_f32 v[70:71], v[72:73], v[50:51], v[70:71] op_sel_hi:[0,1,1] neg_lo:[0,0,1] neg_hi:[0,0,1]
	v_pk_add_f32 v[50:51], v[50:51], v[56:57] neg_lo:[0,1] neg_hi:[0,1]
	v_lshlrev_b32_e32 v73, 16, v65
	v_lshlrev_b32_e32 v72, 16, v64
	v_and_b32_e32 v65, 0xffff0000, v65
	v_and_b32_e32 v64, 0xffff0000, v64
	v_pk_add_f32 v[56:57], v[48:49], v[72:73]
	v_pk_add_f32 v[60:61], v[50:51], v[64:65]
	v_bfe_u32 v48, v71, 16, 1
	v_bfe_u32 v49, v70, 16, 1
	v_bfe_u32 v50, v77, 16, 1
	v_bfe_u32 v51, v76, 16, 1
	v_pk_fma_f32 v[54:55], v[74:75], v[62:63], v[54:55] op_sel_hi:[0,1,1] neg_lo:[0,0,1] neg_hi:[0,0,1]
	v_add3_u32 v75, v76, v51, s68
	v_add3_u32 v76, v77, v50, s68
	v_add3_u32 v49, v70, v49, s68
	v_add3_u32 v48, v71, v48, s68
	v_bfe_u32 v50, v66, 16, 1
	v_bfe_u32 v51, v67, 16, 1
	v_bfe_u32 v70, v68, 16, 1
	v_bfe_u32 v71, v69, 16, 1
	v_add3_u32 v69, v69, v71, s68
	v_add3_u32 v68, v68, v70, s68
	v_add3_u32 v51, v67, v51, s68
	v_add3_u32 v50, v66, v50, s68
	v_lshrrev_b32_e32 v66, 16, v50
	v_lshrrev_b32_e32 v67, 16, v51
	v_lshrrev_b32_e32 v50, 16, v68
	v_lshrrev_b32_e32 v51, 16, v69
	v_pk_fma_f32 v[64:65], v[74:75], v[60:61], v[64:65] op_sel_hi:[0,1,1] neg_lo:[0,0,1] neg_hi:[0,0,1]
	v_and_or_b32 v51, v48, s37, v51
	v_and_or_b32 v50, v49, s37, v50
	v_and_or_b32 v49, v76, s37, v67
	v_and_or_b32 v48, v75, s37, v66
	v_pk_fma_f32 v[66:67], v[74:75], v[56:57], v[72:73] op_sel_hi:[0,1,1] neg_lo:[0,0,1] neg_hi:[0,0,1]
	v_bfe_u32 v68, v65, 16, 1
	v_bfe_u32 v70, v55, 16, 1
	v_bfe_u32 v69, v64, 16, 1
	v_bfe_u32 v71, v54, 16, 1
	v_add3_u32 v70, v55, v70, s68
	v_add3_u32 v55, v65, v68, s68
	v_bfe_u32 v68, v66, 16, 1
	v_add3_u32 v71, v54, v71, s68
	v_add3_u32 v54, v64, v69, s68
	v_bfe_u32 v64, v52, 16, 1
	v_add3_u32 v66, v66, v68, s68
	v_bfe_u32 v69, v67, 16, 1
	v_add3_u32 v52, v52, v64, s68
	v_lshrrev_b32_e32 v64, 16, v66
	v_bfe_u32 v65, v53, 16, 1
	v_add3_u32 v67, v67, v69, s68
	v_and_or_b32 v54, v54, s37, v64
	v_subrev_u32_e32 v64, s10, v106
	v_add3_u32 v53, v53, v65, s68
	v_lshrrev_b32_e32 v65, 16, v67
	v_mad_i32_i24 v64, v64, s8, v95
	v_and_or_b32 v55, v55, s37, v65
	ds_read_b128 v[64:67], v64 offset:4624
	ds_read_b128 v[72:75], v105 offset:4624
	v_add_u32_e32 v107, s23, v110
	v_min_u32_e32 v107, s10, v107
	v_cvt_f32_ubyte0_e32 v107, v107
	v_div_scale_f32 v109, s[24:25], v107, v107, 1.0
	s_waitcnt lgkmcnt(0)
; #define LAS __attribute__((address_space(3)))
; __device__ __forceinline__ unsigned pk2(float lo, float hi) { return f2bf(lo) | (f2bf(hi) << 16); }
; __device__ __forceinline__ float bflo(unsigned w) { return __uint_as_float(w << 16); }
; __device__ __forceinline__ float bfhi(unsigned w) { return __uint_as_float(w & 0xffff0000u); }
; __device__ __forceinline__ void pool_item(LAS unsigned char* wl, const bf16* proj, bf16* ymix, const bf16* WpT, const float* pscale, int chunk, int g, int rq, int lane, v4u (&raw)[12], int nxt_it) {
;     ...
;         for (int i = 0; i < 8; ++i) { const int t = 8 * q + i;
;             const v4u cur = *(const LAS v4u*)(wl + (t + 16) * PP + r * 16);
;             s8[0] += bflo(cur.x); s8[1] += bfhi(cur.x); s8[2] += bflo(cur.y); s8[3] += bfhi(cur.y); s8[4] += bflo(cur.z); s8[5] += bfhi(cur.z); s8[6] += bflo(cur.w); s8[7] += bfhi(cur.w);
;             const int cnt = min(tseq + t + 1, win); const float inv = 1.0f / (float)cnt;
;             dv[i].x = pk2(s8[0] * inv - bflo(cur.x), s8[1] * inv - bfhi(cur.x)); dv[i].y = pk2(s8[2] * inv - bflo(cur.y), s8[3] * inv - bfhi(cur.y));
;             dv[i].z = pk2(s8[4] * inv - bflo(cur.z), s8[5] * inv - bfhi(cur.z)); dv[i].w = pk2(s8[6] * inv - bflo(cur.w), s8[7] * inv - bfhi(cur.w));
;             const v4u old = *(const LAS v4u*)(wl + (t + 16 - (win - 1)) * PP + r * 16);
;             s8[0] -= bflo(old.x); s8[1] -= bfhi(old.x); s8[2] -= bflo(old.y); s8[3] -= bfhi(old.y); s8[4] -= bflo(old.z); s8[5] -= bfhi(old.z); s8[6] -= bflo(old.w); s8[7] -= bfhi(old.w); }
	v_lshlrev_b32_e32 v122, 16, v72
	v_and_b32_e32 v124, 0xffff0000, v72
	v_or_b32_e32 v72, s23, v108
	v_min_u32_e32 v72, s10, v72
	v_cvt_f32_ubyte0_e32 v72, v72
	v_lshlrev_b32_e32 v123, 16, v73
	v_and_b32_e32 v125, 0xffff0000, v73
	v_div_scale_f32 v73, s[24:25], v72, v72, 1.0
	v_lshlrev_b32_e32 v126, 16, v74
	v_and_b32_e32 v128, 0xffff0000, v74
	v_rcp_f32_e32 v74, v73
	v_lshlrev_b32_e32 v127, 16, v75
	v_and_b32_e32 v129, 0xffff0000, v75
	v_rcp_f32_e32 v111, v109
	v_fma_f32 v75, -v73, v74, 1.0
	v_fmac_f32_e32 v74, v75, v74
	v_div_scale_f32 v75, vcc, 1.0, v72, 1.0
	v_mul_f32_e32 v76, v75, v74
	v_fma_f32 v77, -v73, v76, v75
	v_fmac_f32_e32 v76, v77, v74
	v_fma_f32 v73, -v73, v76, v75
	v_div_fmas_f32 v73, v73, v74, v76
	v_div_fixup_f32 v130, v73, v72, 1.0
	v_subrev_u32_e32 v72, s10, v108
	v_mad_i32_i24 v72, v72, s8, v95
	ds_read_b128 v[72:75], v72 offset:4624
	ds_read_b128 v[76:79], v105 offset:4896
	v_fma_f32 v113, -v109, v111, 1.0
	v_lshrrev_b32_e32 v52, 16, v52
	v_lshrrev_b32_e32 v53, 16, v53
	v_lshlrev_b32_e32 v69, 16, v65
	v_lshlrev_b32_e32 v68, 16, v64
	v_fmac_f32_e32 v111, v113, v111
	v_div_scale_f32 v113, vcc, 1.0, v107, 1.0
	v_and_or_b32 v53, v70, s37, v53
	v_and_or_b32 v52, v71, s37, v52
	v_and_b32_e32 v71, 0xffff0000, v65
	v_and_b32_e32 v70, 0xffff0000, v64
	v_mul_f32_e32 v115, v113, v111
	v_pk_add_f32 v[58:59], v[58:59], v[68:69] neg_lo:[0,1] neg_hi:[0,1]
	v_fma_f32 v117, -v109, v115, v113
	v_pk_add_f32 v[62:63], v[62:63], v[70:71] neg_lo:[0,1] neg_hi:[0,1]
	v_pk_add_f32 v[58:59], v[58:59], v[122:123]
	v_fmac_f32_e32 v115, v117, v111
	v_pk_add_f32 v[62:63], v[62:63], v[124:125]
	v_pk_fma_f32 v[68:69], v[130:131], v[58:59], v[122:123] op_sel_hi:[0,1,1] neg_lo:[0,0,1] neg_hi:[0,0,1]
	s_waitcnt lgkmcnt(0)
	v_lshlrev_b32_e32 v123, 16, v73
	v_lshlrev_b32_e32 v122, 16, v72
	v_and_b32_e32 v73, 0xffff0000, v73
	v_and_b32_e32 v72, 0xffff0000, v72
	v_fma_f32 v109, -v109, v115, v113
	v_pk_fma_f32 v[70:71], v[130:131], v[62:63], v[124:125] op_sel_hi:[0,1,1] neg_lo:[0,0,1] neg_hi:[0,0,1]
	v_pk_add_f32 v[58:59], v[58:59], v[122:123] neg_lo:[0,1] neg_hi:[0,1]
	v_pk_add_f32 v[62:63], v[62:63], v[72:73] neg_lo:[0,1] neg_hi:[0,1]
	v_lshlrev_b32_e32 v73, 16, v77
	v_lshlrev_b32_e32 v72, 16, v76
	v_lshlrev_b32_e32 v65, 16, v67
	v_lshlrev_b32_e32 v64, 16, v66
	v_div_fmas_f32 v109, v109, v111, v115
	v_pk_add_f32 v[122:123], v[58:59], v[72:73]
	v_and_b32_e32 v59, 0xffff0000, v77
	v_and_b32_e32 v58, 0xffff0000, v76
	v_and_b32_e32 v67, 0xffff0000, v67
	v_and_b32_e32 v66, 0xffff0000, v66
	v_div_fixup_f32 v132, v109, v107, 1.0
	v_pk_add_f32 v[76:77], v[62:63], v[58:59]
	v_pk_add_f32 v[56:57], v[56:57], v[64:65] neg_lo:[0,1] neg_hi:[0,1]
	v_pk_fma_f32 v[62:63], v[132:133], v[122:123], v[72:73] op_sel_hi:[0,1,1] neg_lo:[0,0,1] neg_hi:[0,0,1]
	v_pk_fma_f32 v[72:73], v[132:133], v[76:77], v[58:59] op_sel_hi:[0,1,1] neg_lo:[0,0,1] neg_hi:[0,0,1]
	v_pk_add_f32 v[58:59], v[60:61], v[66:67] neg_lo:[0,1] neg_hi:[0,1]
	v_pk_add_f32 v[56:57], v[56:57], v[126:127]
	v_lshlrev_b32_e32 v67, 16, v75
	v_lshlrev_b32_e32 v66, 16, v74
	v_pk_add_f32 v[58:59], v[58:59], v[128:129]
	v_pk_fma_f32 v[60:61], v[130:131], v[56:57], v[126:127] op_sel_hi:[0,1,1] neg_lo:[0,0,1] neg_hi:[0,0,1]
	v_pk_add_f32 v[56:57], v[56:57], v[66:67] neg_lo:[0,1] neg_hi:[0,1]
	v_and_b32_e32 v67, 0xffff0000, v75
	v_and_b32_e32 v66, 0xffff0000, v74
	v_pk_fma_f32 v[64:65], v[130:131], v[58:59], v[128:129] op_sel_hi:[0,1,1] neg_lo:[0,0,1] neg_hi:[0,0,1]
	v_pk_add_f32 v[58:59], v[58:59], v[66:67] neg_lo:[0,1] neg_hi:[0,1]
	v_lshlrev_b32_e32 v67, 16, v79
	v_lshlrev_b32_e32 v66, 16, v78
	v_and_b32_e32 v79, 0xffff0000, v79
	v_and_b32_e32 v78, 0xffff0000, v78
	v_pk_add_f32 v[74:75], v[56:57], v[66:67]
	v_pk_add_f32 v[124:125], v[58:59], v[78:79]
	v_bfe_u32 v56, v65, 16, 1
	v_bfe_u32 v57, v64, 16, 1
	v_bfe_u32 v58, v71, 16, 1
	v_bfe_u32 v59, v70, 16, 1
	v_add3_u32 v70, v70, v59, s68
	v_add3_u32 v71, v71, v58, s68
	v_add3_u32 v57, v64, v57, s68
	v_add3_u32 v56, v65, v56, s68
	v_bfe_u32 v58, v68, 16, 1
	v_bfe_u32 v59, v69, 16, 1
	v_bfe_u32 v64, v60, 16, 1
	v_bfe_u32 v65, v61, 16, 1
	v_add3_u32 v61, v61, v65, s68
	v_add3_u32 v60, v60, v64, s68
	v_add3_u32 v59, v69, v59, s68
	v_add3_u32 v58, v68, v58, s68
	v_lshrrev_b32_e32 v64, 16, v58
	v_lshrrev_b32_e32 v65, 16, v59
	v_lshrrev_b32_e32 v58, 16, v60
	v_lshrrev_b32_e32 v59, 16, v61
	v_and_or_b32 v59, v56, s37, v59
	v_and_or_b32 v58, v57, s37, v58
	v_and_or_b32 v57, v71, s37, v65
	v_and_or_b32 v56, v70, s37, v64
	v_pk_fma_f32 v[60:61], v[132:133], v[74:75], v[66:67] op_sel_hi:[0,1,1] neg_lo:[0,0,1] neg_hi:[0,0,1]
	v_pk_fma_f32 v[64:65], v[132:133], v[124:125], v[78:79] op_sel_hi:[0,1,1] neg_lo:[0,0,1] neg_hi:[0,0,1]
	v_bfe_u32 v66, v65, 16, 1
	v_bfe_u32 v70, v60, 16, 1
	v_bfe_u32 v67, v64, 16, 1
	v_add3_u32 v65, v65, v66, s68
	v_bfe_u32 v66, v62, 16, 1
	v_add3_u32 v60, v60, v70, s68
	v_add3_u32 v64, v64, v67, s68
	v_bfe_u32 v67, v63, 16, 1
	v_bfe_u32 v71, v61, 16, 1
	v_add3_u32 v62, v62, v66, s68
	v_lshrrev_b32_e32 v60, 16, v60
	v_bfe_u32 v68, v73, 16, 1
	v_bfe_u32 v69, v72, 16, 1
	v_add3_u32 v61, v61, v71, s68
	v_add3_u32 v63, v63, v67, s68
	v_lshrrev_b32_e32 v66, 16, v62
	v_and_or_b32 v62, v64, s37, v60
	v_subrev_u32_e32 v64, s10, v110
	v_add3_u32 v69, v72, v69, s68
	v_add3_u32 v68, v73, v68, s68
	v_lshrrev_b32_e32 v67, 16, v63
	v_lshrrev_b32_e32 v61, 16, v61
	v_mad_i32_i24 v64, v64, s8, v95
	v_and_or_b32 v63, v65, s37, v61
	v_and_or_b32 v61, v68, s37, v67
	v_and_or_b32 v60, v69, s37, v66
	ds_read_b128 v[64:67], v64 offset:4624
	v_add_u32_e32 v107, s23, v114
	v_min_u32_e32 v107, s10, v107
	v_cvt_f32_ubyte0_e32 v107, v107
	v_div_scale_f32 v109, s[24:25], v107, v107, 1.0
	s_waitcnt lgkmcnt(0)
; #define LAS __attribute__((address_space(3)))
; __device__ __forceinline__ unsigned pk2(float lo, float hi) { return f2bf(lo) | (f2bf(hi) << 16); }
; __device__ __forceinline__ float bflo(unsigned w) { return __uint_as_float(w << 16); }
; __device__ __forceinline__ float bfhi(unsigned w) { return __uint_as_float(w & 0xffff0000u); }
; __device__ __forceinline__ void pool_item(LAS unsigned char* wl, const bf16* proj, bf16* ymix, const bf16* WpT, const float* pscale, int chunk, int g, int rq, int lane, v4u (&raw)[12], int nxt_it) {
;     ...
;         for (int i = 0; i < 8; ++i) { const int t = 8 * q + i;
;             const v4u cur = *(const LAS v4u*)(wl + (t + 16) * PP + r * 16);
;             s8[0] += bflo(cur.x); s8[1] += bfhi(cur.x); s8[2] += bflo(cur.y); s8[3] += bfhi(cur.y); s8[4] += bflo(cur.z); s8[5] += bfhi(cur.z); s8[6] += bflo(cur.w); s8[7] += bfhi(cur.w);
;             const int cnt = min(tseq + t + 1, win); const float inv = 1.0f / (float)cnt;
;             dv[i].x = pk2(s8[0] * inv - bflo(cur.x), s8[1] * inv - bfhi(cur.x)); dv[i].y = pk2(s8[2] * inv - bflo(cur.y), s8[3] * inv - bfhi(cur.y));
;             dv[i].z = pk2(s8[4] * inv - bflo(cur.z), s8[5] * inv - bfhi(cur.z)); dv[i].w = pk2(s8[6] * inv - bflo(cur.w), s8[7] * inv - bfhi(cur.w));
;             const v4u old = *(const LAS v4u*)(wl + (t + 16 - (win - 1)) * PP + r * 16);
;             s8[0] -= bflo(old.x); s8[1] -= bfhi(old.x); s8[2] -= bflo(old.y); s8[3] -= bfhi(old.y); s8[4] -= bflo(old.z); s8[5] -= bfhi(old.z); s8[6] -= bflo(old.w); s8[7] -= bfhi(old.w); }
	v_lshlrev_b32_e32 v73, 16, v65
	v_lshlrev_b32_e32 v72, 16, v64
	v_and_b32_e32 v79, 0xffff0000, v65
	v_and_b32_e32 v78, 0xffff0000, v64
	v_lshlrev_b32_e32 v131, 16, v67
	v_lshlrev_b32_e32 v130, 16, v66
	v_and_b32_e32 v133, 0xffff0000, v67
	v_and_b32_e32 v132, 0xffff0000, v66
	ds_read_b128 v[64:67], v105 offset:5168
	v_rcp_f32_e32 v111, v109
	v_pk_add_f32 v[76:77], v[76:77], v[78:79] neg_lo:[0,1] neg_hi:[0,1]
	v_pk_add_f32 v[72:73], v[122:123], v[72:73] neg_lo:[0,1] neg_hi:[0,1]
	s_lshl_b32 s6, s6, 8
	s_waitcnt lgkmcnt(0)
	v_lshlrev_b32_e32 v126, 16, v64
	v_and_b32_e32 v128, 0xffff0000, v64
	v_or_b32_e32 v64, s23, v112
	v_min_u32_e32 v64, s10, v64
	v_cvt_f32_ubyte0_e32 v64, v64
	v_lshlrev_b32_e32 v127, 16, v65
	v_and_b32_e32 v129, 0xffff0000, v65
	v_div_scale_f32 v65, s[24:25], v64, v64, 1.0
	v_lshlrev_b32_e32 v134, 16, v66
	v_and_b32_e32 v136, 0xffff0000, v66
	v_rcp_f32_e32 v66, v65
	v_lshlrev_b32_e32 v135, 16, v67
	v_and_b32_e32 v137, 0xffff0000, v67
	v_fma_f32 v113, -v109, v111, 1.0
	v_fma_f32 v67, -v65, v66, 1.0
	v_fmac_f32_e32 v66, v67, v66
	v_div_scale_f32 v67, vcc, 1.0, v64, 1.0
	v_mul_f32_e32 v68, v67, v66
	v_fma_f32 v69, -v65, v68, v67
	v_fmac_f32_e32 v68, v69, v66
	v_fma_f32 v65, -v65, v68, v67
	v_div_fmas_f32 v65, v65, v66, v68
	v_div_fixup_f32 v138, v65, v64, 1.0
	v_subrev_u32_e32 v64, s10, v112
	v_mad_i32_i24 v64, v64, s8, v95
	ds_read_b128 v[64:67], v64 offset:4624
	ds_read_b128 v[68:71], v105 offset:5440
	v_fmac_f32_e32 v111, v113, v111
	v_div_scale_f32 v113, vcc, 1.0, v107, 1.0
	v_mul_f32_e32 v115, v113, v111
	v_fma_f32 v117, -v109, v115, v113
	v_pk_add_f32 v[76:77], v[76:77], v[128:129]
	s_waitcnt lgkmcnt(0)
	v_lshlrev_b32_e32 v123, 16, v65
	v_lshlrev_b32_e32 v122, 16, v64
	v_and_b32_e32 v65, 0xffff0000, v65
	v_and_b32_e32 v64, 0xffff0000, v64
	v_fmac_f32_e32 v115, v117, v111
	v_pk_fma_f32 v[144:145], v[138:139], v[76:77], v[128:129] op_sel_hi:[0,1,1] neg_lo:[0,0,1] neg_hi:[0,0,1]
	v_pk_add_f32 v[64:65], v[76:77], v[64:65] neg_lo:[0,1] neg_hi:[0,1]
	v_lshlrev_b32_e32 v77, 16, v69
	v_lshlrev_b32_e32 v76, 16, v68
	v_and_b32_e32 v69, 0xffff0000, v69
	v_and_b32_e32 v68, 0xffff0000, v68
	v_fma_f32 v109, -v109, v115, v113
	v_pk_add_f32 v[72:73], v[72:73], v[126:127]
	v_pk_add_f32 v[128:129], v[64:65], v[68:69]
	v_pk_add_f32 v[64:65], v[74:75], v[130:131] neg_lo:[0,1] neg_hi:[0,1]
	v_pk_add_f32 v[74:75], v[124:125], v[132:133] neg_lo:[0,1] neg_hi:[0,1]
	v_div_fmas_f32 v109, v109, v111, v115
	v_pk_fma_f32 v[78:79], v[138:139], v[72:73], v[126:127] op_sel_hi:[0,1,1] neg_lo:[0,0,1] neg_hi:[0,0,1]
	v_pk_add_f32 v[72:73], v[72:73], v[122:123] neg_lo:[0,1] neg_hi:[0,1]
	v_pk_add_f32 v[74:75], v[74:75], v[136:137]
	v_lshlrev_b32_e32 v123, 16, v67
	v_lshlrev_b32_e32 v122, 16, v66
	v_and_b32_e32 v67, 0xffff0000, v67
	v_and_b32_e32 v66, 0xffff0000, v66
	v_div_fixup_f32 v142, v109, v107, 1.0
	v_pk_add_f32 v[126:127], v[72:73], v[76:77]
	v_pk_add_f32 v[64:65], v[64:65], v[134:135]
	v_pk_fma_f32 v[130:131], v[138:139], v[74:75], v[136:137] op_sel_hi:[0,1,1] neg_lo:[0,0,1] neg_hi:[0,0,1]
	v_pk_add_f32 v[66:67], v[74:75], v[66:67] neg_lo:[0,1] neg_hi:[0,1]
	v_lshlrev_b32_e32 v75, 16, v71
	v_lshlrev_b32_e32 v74, 16, v70
	v_and_b32_e32 v71, 0xffff0000, v71
	v_and_b32_e32 v70, 0xffff0000, v70
	v_pk_fma_f32 v[72:73], v[142:143], v[126:127], v[76:77] op_sel_hi:[0,1,1] neg_lo:[0,0,1] neg_hi:[0,0,1]
	v_pk_fma_f32 v[76:77], v[138:139], v[64:65], v[134:135] op_sel_hi:[0,1,1] neg_lo:[0,0,1] neg_hi:[0,0,1]
	v_pk_add_f32 v[124:125], v[66:67], v[70:71]
	v_bfe_u32 v66, v145, 16, 1
	v_bfe_u32 v67, v144, 16, 1
	v_add3_u32 v109, v145, v66, s68
	v_bfe_u32 v66, v78, 16, 1
	v_bfe_u32 v111, v76, 16, 1
	v_pk_add_f32 v[64:65], v[64:65], v[122:123] neg_lo:[0,1] neg_hi:[0,1]
	v_add3_u32 v107, v144, v67, s68
	v_bfe_u32 v67, v79, 16, 1
	v_bfe_u32 v113, v77, 16, 1
	v_add3_u32 v76, v76, v111, s68
	v_add3_u32 v66, v78, v66, s68
	v_pk_fma_f32 v[70:71], v[142:143], v[124:125], v[70:71] op_sel_hi:[0,1,1] neg_lo:[0,0,1] neg_hi:[0,0,1]
	v_pk_add_f32 v[122:123], v[64:65], v[74:75]
	v_bfe_u32 v64, v131, 16, 1
	v_bfe_u32 v65, v130, 16, 1
	v_add3_u32 v77, v77, v113, s68
	v_add3_u32 v67, v79, v67, s68
	v_lshrrev_b32_e32 v78, 16, v66
	v_lshrrev_b32_e32 v66, 16, v76
	v_bfe_u32 v76, v71, 16, 1
	v_pk_fma_f32 v[68:69], v[142:143], v[128:129], v[68:69] op_sel_hi:[0,1,1] neg_lo:[0,0,1] neg_hi:[0,0,1]
	v_add3_u32 v65, v130, v65, s68
	v_add3_u32 v64, v131, v64, s68
	v_lshrrev_b32_e32 v79, 16, v67
	v_lshrrev_b32_e32 v67, 16, v77
	v_add3_u32 v71, v71, v76, s68
	v_bfe_u32 v76, v72, 16, 1
	v_and_or_b32 v67, v64, s37, v67
	v_and_or_b32 v66, v65, s37, v66
	v_and_or_b32 v65, v109, s37, v79
	v_and_or_b32 v64, v107, s37, v78
	v_pk_fma_f32 v[74:75], v[142:143], v[122:123], v[74:75] op_sel_hi:[0,1,1] neg_lo:[0,0,1] neg_hi:[0,0,1]
	v_bfe_u32 v77, v70, 16, 1
	v_bfe_u32 v78, v69, 16, 1
	v_bfe_u32 v79, v68, 16, 1
	v_add3_u32 v72, v72, v76, s68
	v_add3_u32 v68, v68, v79, s68
	v_add3_u32 v69, v69, v78, s68
	v_add3_u32 v70, v70, v77, s68
	v_bfe_u32 v77, v73, 16, 1
	v_bfe_u32 v78, v74, 16, 1
	v_bfe_u32 v79, v75, 16, 1
	v_lshrrev_b32_e32 v72, 16, v72
	v_add3_u32 v75, v75, v79, s68
	v_add3_u32 v74, v74, v78, s68
	v_add3_u32 v73, v73, v77, s68
	v_and_or_b32 v68, v68, s37, v72
	v_subrev_u32_e32 v72, s10, v114
	v_lshrrev_b32_e32 v73, 16, v73
	v_lshrrev_b32_e32 v74, 16, v74
	v_lshrrev_b32_e32 v75, 16, v75
	v_mad_i32_i24 v72, v72, s8, v95
	v_and_or_b32 v71, v71, s37, v75
	v_and_or_b32 v70, v70, s37, v74
	v_and_or_b32 v69, v69, s37, v73
	ds_read_b128 v[72:75], v72 offset:4624
	v_add_u32_e32 v107, s23, v118
	v_min_u32_e32 v107, s10, v107
	v_cvt_f32_ubyte0_e32 v107, v107
	v_div_scale_f32 v109, s[24:25], v107, v107, 1.0
	s_waitcnt lgkmcnt(0)
; #define LAS __attribute__((address_space(3)))
; __device__ __forceinline__ unsigned pk2(float lo, float hi) { return f2bf(lo) | (f2bf(hi) << 16); }
; __device__ __forceinline__ float bflo(unsigned w) { return __uint_as_float(w << 16); }
; __device__ __forceinline__ float bfhi(unsigned w) { return __uint_as_float(w & 0xffff0000u); }
; __device__ __forceinline__ void pool_item(LAS unsigned char* wl, const bf16* proj, bf16* ymix, const bf16* WpT, const float* pscale, int chunk, int g, int rq, int lane, v4u (&raw)[12], int nxt_it) {
;     ...
;         for (int i = 0; i < 8; ++i) { const int t = 8 * q + i;
;             const v4u cur = *(const LAS v4u*)(wl + (t + 16) * PP + r * 16);
;             s8[0] += bflo(cur.x); s8[1] += bfhi(cur.x); s8[2] += bflo(cur.y); s8[3] += bfhi(cur.y); s8[4] += bflo(cur.z); s8[5] += bfhi(cur.z); s8[6] += bflo(cur.w); s8[7] += bfhi(cur.w);
;             const int cnt = min(tseq + t + 1, win); const float inv = 1.0f / (float)cnt;
;             dv[i].x = pk2(s8[0] * inv - bflo(cur.x), s8[1] * inv - bfhi(cur.x)); dv[i].y = pk2(s8[2] * inv - bflo(cur.y), s8[3] * inv - bfhi(cur.y));
;             dv[i].z = pk2(s8[4] * inv - bflo(cur.z), s8[5] * inv - bfhi(cur.z)); dv[i].w = pk2(s8[6] * inv - bflo(cur.w), s8[7] * inv - bfhi(cur.w));
;             const v4u old = *(const LAS v4u*)(wl + (t + 16 - (win - 1)) * PP + r * 16);
;             s8[0] -= bflo(old.x); s8[1] -= bfhi(old.x); s8[2] -= bflo(old.y); s8[3] -= bfhi(old.y); s8[4] -= bflo(old.z); s8[5] -= bfhi(old.z); s8[6] -= bflo(old.w); s8[7] -= bfhi(old.w); }
	v_lshlrev_b32_e32 v147, 16, v73
	v_lshlrev_b32_e32 v146, 16, v72
	v_and_b32_e32 v149, 0xffff0000, v73
	v_and_b32_e32 v148, 0xffff0000, v72
	v_lshlrev_b32_e32 v131, 16, v75
	v_lshlrev_b32_e32 v130, 16, v74
	v_and_b32_e32 v133, 0xffff0000, v75
	v_and_b32_e32 v132, 0xffff0000, v74
	ds_read_b128 v[72:75], v105 offset:5712
	v_rcp_f32_e32 v111, v109
	v_pk_add_f32 v[128:129], v[128:129], v[148:149] neg_lo:[0,1] neg_hi:[0,1]
	v_pk_add_f32 v[126:127], v[126:127], v[146:147] neg_lo:[0,1] neg_hi:[0,1]
	v_mov_b32_e32 v121, v193
	s_waitcnt lgkmcnt(0)
	v_lshlrev_b32_e32 v144, 16, v72
	v_and_b32_e32 v142, 0xffff0000, v72
	v_or_b32_e32 v72, s23, v116
	v_min_u32_e32 v72, s10, v72
	v_cvt_f32_ubyte0_e32 v72, v72
	v_lshlrev_b32_e32 v145, 16, v73
	v_and_b32_e32 v143, 0xffff0000, v73
	v_div_scale_f32 v73, s[24:25], v72, v72, 1.0
	v_lshlrev_b32_e32 v136, 16, v74
	v_and_b32_e32 v134, 0xffff0000, v74
	v_rcp_f32_e32 v74, v73
	v_lshlrev_b32_e32 v137, 16, v75
	v_and_b32_e32 v135, 0xffff0000, v75
	v_fma_f32 v113, -v109, v111, 1.0
	v_fma_f32 v75, -v73, v74, 1.0
	v_fmac_f32_e32 v74, v75, v74
	v_div_scale_f32 v75, vcc, 1.0, v72, 1.0
	v_mul_f32_e32 v76, v75, v74
	v_fma_f32 v77, -v73, v76, v75
	v_fmac_f32_e32 v76, v77, v74
	v_fma_f32 v73, -v73, v76, v75
	v_div_fmas_f32 v73, v73, v74, v76
	v_div_fixup_f32 v138, v73, v72, 1.0
	v_subrev_u32_e32 v72, s10, v116
	v_mad_i32_i24 v72, v72, s8, v95
	ds_read_b128 v[72:75], v72 offset:4624
	ds_read_b128 v[76:79], v105 offset:5984
	v_fmac_f32_e32 v111, v113, v111
	v_div_scale_f32 v113, vcc, 1.0, v107, 1.0
	v_mul_f32_e32 v115, v113, v111
	v_fma_f32 v117, -v109, v115, v113
	v_fmac_f32_e32 v115, v117, v111
	v_fma_f32 v109, -v109, v115, v113
	v_pk_add_f32 v[128:129], v[128:129], v[142:143]
	s_waitcnt lgkmcnt(0)
; #define LAS __attribute__((address_space(3)))
; __device__ __forceinline__ unsigned pk2(float lo, float hi) { return f2bf(lo) | (f2bf(hi) << 16); }
; __device__ __forceinline__ float bflo(unsigned w) { return __uint_as_float(w << 16); }
; __device__ __forceinline__ float bfhi(unsigned w) { return __uint_as_float(w & 0xffff0000u); }
; #define LDS_WAIT() asm volatile("s_waitcnt lgkmcnt(0)" ::: "memory")
; __device__ __forceinline__ void pool_item(LAS unsigned char* wl, const bf16* proj, bf16* ymix, const bf16* WpT, const float* pscale, int chunk, int g, int rq, int lane, v4u (&raw)[12], int nxt_it) {
;     ...
;         for (int i = 0; i < 8; ++i) { const int t = 8 * q + i;
;             const v4u cur = *(const LAS v4u*)(wl + (t + 16) * PP + r * 16);
;             s8[0] += bflo(cur.x); s8[1] += bfhi(cur.x); s8[2] += bflo(cur.y); s8[3] += bfhi(cur.y); s8[4] += bflo(cur.z); s8[5] += bfhi(cur.z); s8[6] += bflo(cur.w); s8[7] += bfhi(cur.w);
;             const int cnt = min(tseq + t + 1, win); const float inv = 1.0f / (float)cnt;
;             dv[i].x = pk2(s8[0] * inv - bflo(cur.x), s8[1] * inv - bfhi(cur.x)); dv[i].y = pk2(s8[2] * inv - bflo(cur.y), s8[3] * inv - bfhi(cur.y));
;             dv[i].z = pk2(s8[4] * inv - bflo(cur.z), s8[5] * inv - bfhi(cur.z)); dv[i].w = pk2(s8[6] * inv - bflo(cur.w), s8[7] * inv - bfhi(cur.w));
;             const v4u old = *(const LAS v4u*)(wl + (t + 16 - (win - 1)) * PP + r * 16);
;             s8[0] -= bflo(old.x); s8[1] -= bfhi(old.x); s8[2] -= bflo(old.y); s8[3] -= bfhi(old.y); s8[4] -= bflo(old.z); s8[5] -= bfhi(old.z); s8[6] -= bflo(old.w); s8[7] -= bfhi(old.w); }
;     }
; #pragma unroll
;     for (int i = 0; i < 8; ++i) *(v4u*)(ymix + (R0 + 8 * q + i) * D + g * 128 + r * 8) = dv[i];
;     LDS_WAIT();
	v_lshlrev_b32_e32 v147, 16, v73
	v_lshlrev_b32_e32 v146, 16, v72
	v_and_b32_e32 v73, 0xffff0000, v73
	v_and_b32_e32 v72, 0xffff0000, v72
	v_div_fmas_f32 v109, v109, v111, v115
	v_pk_fma_f32 v[142:143], v[138:139], v[128:129], v[142:143] op_sel_hi:[0,1,1] neg_lo:[0,0,1] neg_hi:[0,0,1]
	v_pk_add_f32 v[72:73], v[128:129], v[72:73] neg_lo:[0,1] neg_hi:[0,1]
	v_lshlrev_b32_e32 v129, 16, v77
	v_lshlrev_b32_e32 v128, 16, v76
	v_and_b32_e32 v77, 0xffff0000, v77
	v_and_b32_e32 v76, 0xffff0000, v76
	v_div_fixup_f32 v150, v109, v107, 1.0
	v_pk_add_f32 v[126:127], v[126:127], v[144:145]
	v_pk_add_f32 v[72:73], v[72:73], v[76:77]
	v_pk_fma_f32 v[144:145], v[138:139], v[126:127], v[144:145] op_sel_hi:[0,1,1] neg_lo:[0,0,1] neg_hi:[0,0,1]
	v_pk_add_f32 v[126:127], v[126:127], v[146:147] neg_lo:[0,1] neg_hi:[0,1]
	v_pk_fma_f32 v[76:77], v[150:151], v[72:73], v[76:77] op_sel_hi:[0,1,1] neg_lo:[0,0,1] neg_hi:[0,0,1]
	v_pk_add_f32 v[72:73], v[122:123], v[130:131] neg_lo:[0,1] neg_hi:[0,1]
	v_pk_add_f32 v[122:123], v[124:125], v[132:133] neg_lo:[0,1] neg_hi:[0,1]
	v_pk_add_f32 v[126:127], v[126:127], v[128:129]
	v_pk_add_f32 v[122:123], v[122:123], v[134:135]
	v_lshlrev_b32_e32 v131, 16, v75
	v_lshlrev_b32_e32 v130, 16, v74
	v_and_b32_e32 v75, 0xffff0000, v75
	v_and_b32_e32 v74, 0xffff0000, v74
	v_pk_fma_f32 v[126:127], v[150:151], v[126:127], v[128:129] op_sel_hi:[0,1,1] neg_lo:[0,0,1] neg_hi:[0,0,1]
	v_pk_add_f32 v[72:73], v[72:73], v[136:137]
	v_pk_fma_f32 v[128:129], v[138:139], v[122:123], v[134:135] op_sel_hi:[0,1,1] neg_lo:[0,0,1] neg_hi:[0,0,1]
	v_pk_add_f32 v[74:75], v[122:123], v[74:75] neg_lo:[0,1] neg_hi:[0,1]
	v_lshlrev_b32_e32 v123, 16, v79
	v_lshlrev_b32_e32 v122, 16, v78
	v_and_b32_e32 v79, 0xffff0000, v79
	v_and_b32_e32 v78, 0xffff0000, v78
	v_pk_fma_f32 v[124:125], v[138:139], v[72:73], v[136:137] op_sel_hi:[0,1,1] neg_lo:[0,0,1] neg_hi:[0,0,1]
	v_pk_add_f32 v[132:133], v[74:75], v[78:79]
	v_bfe_u32 v74, v143, 16, 1
	v_bfe_u32 v75, v142, 16, 1
	v_pk_add_f32 v[72:73], v[72:73], v[130:131] neg_lo:[0,1] neg_hi:[0,1]
	v_add3_u32 v107, v142, v75, s68
	v_add3_u32 v109, v143, v74, s68
	v_bfe_u32 v74, v144, 16, 1
	v_bfe_u32 v75, v145, 16, 1
	v_bfe_u32 v111, v124, 16, 1
	v_bfe_u32 v113, v125, 16, 1
	v_pk_add_f32 v[130:131], v[72:73], v[122:123]
	v_add3_u32 v113, v125, v113, s68
	v_add3_u32 v111, v124, v111, s68
	v_add3_u32 v75, v145, v75, s68
	v_add3_u32 v74, v144, v74, s68
	v_lshrrev_b32_e32 v115, 16, v74
	v_lshrrev_b32_e32 v117, 16, v75
	v_lshrrev_b32_e32 v74, 16, v111
	v_lshrrev_b32_e32 v75, 16, v113
	v_pk_fma_f32 v[122:123], v[150:151], v[130:131], v[122:123] op_sel_hi:[0,1,1] neg_lo:[0,0,1] neg_hi:[0,0,1]
	v_bfe_u32 v111, v77, 16, 1
	v_bfe_u32 v113, v76, 16, 1
	s_add_u32 s10, s11, s6
	v_add3_u32 v76, v76, v113, s68
	v_add3_u32 v77, v77, v111, s68
	v_bfe_u32 v111, v122, 16, 1
	v_bfe_u32 v113, v123, 16, 1
	s_addc_u32 s11, s22, 0
	v_mov_b32_e32 v125, s5
	v_or_b32_e32 v124, s4, v104
	v_add3_u32 v113, v123, v113, s68
	v_add3_u32 v111, v122, v111, s68
	v_lshl_add_u64 v[122:123], s[10:11], 0, v[120:121]
	v_lshlrev_b64 v[124:125], 11, v[124:125]
	v_lshl_add_u64 v[124:125], v[122:123], 0, v[124:125]
	global_store_dwordx4 v[124:125], v[48:51], off
	v_bfe_u32 v72, v129, 16, 1
	v_bfe_u32 v73, v128, 16, 1
	v_mov_b32_e32 v49, s5
	v_or_b32_e32 v48, s4, v106
	v_lshlrev_b64 v[48:49], 11, v[48:49]
	v_lshl_add_u64 v[48:49], v[122:123], 0, v[48:49]
	global_store_dwordx4 v[48:49], v[52:55], off
	v_mov_b32_e32 v49, s5
	v_or_b32_e32 v48, s4, v108
	v_lshlrev_b64 v[48:49], 11, v[48:49]
	v_lshl_add_u64 v[48:49], v[122:123], 0, v[48:49]
	global_store_dwordx4 v[48:49], v[56:59], off
	v_mov_b32_e32 v49, s5
	v_or_b32_e32 v48, s4, v110
	v_lshlrev_b64 v[48:49], 11, v[48:49]
	v_lshl_add_u64 v[48:49], v[122:123], 0, v[48:49]
	global_store_dwordx4 v[48:49], v[60:63], off
	v_mov_b32_e32 v49, s5
	v_or_b32_e32 v48, s4, v112
	v_lshlrev_b64 v[48:49], 11, v[48:49]
	v_lshl_add_u64 v[48:49], v[122:123], 0, v[48:49]
	global_store_dwordx4 v[48:49], v[64:67], off
	v_mov_b32_e32 v49, s5
	v_or_b32_e32 v48, s4, v114
	v_lshlrev_b64 v[48:49], 11, v[48:49]
	v_lshl_add_u64 v[48:49], v[122:123], 0, v[48:49]
	v_add3_u32 v73, v128, v73, s68
	v_add3_u32 v72, v129, v72, s68
	v_pk_fma_f32 v[78:79], v[150:151], v[132:133], v[78:79] op_sel_hi:[0,1,1] neg_lo:[0,0,1] neg_hi:[0,0,1]
	global_store_dwordx4 v[48:49], v[68:71], off
	v_mov_b32_e32 v49, s5
	v_or_b32_e32 v48, s4, v116
	v_and_or_b32 v75, v72, s37, v75
	v_and_or_b32 v74, v73, s37, v74
	v_and_or_b32 v73, v109, s37, v117
	v_and_or_b32 v72, v107, s37, v115
	v_bfe_u32 v107, v79, 16, 1
	v_bfe_u32 v109, v78, 16, 1
	v_lshlrev_b64 v[48:49], 11, v[48:49]
	v_add3_u32 v78, v78, v109, s68
	v_add3_u32 v79, v79, v107, s68
	v_bfe_u32 v107, v126, 16, 1
	v_bfe_u32 v109, v127, 16, 1
	v_lshl_add_u64 v[48:49], v[122:123], 0, v[48:49]
	v_add3_u32 v109, v127, v109, s68
	v_add3_u32 v107, v126, v107, s68
	global_store_dwordx4 v[48:49], v[72:75], off
	v_mov_b32_e32 v49, s5
	v_or_b32_e32 v48, s4, v118
	v_lshrrev_b32_e32 v107, 16, v107
	v_lshrrev_b32_e32 v109, 16, v109
	v_lshrrev_b32_e32 v111, 16, v111
	v_lshrrev_b32_e32 v113, 16, v113
	v_lshlrev_b64 v[48:49], 11, v[48:49]
	v_and_or_b32 v79, v79, s37, v113
	v_and_or_b32 v78, v78, s37, v111
	v_and_or_b32 v77, v77, s37, v109
	v_and_or_b32 v76, v76, s37, v107
	v_lshl_add_u64 v[48:49], v[122:123], 0, v[48:49]
	global_store_dwordx4 v[48:49], v[76:79], off
	s_waitcnt lgkmcnt(0)
	s_and_b64 vcc, exec, s[0:1]
	s_mov_b32 s22, s15
	s_cbranch_vccz .LBB0_500

; #define lane (hw_lane())
; __device__ __forceinline__ void sgu_item(LAS unsigned char* wl, const bf16* proj, bf16* ymix, const float* vstat, const float* sgu_g, const bf16* Wm, const float* sgu_b, int chunk, int h, int lane) {
;     ...
;     for (int hh = 0; hh < 2; ++hh) { const f32x4* sp = (const f32x4*)(vstat + (R0 + lane + 64 * hh) * 16);
;         const f32x4 a = sp[0], b = sp[1], c = sp[2], d = sp[3];
;         const float s1 = ((a[0] + a[2]) + (b[0] + b[2])) + ((c[0] + c[2]) + (d[0] + d[2])), s2 = ((a[1] + a[3]) + (b[1] + b[3])) + ((c[1] + c[3]) + (d[1] + d[3]));
;         const float mean = s1 * (1.0f / 512.0f), var = fmaxf(s2 * (1.0f / 512.0f) - mean * mean, 0.f);
;         st[lane + 64 * hh] = (f32x2){mean, __builtin_amdgcn_rsqf(var + EPS)}; }
;     bf16x8 wmf[20];
;     { const bf16* wm = Wm + (size_t)(h * 128 + r) * 128 + q * 8; int f = 0;
; #pragma unroll
;       for (int ks = 0; ks < 4; ++ks)
; #pragma unroll
;         for (int tb = 2 * ks; tb < 8; ++tb) wmf[f++] = *(const bf16x8*)(wm + (size_t)(16 * tb) * 128 + ks * 32); }
;     float bias[8];
; #pragma unroll
;     for (int tb = 0; tb < 8; ++tb) bias[tb] = sgu_b[h * 128 + 16 * tb + r];
.LBB0_510:
	s_ashr_i32 s0, s5, 2
	s_ashr_i32 s1, s0, 31
	s_lshl_b64 s[8:9], s[0:1], 7
	v_mov_b32_e32 v1, s9
	v_or_b32_e32 v0, s8, v140
	v_lshlrev_b64 v[0:1], 6, v[0:1]
	v_lshl_add_u64 v[12:13], s[18:19], 0, v[0:1]
	global_load_dwordx4 v[0:3], v[12:13], off
	global_load_dwordx4 v[4:7], v[12:13], off offset:16
	global_load_dwordx4 v[8:11], v[12:13], off offset:32
	s_nop 0
	global_load_dwordx4 v[12:15], v[12:13], off offset:48
	s_mov_b32 s10, 0x3b000000
	v_mov_b32_e32 v17, s9
	v_or_b32_e32 v16, s8, v142
	s_lshl_b32 s6, s5, 7
	s_and_b32 s6, s6, 0x180
	s_lshl_b64 s[8:9], s[0:1], 18
	s_mov_b64 s[20:21], 0
	s_waitcnt vmcnt(0) lgkmcnt(0)
	v_pk_add_f32 v[0:1], v[0:1], v[2:3]
	v_pk_add_f32 v[2:3], v[4:5], v[6:7]
	v_pk_add_f32 v[4:5], v[8:9], v[10:11]
	v_pk_add_f32 v[6:7], v[12:13], v[14:15]
	v_pk_add_f32 v[0:1], v[0:1], v[2:3]
	v_pk_add_f32 v[2:3], v[4:5], v[6:7]
	s_nop 0
	v_pk_add_f32 v[0:1], v[0:1], v[2:3]
	v_lshlrev_b64 v[2:3], 6, v[16:17]
	v_pk_mul_f32 v[0:1], v[0:1], s[10:11] op_sel_hi:[1,0]
	v_lshl_add_u64 v[12:13], s[18:19], 0, v[2:3]
	v_fma_f32 v1, -v0, v0, v1
	v_max_f32_e32 v1, 0, v1
	v_add_f32_e32 v1, 0x358637bd, v1
	v_rsq_f32_e32 v1, v1
	v_or_b32_e32 v16, s6, v143
	v_lshlrev_b32_e32 v192, 8, v16
	v_lshlrev_b32_e32 v18, 2, v16
	ds_write_b64 v141, v[0:1] offset:10240
	global_load_dwordx4 v[0:3], v[12:13], off
	global_load_dwordx4 v[4:7], v[12:13], off offset:16
	global_load_dwordx4 v[8:11], v[12:13], off offset:32
	s_nop 0
	global_load_dwordx4 v[12:15], v[12:13], off offset:48
	v_lshl_add_u64 v[16:17], v[144:145], 0, v[192:193]
	s_movk_i32 s6, 0x1000
	global_load_dword v162, v18, s[14:15]
	global_load_dword v164, v18, s[14:15] offset:64
	global_load_dword v166, v18, s[14:15] offset:128
	global_load_dword v168, v18, s[14:15] offset:192
	global_load_dword v170, v18, s[14:15] offset:256
	global_load_dword v172, v18, s[14:15] offset:320
	global_load_dword v174, v18, s[14:15] offset:384
	global_load_dword v176, v18, s[14:15] offset:448
	v_add_co_u32_e32 v18, vcc, s6, v16
	s_movk_i32 s6, 0x2000
	s_nop 0
	v_addc_co_u32_e32 v19, vcc, 0, v17, vcc
	v_add_co_u32_e32 v20, vcc, s6, v16
	s_movk_i32 s6, 0x3000
	s_nop 0
	v_addc_co_u32_e32 v21, vcc, 0, v17, vcc
	v_add_co_u32_e32 v22, vcc, s6, v16
	s_movk_i32 s6, 0x4000
	s_nop 0
	v_addc_co_u32_e32 v23, vcc, 0, v17, vcc
	v_add_co_u32_e32 v52, vcc, s6, v16
	s_movk_i32 s6, 0x5000
	s_nop 0
	v_addc_co_u32_e32 v53, vcc, 0, v17, vcc
	v_add_co_u32_e32 v60, vcc, s6, v16
	s_movk_i32 s6, 0x6000
	s_nop 0
	v_addc_co_u32_e32 v61, vcc, 0, v17, vcc
	v_add_co_u32_e32 v68, vcc, s6, v16
	s_movk_i32 s6, 0x7000
	s_nop 0
	v_addc_co_u32_e32 v69, vcc, 0, v17, vcc
	v_add_co_u32_e32 v76, vcc, s6, v16
	s_lshl_b32 s6, s4, 1
	s_nop 0
	v_addc_co_u32_e32 v77, vcc, 0, v17, vcc
	s_waitcnt vmcnt(0)
	v_mov_b32_e32 v163, v162
	s_waitcnt lgkmcnt(0)
	v_pk_add_f32 v[0:1], v[0:1], v[2:3]
	v_pk_add_f32 v[2:3], v[4:5], v[6:7]
	v_pk_add_f32 v[4:5], v[8:9], v[10:11]
	v_pk_add_f32 v[6:7], v[12:13], v[14:15]
	v_pk_add_f32 v[0:1], v[0:1], v[2:3]
	v_pk_add_f32 v[2:3], v[4:5], v[6:7]
	v_mov_b32_e32 v165, v164
	v_pk_add_f32 v[0:1], v[0:1], v[2:3]
	v_mov_b32_e32 v167, v166
	v_pk_mul_f32 v[0:1], v[0:1], s[10:11] op_sel_hi:[1,0]
	s_and_b32 s10, s6, 0x300
	v_fma_f32 v1, -v0, v0, v1
	v_max_f32_e32 v1, 0, v1
	v_add_f32_e32 v1, 0x358637bd, v1
	v_rsq_f32_e32 v1, v1
	s_lshl_b32 s6, s4, 2
	s_and_b32 s86, s6, 0x600
	s_ashr_i32 s6, s5, 8
	ds_write_b64 v141, v[0:1] offset:10752
	global_load_dwordx4 v[0:3], v[16:17], off
	global_load_dwordx4 v[4:7], v[18:19], off
	global_load_dwordx4 v[8:11], v[20:21], off
	global_load_dwordx4 v[12:15], v[20:21], off offset:64
	s_nop 0
	global_load_dwordx4 v[16:19], v[22:23], off
	s_nop 0
	global_load_dwordx4 v[20:23], v[22:23], off offset:64
	s_nop 0
	global_load_dwordx4 v[24:27], v[52:53], off
	global_load_dwordx4 v[28:31], v[52:53], off offset:64
	global_load_dwordx4 v[32:35], v[68:69], off
	global_load_dwordx4 v[36:39], v[68:69], off offset:64
	global_load_dwordx4 v[40:43], v[76:77], off
	global_load_dwordx4 v[44:47], v[76:77], off offset:64
	global_load_dwordx4 v[48:51], v[60:61], off
	s_nop 0
	global_load_dwordx4 v[52:55], v[52:53], off offset:128
	s_nop 0
	global_load_dwordx4 v[56:59], v[60:61], off offset:64
	s_nop 0
	global_load_dwordx4 v[60:63], v[60:61], off offset:128
	s_nop 0
	global_load_dwordx4 v[64:67], v[68:69], off offset:128
	s_nop 0
	global_load_dwordx4 v[68:71], v[68:69], off offset:192
	s_nop 0
	global_load_dwordx4 v[72:75], v[76:77], off offset:128
	s_nop 0
	global_load_dwordx4 v[76:79], v[76:77], off offset:192
	s_mul_hi_i32 s11, s6, 0x1400000
	s_mul_i32 s12, s6, 0x1400000
	s_mul_hi_i32 s13, s6, 0x1c00000
	s_mul_i32 s6, s6, 0x1c00000
	s_add_u32 s1, s6, s8
	s_addc_u32 s9, s13, s9
	s_or_b32 s8, s1, s10
	s_mul_hi_i32 s1, s0, 0x60000
	s_mul_i32 s0, s0, 0x60000
	s_waitcnt lgkmcnt(0)
	s_add_u32 s0, s12, s0
	s_addc_u32 s1, s11, s1
	s_or_b32 s0, s0, s10
	v_lshl_add_u64 v[178:179], v[160:161], 0, s[86:87]
	v_mov_b32_e32 v169, v168
	v_mov_b32_e32 v171, v170
	v_mov_b32_e32 v173, v172
	v_mov_b32_e32 v175, v174
	v_mov_b32_e32 v177, v176
	v_lshl_add_u64 v[180:181], v[146:147], 0, s[8:9]
	v_lshl_add_u64 v[182:183], v[148:149], 0, s[8:9]
	v_lshl_add_u64 v[184:185], v[150:151], 0, s[8:9]
	v_lshl_add_u64 v[186:187], v[152:153], 0, s[0:1]
	v_lshl_add_u64 v[188:189], v[154:155], 0, s[0:1]
	v_lshl_add_u64 v[190:191], v[156:157], 0, s[0:1]
	v_lshl_add_u64 v[198:199], v[158:159], 0, s[0:1]
; #define LAS __attribute__((address_space(3)))
; __device__ __forceinline__ unsigned pk2(float lo, float hi) { return f2bf(lo) | (f2bf(hi) << 16); }
; __device__ __forceinline__ float bflo(unsigned w) { return __uint_as_float(w << 16); }
; __device__ __forceinline__ float bfhi(unsigned w) { return __uint_as_float(w & 0xffff0000u); }
; __device__ __forceinline__ void sgu_item(LAS unsigned char* wl, const bf16* proj, bf16* ymix, const float* vstat, const float* sgu_g, const bf16* Wm, const float* sgu_b, int chunk, int h, int lane) {
;     ...
;     for (int dq = 0; dq < 4; ++dq) {
;         const int colv = h * 128 + dq * 32;
;         v4u raw[8];
; #pragma unroll
;         for (int i = 0; i < 8; ++i) raw[i] = __builtin_nontemporal_load((const v4u*)(proj + (R0 + rsub + 16 * i) * DIN + 1024 + colv + c16 * 8));
;         const f32x4 g0 = *(const f32x4*)(sgu_g + colv + c16 * 8), g1 = *(const f32x4*)(sgu_g + colv + c16 * 8 + 4);
; #pragma unroll
;         for (int i = 0; i < 8; ++i) { const int s = rsub + 16 * i; const f32x2 ms = st[s]; const v4u w = raw[i];
;             v2u lo, hi; lo.x = pk2((bflo(w.x) - ms.x) * ms.y * g0[0], (bfhi(w.x) - ms.x) * ms.y * g0[1]); lo.y = pk2((bflo(w.y) - ms.x) * ms.y * g0[2], (bfhi(w.y) - ms.x) * ms.y * g0[3]);
;             hi.x = pk2((bflo(w.z) - ms.x) * ms.y * g1[0], (bfhi(w.z) - ms.x) * ms.y * g1[1]); hi.y = pk2((bflo(w.w) - ms.x) * ms.y * g1[2], (bfhi(w.w) - ms.x) * ms.y * g1[3]);
;             *(LAS v2u*)(wl + s * VP2 + (4 * c16) * 2) = lo; *(LAS v2u*)(wl + s * VP2 + (16 + 4 * c16) * 2) = hi; }
.LBB0_511:
	v_lshl_add_u64 v[80:81], v[198:199], 0, s[20:21]
	v_add_co_u32_e32 v82, vcc, 0xf100000, v80
	s_mov_b32 s0, 0xf100000
	s_nop 0
	v_addc_co_u32_e32 v83, vcc, 0, v81, vcc
	global_load_dwordx4 v[118:121], v[82:83], off offset:2048 nt
	v_add_co_u32_e32 v82, vcc, 0xf10c000, v80
	s_waitcnt vmcnt(0) lgkmcnt(0)
	v_lshlrev_b32_e32 v117, 16, v119
	v_addc_co_u32_e32 v83, vcc, 0, v81, vcc
	global_load_dwordx4 v[112:115], v[82:83], off offset:2048 nt
	v_add_co_u32_e32 v82, vcc, 0xf118000, v80
	v_lshlrev_b32_e32 v116, 16, v118
	s_nop 0
	v_addc_co_u32_e32 v83, vcc, 0, v81, vcc
	global_load_dwordx4 v[108:111], v[82:83], off offset:2048 nt
	v_add_co_u32_e32 v82, vcc, 0xf124000, v80
	v_and_b32_e32 v119, 0xffff0000, v119
	s_nop 0
	v_addc_co_u32_e32 v83, vcc, 0, v81, vcc
	global_load_dwordx4 v[104:107], v[82:83], off offset:2048 nt
	v_add_co_u32_e32 v82, vcc, 0xf130000, v80
	v_and_b32_e32 v118, 0xffff0000, v118
	s_nop 0
	v_addc_co_u32_e32 v83, vcc, 0, v81, vcc
	global_load_dwordx4 v[100:103], v[82:83], off offset:2048 nt
	v_add_co_u32_e32 v82, vcc, 0xf13c000, v80
	s_nop 1
	v_addc_co_u32_e32 v83, vcc, 0, v81, vcc
	global_load_dwordx4 v[96:99], v[82:83], off offset:2048 nt
	v_add_co_u32_e32 v82, vcc, 0xf148000, v80
	s_nop 1
	v_addc_co_u32_e32 v83, vcc, 0, v81, vcc
	v_add_co_u32_e32 v80, vcc, 0xf154000, v80
	global_load_dwordx4 v[84:87], v[82:83], off offset:2048 nt
	s_nop 0
	v_addc_co_u32_e32 v81, vcc, 0, v81, vcc
	global_load_dwordx4 v[80:83], v[80:81], off offset:2048 nt
	s_nop 0
	global_load_dwordx4 v[88:91], v[178:179], off
	global_load_dwordx4 v[92:95], v[178:179], off offset:-16
	ds_read_b64 v[122:123], v218 offset:10240
	v_lshl_add_u64 v[178:179], v[178:179], 0, s[88:89]
	s_waitcnt lgkmcnt(0)
	v_pk_add_f32 v[116:117], v[116:117], v[122:123] op_sel_hi:[1,0] neg_lo:[0,1] neg_hi:[0,1]
	s_nop 0
	v_pk_mul_f32 v[124:125], v[122:123], v[116:117] op_sel:[1,0]
	v_pk_add_f32 v[118:119], v[118:119], v[122:123] op_sel_hi:[1,0] neg_lo:[0,1] neg_hi:[0,1]
	s_waitcnt vmcnt(0)
	v_mov_b32_e32 v116, v92
	v_mov_b32_e32 v117, v94
	v_pk_mul_f32 v[124:125], v[116:117], v[124:125]
	v_pk_mul_f32 v[118:119], v[122:123], v[118:119] op_sel:[1,0]
	v_mov_b32_e32 v94, v93
	v_pk_mul_f32 v[92:93], v[94:95], v[118:119]
	v_and_b32_sdwa v118, v125, v245 dst_sel:DWORD dst_unused:UNUSED_PAD src0_sel:WORD_1 src1_sel:DWORD
	v_and_b32_sdwa v119, v124, v245 dst_sel:DWORD dst_unused:UNUSED_PAD src0_sel:WORD_1 src1_sel:DWORD
	v_add3_u32 v124, v124, v119, s68
	v_add3_u32 v118, v125, v118, s68
	v_and_b32_sdwa v119, v93, v245 dst_sel:DWORD dst_unused:UNUSED_PAD src0_sel:WORD_1 src1_sel:DWORD
	v_and_b32_sdwa v125, v92, v245 dst_sel:DWORD dst_unused:UNUSED_PAD src0_sel:WORD_1 src1_sel:DWORD
	v_add3_u32 v93, v93, v119, s68
	v_add3_u32 v92, v92, v125, s68
	v_and_b32_e32 v93, 0xffff0000, v93
	v_and_b32_e32 v92, 0xffff0000, v92
	v_or_b32_sdwa v119, v93, v118 dst_sel:DWORD dst_unused:UNUSED_PAD src0_sel:DWORD src1_sel:WORD_1
	v_or_b32_sdwa v118, v92, v124 dst_sel:DWORD dst_unused:UNUSED_PAD src0_sel:DWORD src1_sel:WORD_1
	v_lshlrev_b32_e32 v93, 16, v121
	v_lshlrev_b32_e32 v92, 16, v120
	v_and_b32_e32 v121, 0xffff0000, v121
	v_and_b32_e32 v120, 0xffff0000, v120
	v_pk_add_f32 v[92:93], v[92:93], v[122:123] op_sel_hi:[1,0] neg_lo:[0,1] neg_hi:[0,1]
	v_pk_add_f32 v[120:121], v[120:121], v[122:123] op_sel_hi:[1,0] neg_lo:[0,1] neg_hi:[0,1]
	v_pk_mul_f32 v[124:125], v[122:123], v[92:93] op_sel:[1,0]
	v_mov_b32_e32 v93, v90
	v_pk_mul_f32 v[120:121], v[122:123], v[120:121] op_sel:[1,0]
	v_mov_b32_e32 v90, v89
	v_mov_b32_e32 v92, v88
	v_pk_mul_f32 v[88:89], v[90:91], v[120:121]
	v_pk_mul_f32 v[124:125], v[92:93], v[124:125]
	v_and_b32_sdwa v122, v89, v245 dst_sel:DWORD dst_unused:UNUSED_PAD src0_sel:WORD_1 src1_sel:DWORD
	v_and_b32_sdwa v123, v88, v245 dst_sel:DWORD dst_unused:UNUSED_PAD src0_sel:WORD_1 src1_sel:DWORD
	v_and_b32_sdwa v120, v125, v245 dst_sel:DWORD dst_unused:UNUSED_PAD src0_sel:WORD_1 src1_sel:DWORD
	v_and_b32_sdwa v121, v124, v245 dst_sel:DWORD dst_unused:UNUSED_PAD src0_sel:WORD_1 src1_sel:DWORD
	v_add3_u32 v89, v89, v122, s68
	v_add3_u32 v88, v88, v123, s68
	v_add3_u32 v121, v124, v121, s68
	v_add3_u32 v120, v125, v120, s68
	v_and_b32_e32 v89, 0xffff0000, v89
	v_and_b32_e32 v88, 0xffff0000, v88
	v_or_b32_sdwa v89, v89, v120 dst_sel:DWORD dst_unused:UNUSED_PAD src0_sel:DWORD src1_sel:WORD_1
	v_or_b32_sdwa v88, v88, v121 dst_sel:DWORD dst_unused:UNUSED_PAD src0_sel:DWORD src1_sel:WORD_1
	ds_write2_b64 v219, v[118:119], v[88:89] offset1:4
	ds_read_b64 v[88:89], v218 offset:10368
	v_lshlrev_b32_e32 v119, 16, v113
	v_lshlrev_b32_e32 v118, 16, v112
	v_and_b32_e32 v113, 0xffff0000, v113
	v_and_b32_e32 v112, 0xffff0000, v112
	s_waitcnt lgkmcnt(0)
; #define LAS __attribute__((address_space(3)))
; __device__ __forceinline__ unsigned pk2(float lo, float hi) { return f2bf(lo) | (f2bf(hi) << 16); }
; __device__ __forceinline__ float bflo(unsigned w) { return __uint_as_float(w << 16); }
; __device__ __forceinline__ float bfhi(unsigned w) { return __uint_as_float(w & 0xffff0000u); }
; __device__ __forceinline__ void sgu_item(LAS unsigned char* wl, const bf16* proj, bf16* ymix, const float* vstat, const float* sgu_g, const bf16* Wm, const float* sgu_b, int chunk, int h, int lane) {
;     ...
;         for (int i = 0; i < 8; ++i) { const int s = rsub + 16 * i; const f32x2 ms = st[s]; const v4u w = raw[i];
;             v2u lo, hi; lo.x = pk2((bflo(w.x) - ms.x) * ms.y * g0[0], (bfhi(w.x) - ms.x) * ms.y * g0[1]); lo.y = pk2((bflo(w.y) - ms.x) * ms.y * g0[2], (bfhi(w.y) - ms.x) * ms.y * g0[3]);
;             hi.x = pk2((bflo(w.z) - ms.x) * ms.y * g1[0], (bfhi(w.z) - ms.x) * ms.y * g1[1]); hi.y = pk2((bflo(w.w) - ms.x) * ms.y * g1[2], (bfhi(w.w) - ms.x) * ms.y * g1[3]);
;             *(LAS v2u*)(wl + s * VP2 + (4 * c16) * 2) = lo; *(LAS v2u*)(wl + s * VP2 + (16 + 4 * c16) * 2) = hi; }
	v_pk_add_f32 v[118:119], v[118:119], v[88:89] op_sel_hi:[1,0] neg_lo:[0,1] neg_hi:[0,1]
	v_pk_add_f32 v[112:113], v[112:113], v[88:89] op_sel_hi:[1,0] neg_lo:[0,1] neg_hi:[0,1]
	v_pk_mul_f32 v[118:119], v[88:89], v[118:119] op_sel:[1,0]
	v_pk_mul_f32 v[112:113], v[88:89], v[112:113] op_sel:[1,0]
	v_pk_mul_f32 v[118:119], v[116:117], v[118:119]
	v_pk_mul_f32 v[112:113], v[94:95], v[112:113]
	v_and_b32_sdwa v120, v119, v245 dst_sel:DWORD dst_unused:UNUSED_PAD src0_sel:WORD_1 src1_sel:DWORD
	v_and_b32_sdwa v121, v118, v245 dst_sel:DWORD dst_unused:UNUSED_PAD src0_sel:WORD_1 src1_sel:DWORD
	v_add3_u32 v118, v118, v121, s68
	v_add3_u32 v119, v119, v120, s68
	v_and_b32_sdwa v120, v113, v245 dst_sel:DWORD dst_unused:UNUSED_PAD src0_sel:WORD_1 src1_sel:DWORD
	v_and_b32_sdwa v121, v112, v245 dst_sel:DWORD dst_unused:UNUSED_PAD src0_sel:WORD_1 src1_sel:DWORD
	v_add3_u32 v113, v113, v120, s68
	v_add3_u32 v112, v112, v121, s68
	v_and_b32_e32 v113, 0xffff0000, v113
	v_and_b32_e32 v112, 0xffff0000, v112
	v_or_b32_sdwa v113, v113, v119 dst_sel:DWORD dst_unused:UNUSED_PAD src0_sel:DWORD src1_sel:WORD_1
	v_or_b32_sdwa v112, v112, v118 dst_sel:DWORD dst_unused:UNUSED_PAD src0_sel:DWORD src1_sel:WORD_1
	v_lshlrev_b32_e32 v119, 16, v115
	v_lshlrev_b32_e32 v118, 16, v114
	v_pk_add_f32 v[118:119], v[118:119], v[88:89] op_sel_hi:[1,0] neg_lo:[0,1] neg_hi:[0,1]
	v_and_b32_e32 v115, 0xffff0000, v115
	v_and_b32_e32 v114, 0xffff0000, v114
	v_pk_mul_f32 v[118:119], v[88:89], v[118:119] op_sel:[1,0]
	v_pk_add_f32 v[114:115], v[114:115], v[88:89] op_sel_hi:[1,0] neg_lo:[0,1] neg_hi:[0,1]
	v_pk_mul_f32 v[118:119], v[92:93], v[118:119]
	v_pk_mul_f32 v[88:89], v[88:89], v[114:115] op_sel:[1,0]
	v_and_b32_sdwa v114, v119, v245 dst_sel:DWORD dst_unused:UNUSED_PAD src0_sel:WORD_1 src1_sel:DWORD
	v_pk_mul_f32 v[88:89], v[90:91], v[88:89]
	v_and_b32_sdwa v115, v118, v245 dst_sel:DWORD dst_unused:UNUSED_PAD src0_sel:WORD_1 src1_sel:DWORD
	v_add3_u32 v115, v118, v115, s68
	v_add3_u32 v114, v119, v114, s68
	v_and_b32_sdwa v118, v89, v245 dst_sel:DWORD dst_unused:UNUSED_PAD src0_sel:WORD_1 src1_sel:DWORD
	v_and_b32_sdwa v119, v88, v245 dst_sel:DWORD dst_unused:UNUSED_PAD src0_sel:WORD_1 src1_sel:DWORD
	v_add3_u32 v89, v89, v118, s68
	v_add3_u32 v88, v88, v119, s68
	v_and_b32_e32 v89, 0xffff0000, v89
	v_and_b32_e32 v88, 0xffff0000, v88
	v_or_b32_sdwa v89, v89, v114 dst_sel:DWORD dst_unused:UNUSED_PAD src0_sel:DWORD src1_sel:WORD_1
	v_or_b32_sdwa v88, v88, v115 dst_sel:DWORD dst_unused:UNUSED_PAD src0_sel:DWORD src1_sel:WORD_1
	ds_write2_b64 v219, v[112:113], v[88:89] offset0:160 offset1:164
	ds_read_b64 v[112:113], v218 offset:10496
	v_lshlrev_b32_e32 v89, 16, v109
	v_lshlrev_b32_e32 v88, 16, v108
	v_and_b32_e32 v109, 0xffff0000, v109
	v_and_b32_e32 v108, 0xffff0000, v108
	s_waitcnt lgkmcnt(0)
	v_pk_add_f32 v[88:89], v[88:89], v[112:113] op_sel_hi:[1,0] neg_lo:[0,1] neg_hi:[0,1]
	v_pk_add_f32 v[108:109], v[108:109], v[112:113] op_sel_hi:[1,0] neg_lo:[0,1] neg_hi:[0,1]
	v_pk_mul_f32 v[88:89], v[112:113], v[88:89] op_sel:[1,0]
	v_pk_mul_f32 v[108:109], v[112:113], v[108:109] op_sel:[1,0]
	v_pk_mul_f32 v[88:89], v[116:117], v[88:89]
	v_pk_mul_f32 v[108:109], v[94:95], v[108:109]
	v_and_b32_sdwa v114, v89, v245 dst_sel:DWORD dst_unused:UNUSED_PAD src0_sel:WORD_1 src1_sel:DWORD
	v_and_b32_sdwa v115, v88, v245 dst_sel:DWORD dst_unused:UNUSED_PAD src0_sel:WORD_1 src1_sel:DWORD
	v_add3_u32 v88, v88, v115, s68
	v_add3_u32 v89, v89, v114, s68
	v_and_b32_sdwa v114, v109, v245 dst_sel:DWORD dst_unused:UNUSED_PAD src0_sel:WORD_1 src1_sel:DWORD
	v_and_b32_sdwa v115, v108, v245 dst_sel:DWORD dst_unused:UNUSED_PAD src0_sel:WORD_1 src1_sel:DWORD
	v_add3_u32 v109, v109, v114, s68
	v_add3_u32 v108, v108, v115, s68
	v_and_b32_e32 v109, 0xffff0000, v109
	v_and_b32_e32 v108, 0xffff0000, v108
	v_or_b32_sdwa v89, v109, v89 dst_sel:DWORD dst_unused:UNUSED_PAD src0_sel:DWORD src1_sel:WORD_1
	v_or_b32_sdwa v88, v108, v88 dst_sel:DWORD dst_unused:UNUSED_PAD src0_sel:DWORD src1_sel:WORD_1
	v_lshlrev_b32_e32 v109, 16, v111
	v_lshlrev_b32_e32 v108, 16, v110
	v_pk_add_f32 v[108:109], v[108:109], v[112:113] op_sel_hi:[1,0] neg_lo:[0,1] neg_hi:[0,1]
	v_and_b32_e32 v111, 0xffff0000, v111
	v_and_b32_e32 v110, 0xffff0000, v110
	v_pk_mul_f32 v[108:109], v[112:113], v[108:109] op_sel:[1,0]
	v_pk_add_f32 v[110:111], v[110:111], v[112:113] op_sel_hi:[1,0] neg_lo:[0,1] neg_hi:[0,1]
	v_pk_mul_f32 v[108:109], v[92:93], v[108:109]
	v_pk_mul_f32 v[110:111], v[112:113], v[110:111] op_sel:[1,0]
	v_and_b32_sdwa v112, v109, v245 dst_sel:DWORD dst_unused:UNUSED_PAD src0_sel:WORD_1 src1_sel:DWORD
	v_pk_mul_f32 v[110:111], v[90:91], v[110:111]
	v_and_b32_sdwa v113, v108, v245 dst_sel:DWORD dst_unused:UNUSED_PAD src0_sel:WORD_1 src1_sel:DWORD
	v_add3_u32 v108, v108, v113, s68
	v_add3_u32 v109, v109, v112, s68
	v_and_b32_sdwa v112, v111, v245 dst_sel:DWORD dst_unused:UNUSED_PAD src0_sel:WORD_1 src1_sel:DWORD
	v_and_b32_sdwa v113, v110, v245 dst_sel:DWORD dst_unused:UNUSED_PAD src0_sel:WORD_1 src1_sel:DWORD
	v_add3_u32 v111, v111, v112, s68
	v_add3_u32 v110, v110, v113, s68
	v_and_b32_e32 v111, 0xffff0000, v111
	v_and_b32_e32 v110, 0xffff0000, v110
	v_or_b32_sdwa v109, v111, v109 dst_sel:DWORD dst_unused:UNUSED_PAD src0_sel:DWORD src1_sel:WORD_1
	v_or_b32_sdwa v108, v110, v108 dst_sel:DWORD dst_unused:UNUSED_PAD src0_sel:DWORD src1_sel:WORD_1
	v_add_u32_e32 v110, 0x800, v219
	ds_write2_b64 v110, v[88:89], v[108:109] offset0:64 offset1:68
	ds_read_b64 v[88:89], v218 offset:10624
	v_lshlrev_b32_e32 v109, 16, v105
	v_lshlrev_b32_e32 v108, 16, v104
	v_and_b32_e32 v105, 0xffff0000, v105
	v_and_b32_e32 v104, 0xffff0000, v104
	s_waitcnt lgkmcnt(0)
; #define LAS __attribute__((address_space(3)))
; __device__ __forceinline__ unsigned pk2(float lo, float hi) { return f2bf(lo) | (f2bf(hi) << 16); }
; __device__ __forceinline__ float bflo(unsigned w) { return __uint_as_float(w << 16); }
; __device__ __forceinline__ float bfhi(unsigned w) { return __uint_as_float(w & 0xffff0000u); }
; __device__ __forceinline__ void sgu_item(LAS unsigned char* wl, const bf16* proj, bf16* ymix, const float* vstat, const float* sgu_g, const bf16* Wm, const float* sgu_b, int chunk, int h, int lane) {
;     ...
;         for (int i = 0; i < 8; ++i) { const int s = rsub + 16 * i; const f32x2 ms = st[s]; const v4u w = raw[i];
;             v2u lo, hi; lo.x = pk2((bflo(w.x) - ms.x) * ms.y * g0[0], (bfhi(w.x) - ms.x) * ms.y * g0[1]); lo.y = pk2((bflo(w.y) - ms.x) * ms.y * g0[2], (bfhi(w.y) - ms.x) * ms.y * g0[3]);
;             hi.x = pk2((bflo(w.z) - ms.x) * ms.y * g1[0], (bfhi(w.z) - ms.x) * ms.y * g1[1]); hi.y = pk2((bflo(w.w) - ms.x) * ms.y * g1[2], (bfhi(w.w) - ms.x) * ms.y * g1[3]);
;             *(LAS v2u*)(wl + s * VP2 + (4 * c16) * 2) = lo; *(LAS v2u*)(wl + s * VP2 + (16 + 4 * c16) * 2) = hi; }
	v_pk_add_f32 v[108:109], v[108:109], v[88:89] op_sel_hi:[1,0] neg_lo:[0,1] neg_hi:[0,1]
	v_pk_add_f32 v[104:105], v[104:105], v[88:89] op_sel_hi:[1,0] neg_lo:[0,1] neg_hi:[0,1]
	v_pk_mul_f32 v[108:109], v[88:89], v[108:109] op_sel:[1,0]
	v_pk_mul_f32 v[104:105], v[88:89], v[104:105] op_sel:[1,0]
	v_pk_mul_f32 v[108:109], v[116:117], v[108:109]
	v_pk_mul_f32 v[104:105], v[94:95], v[104:105]
	v_and_b32_sdwa v111, v109, v245 dst_sel:DWORD dst_unused:UNUSED_PAD src0_sel:WORD_1 src1_sel:DWORD
	v_and_b32_sdwa v112, v108, v245 dst_sel:DWORD dst_unused:UNUSED_PAD src0_sel:WORD_1 src1_sel:DWORD
	v_add3_u32 v108, v108, v112, s68
	v_add3_u32 v109, v109, v111, s68
	v_and_b32_sdwa v111, v105, v245 dst_sel:DWORD dst_unused:UNUSED_PAD src0_sel:WORD_1 src1_sel:DWORD
	v_and_b32_sdwa v112, v104, v245 dst_sel:DWORD dst_unused:UNUSED_PAD src0_sel:WORD_1 src1_sel:DWORD
	v_add3_u32 v105, v105, v111, s68
	v_add3_u32 v104, v104, v112, s68
	v_and_b32_e32 v105, 0xffff0000, v105
	v_and_b32_e32 v104, 0xffff0000, v104
	v_or_b32_sdwa v105, v105, v109 dst_sel:DWORD dst_unused:UNUSED_PAD src0_sel:DWORD src1_sel:WORD_1
	v_or_b32_sdwa v104, v104, v108 dst_sel:DWORD dst_unused:UNUSED_PAD src0_sel:DWORD src1_sel:WORD_1
	v_lshlrev_b32_e32 v109, 16, v107
	v_lshlrev_b32_e32 v108, 16, v106
	v_pk_add_f32 v[108:109], v[108:109], v[88:89] op_sel_hi:[1,0] neg_lo:[0,1] neg_hi:[0,1]
	v_and_b32_e32 v107, 0xffff0000, v107
	v_and_b32_e32 v106, 0xffff0000, v106
	v_pk_mul_f32 v[108:109], v[88:89], v[108:109] op_sel:[1,0]
	v_pk_add_f32 v[106:107], v[106:107], v[88:89] op_sel_hi:[1,0] neg_lo:[0,1] neg_hi:[0,1]
	v_pk_mul_f32 v[108:109], v[92:93], v[108:109]
	v_pk_mul_f32 v[88:89], v[88:89], v[106:107] op_sel:[1,0]
	v_and_b32_sdwa v106, v109, v245 dst_sel:DWORD dst_unused:UNUSED_PAD src0_sel:WORD_1 src1_sel:DWORD
	v_pk_mul_f32 v[88:89], v[90:91], v[88:89]
	v_and_b32_sdwa v107, v108, v245 dst_sel:DWORD dst_unused:UNUSED_PAD src0_sel:WORD_1 src1_sel:DWORD
	v_add3_u32 v107, v108, v107, s68
	v_add3_u32 v106, v109, v106, s68
	v_and_b32_sdwa v108, v89, v245 dst_sel:DWORD dst_unused:UNUSED_PAD src0_sel:WORD_1 src1_sel:DWORD
	v_and_b32_sdwa v109, v88, v245 dst_sel:DWORD dst_unused:UNUSED_PAD src0_sel:WORD_1 src1_sel:DWORD
	v_add3_u32 v89, v89, v108, s68
	v_add3_u32 v88, v88, v109, s68
	v_and_b32_e32 v89, 0xffff0000, v89
	v_and_b32_e32 v88, 0xffff0000, v88
	v_or_b32_sdwa v89, v89, v106 dst_sel:DWORD dst_unused:UNUSED_PAD src0_sel:DWORD src1_sel:WORD_1
	v_or_b32_sdwa v88, v88, v107 dst_sel:DWORD dst_unused:UNUSED_PAD src0_sel:DWORD src1_sel:WORD_1
	ds_write2_b64 v110, v[104:105], v[88:89] offset0:224 offset1:228
	ds_read_b64 v[104:105], v218 offset:10752
	v_lshlrev_b32_e32 v89, 16, v101
	v_lshlrev_b32_e32 v88, 16, v100
	v_and_b32_e32 v101, 0xffff0000, v101
	v_and_b32_e32 v100, 0xffff0000, v100
	s_waitcnt lgkmcnt(0)
	v_pk_add_f32 v[88:89], v[88:89], v[104:105] op_sel_hi:[1,0] neg_lo:[0,1] neg_hi:[0,1]
	v_pk_add_f32 v[100:101], v[100:101], v[104:105] op_sel_hi:[1,0] neg_lo:[0,1] neg_hi:[0,1]
	v_pk_mul_f32 v[88:89], v[104:105], v[88:89] op_sel:[1,0]
	v_pk_mul_f32 v[100:101], v[104:105], v[100:101] op_sel:[1,0]
	v_pk_mul_f32 v[88:89], v[116:117], v[88:89]
	v_pk_mul_f32 v[100:101], v[94:95], v[100:101]
	v_and_b32_sdwa v106, v89, v245 dst_sel:DWORD dst_unused:UNUSED_PAD src0_sel:WORD_1 src1_sel:DWORD
	v_and_b32_sdwa v107, v88, v245 dst_sel:DWORD dst_unused:UNUSED_PAD src0_sel:WORD_1 src1_sel:DWORD
	v_add3_u32 v88, v88, v107, s68
	v_add3_u32 v89, v89, v106, s68
	v_and_b32_sdwa v106, v101, v245 dst_sel:DWORD dst_unused:UNUSED_PAD src0_sel:WORD_1 src1_sel:DWORD
	v_and_b32_sdwa v107, v100, v245 dst_sel:DWORD dst_unused:UNUSED_PAD src0_sel:WORD_1 src1_sel:DWORD
	v_add3_u32 v101, v101, v106, s68
	v_add3_u32 v100, v100, v107, s68
	v_and_b32_e32 v101, 0xffff0000, v101
	v_and_b32_e32 v100, 0xffff0000, v100
	v_or_b32_sdwa v89, v101, v89 dst_sel:DWORD dst_unused:UNUSED_PAD src0_sel:DWORD src1_sel:WORD_1
	v_or_b32_sdwa v88, v100, v88 dst_sel:DWORD dst_unused:UNUSED_PAD src0_sel:DWORD src1_sel:WORD_1
	v_lshlrev_b32_e32 v101, 16, v103
	v_lshlrev_b32_e32 v100, 16, v102
	v_pk_add_f32 v[100:101], v[100:101], v[104:105] op_sel_hi:[1,0] neg_lo:[0,1] neg_hi:[0,1]
	v_and_b32_e32 v103, 0xffff0000, v103
	v_and_b32_e32 v102, 0xffff0000, v102
	v_pk_mul_f32 v[100:101], v[104:105], v[100:101] op_sel:[1,0]
	v_pk_add_f32 v[102:103], v[102:103], v[104:105] op_sel_hi:[1,0] neg_lo:[0,1] neg_hi:[0,1]
	v_pk_mul_f32 v[100:101], v[92:93], v[100:101]
	v_pk_mul_f32 v[102:103], v[104:105], v[102:103] op_sel:[1,0]
	v_and_b32_sdwa v104, v101, v245 dst_sel:DWORD dst_unused:UNUSED_PAD src0_sel:WORD_1 src1_sel:DWORD
	v_pk_mul_f32 v[102:103], v[90:91], v[102:103]
	v_and_b32_sdwa v105, v100, v245 dst_sel:DWORD dst_unused:UNUSED_PAD src0_sel:WORD_1 src1_sel:DWORD
	v_add3_u32 v100, v100, v105, s68
	v_add3_u32 v101, v101, v104, s68
	v_and_b32_sdwa v104, v103, v245 dst_sel:DWORD dst_unused:UNUSED_PAD src0_sel:WORD_1 src1_sel:DWORD
	v_and_b32_sdwa v105, v102, v245 dst_sel:DWORD dst_unused:UNUSED_PAD src0_sel:WORD_1 src1_sel:DWORD
	v_add3_u32 v103, v103, v104, s68
	v_add3_u32 v102, v102, v105, s68
	v_and_b32_e32 v103, 0xffff0000, v103
	v_and_b32_e32 v102, 0xffff0000, v102
	v_or_b32_sdwa v101, v103, v101 dst_sel:DWORD dst_unused:UNUSED_PAD src0_sel:DWORD src1_sel:WORD_1
	v_or_b32_sdwa v100, v102, v100 dst_sel:DWORD dst_unused:UNUSED_PAD src0_sel:DWORD src1_sel:WORD_1
	v_add_u32_e32 v102, 0x1000, v219
	ds_write2_b64 v102, v[88:89], v[100:101] offset0:128 offset1:132
	ds_read_b64 v[88:89], v218 offset:10880
	v_lshlrev_b32_e32 v101, 16, v97
	v_lshlrev_b32_e32 v100, 16, v96
	v_and_b32_e32 v97, 0xffff0000, v97
	v_and_b32_e32 v96, 0xffff0000, v96
	s_waitcnt lgkmcnt(0)
; #define LAS __attribute__((address_space(3)))
; __device__ __forceinline__ unsigned pk2(float lo, float hi) { return f2bf(lo) | (f2bf(hi) << 16); }
; __device__ __forceinline__ float bflo(unsigned w) { return __uint_as_float(w << 16); }
; __device__ __forceinline__ float bfhi(unsigned w) { return __uint_as_float(w & 0xffff0000u); }
; __device__ __forceinline__ void sgu_item(LAS unsigned char* wl, const bf16* proj, bf16* ymix, const float* vstat, const float* sgu_g, const bf16* Wm, const float* sgu_b, int chunk, int h, int lane) {
;     ...
;         for (int i = 0; i < 8; ++i) { const int s = rsub + 16 * i; const f32x2 ms = st[s]; const v4u w = raw[i];
;             v2u lo, hi; lo.x = pk2((bflo(w.x) - ms.x) * ms.y * g0[0], (bfhi(w.x) - ms.x) * ms.y * g0[1]); lo.y = pk2((bflo(w.y) - ms.x) * ms.y * g0[2], (bfhi(w.y) - ms.x) * ms.y * g0[3]);
;             hi.x = pk2((bflo(w.z) - ms.x) * ms.y * g1[0], (bfhi(w.z) - ms.x) * ms.y * g1[1]); hi.y = pk2((bflo(w.w) - ms.x) * ms.y * g1[2], (bfhi(w.w) - ms.x) * ms.y * g1[3]);
;             *(LAS v2u*)(wl + s * VP2 + (4 * c16) * 2) = lo; *(LAS v2u*)(wl + s * VP2 + (16 + 4 * c16) * 2) = hi; }
	v_pk_add_f32 v[100:101], v[100:101], v[88:89] op_sel_hi:[1,0] neg_lo:[0,1] neg_hi:[0,1]
	v_pk_add_f32 v[96:97], v[96:97], v[88:89] op_sel_hi:[1,0] neg_lo:[0,1] neg_hi:[0,1]
	v_pk_mul_f32 v[100:101], v[88:89], v[100:101] op_sel:[1,0]
	v_pk_mul_f32 v[96:97], v[88:89], v[96:97] op_sel:[1,0]
	v_pk_mul_f32 v[100:101], v[116:117], v[100:101]
	v_pk_mul_f32 v[96:97], v[94:95], v[96:97]
	v_and_b32_sdwa v102, v101, v245 dst_sel:DWORD dst_unused:UNUSED_PAD src0_sel:WORD_1 src1_sel:DWORD
	v_and_b32_sdwa v103, v100, v245 dst_sel:DWORD dst_unused:UNUSED_PAD src0_sel:WORD_1 src1_sel:DWORD
	v_add3_u32 v100, v100, v103, s68
	v_add3_u32 v101, v101, v102, s68
	v_and_b32_sdwa v102, v97, v245 dst_sel:DWORD dst_unused:UNUSED_PAD src0_sel:WORD_1 src1_sel:DWORD
	v_and_b32_sdwa v103, v96, v245 dst_sel:DWORD dst_unused:UNUSED_PAD src0_sel:WORD_1 src1_sel:DWORD
	v_add3_u32 v97, v97, v102, s68
	v_add3_u32 v96, v96, v103, s68
	v_and_b32_e32 v97, 0xffff0000, v97
	v_and_b32_e32 v96, 0xffff0000, v96
	v_or_b32_sdwa v97, v97, v101 dst_sel:DWORD dst_unused:UNUSED_PAD src0_sel:DWORD src1_sel:WORD_1
	v_or_b32_sdwa v96, v96, v100 dst_sel:DWORD dst_unused:UNUSED_PAD src0_sel:DWORD src1_sel:WORD_1
	v_lshlrev_b32_e32 v101, 16, v99
	v_lshlrev_b32_e32 v100, 16, v98
	v_pk_add_f32 v[100:101], v[100:101], v[88:89] op_sel_hi:[1,0] neg_lo:[0,1] neg_hi:[0,1]
	v_and_b32_e32 v99, 0xffff0000, v99
	v_and_b32_e32 v98, 0xffff0000, v98
	v_pk_mul_f32 v[100:101], v[88:89], v[100:101] op_sel:[1,0]
	v_pk_add_f32 v[98:99], v[98:99], v[88:89] op_sel_hi:[1,0] neg_lo:[0,1] neg_hi:[0,1]
	v_pk_mul_f32 v[100:101], v[92:93], v[100:101]
	v_pk_mul_f32 v[88:89], v[88:89], v[98:99] op_sel:[1,0]
	v_and_b32_sdwa v98, v101, v245 dst_sel:DWORD dst_unused:UNUSED_PAD src0_sel:WORD_1 src1_sel:DWORD
	v_pk_mul_f32 v[88:89], v[90:91], v[88:89]
	v_and_b32_sdwa v99, v100, v245 dst_sel:DWORD dst_unused:UNUSED_PAD src0_sel:WORD_1 src1_sel:DWORD
	v_add3_u32 v99, v100, v99, s68
	v_add3_u32 v98, v101, v98, s68
	v_and_b32_sdwa v100, v89, v245 dst_sel:DWORD dst_unused:UNUSED_PAD src0_sel:WORD_1 src1_sel:DWORD
	v_and_b32_sdwa v101, v88, v245 dst_sel:DWORD dst_unused:UNUSED_PAD src0_sel:WORD_1 src1_sel:DWORD
	v_add3_u32 v89, v89, v100, s68
	v_add3_u32 v88, v88, v101, s68
	v_and_b32_e32 v89, 0xffff0000, v89
	v_and_b32_e32 v88, 0xffff0000, v88
	v_or_b32_sdwa v89, v89, v98 dst_sel:DWORD dst_unused:UNUSED_PAD src0_sel:DWORD src1_sel:WORD_1
	v_or_b32_sdwa v88, v88, v99 dst_sel:DWORD dst_unused:UNUSED_PAD src0_sel:DWORD src1_sel:WORD_1
	v_add_u32_e32 v98, 0x1800, v219
	ds_write2_b64 v98, v[96:97], v[88:89] offset0:32 offset1:36
	ds_read_b64 v[88:89], v218 offset:11008
	v_lshlrev_b32_e32 v97, 16, v85
	v_lshlrev_b32_e32 v96, 16, v84
	v_and_b32_e32 v85, 0xffff0000, v85
	v_and_b32_e32 v84, 0xffff0000, v84
	s_waitcnt lgkmcnt(0)
	v_pk_add_f32 v[96:97], v[96:97], v[88:89] op_sel_hi:[1,0] neg_lo:[0,1] neg_hi:[0,1]
	v_pk_add_f32 v[84:85], v[84:85], v[88:89] op_sel_hi:[1,0] neg_lo:[0,1] neg_hi:[0,1]
	v_pk_mul_f32 v[96:97], v[88:89], v[96:97] op_sel:[1,0]
	v_pk_mul_f32 v[84:85], v[88:89], v[84:85] op_sel:[1,0]
	v_pk_mul_f32 v[96:97], v[116:117], v[96:97]
	v_pk_mul_f32 v[84:85], v[94:95], v[84:85]
	v_and_b32_sdwa v99, v97, v245 dst_sel:DWORD dst_unused:UNUSED_PAD src0_sel:WORD_1 src1_sel:DWORD
	v_and_b32_sdwa v100, v96, v245 dst_sel:DWORD dst_unused:UNUSED_PAD src0_sel:WORD_1 src1_sel:DWORD
	v_add3_u32 v96, v96, v100, s68
	v_add3_u32 v97, v97, v99, s68
	v_and_b32_sdwa v99, v85, v245 dst_sel:DWORD dst_unused:UNUSED_PAD src0_sel:WORD_1 src1_sel:DWORD
	v_and_b32_sdwa v100, v84, v245 dst_sel:DWORD dst_unused:UNUSED_PAD src0_sel:WORD_1 src1_sel:DWORD
	v_add3_u32 v85, v85, v99, s68
	v_add3_u32 v84, v84, v100, s68
	v_and_b32_e32 v85, 0xffff0000, v85
	v_and_b32_e32 v84, 0xffff0000, v84
	v_or_b32_sdwa v85, v85, v97 dst_sel:DWORD dst_unused:UNUSED_PAD src0_sel:DWORD src1_sel:WORD_1
	v_or_b32_sdwa v84, v84, v96 dst_sel:DWORD dst_unused:UNUSED_PAD src0_sel:DWORD src1_sel:WORD_1
	v_lshlrev_b32_e32 v97, 16, v87
	v_lshlrev_b32_e32 v96, 16, v86
	v_pk_add_f32 v[96:97], v[96:97], v[88:89] op_sel_hi:[1,0] neg_lo:[0,1] neg_hi:[0,1]
	v_and_b32_e32 v87, 0xffff0000, v87
	v_and_b32_e32 v86, 0xffff0000, v86
	v_pk_mul_f32 v[96:97], v[88:89], v[96:97] op_sel:[1,0]
	v_pk_add_f32 v[86:87], v[86:87], v[88:89] op_sel_hi:[1,0] neg_lo:[0,1] neg_hi:[0,1]
	v_pk_mul_f32 v[96:97], v[92:93], v[96:97]
	v_pk_mul_f32 v[86:87], v[88:89], v[86:87] op_sel:[1,0]
	v_and_b32_sdwa v88, v97, v245 dst_sel:DWORD dst_unused:UNUSED_PAD src0_sel:WORD_1 src1_sel:DWORD
	v_pk_mul_f32 v[86:87], v[90:91], v[86:87]
	v_and_b32_sdwa v89, v96, v245 dst_sel:DWORD dst_unused:UNUSED_PAD src0_sel:WORD_1 src1_sel:DWORD
	v_add3_u32 v89, v96, v89, s68
	v_add3_u32 v88, v97, v88, s68
	v_and_b32_sdwa v96, v87, v245 dst_sel:DWORD dst_unused:UNUSED_PAD src0_sel:WORD_1 src1_sel:DWORD
	v_and_b32_sdwa v97, v86, v245 dst_sel:DWORD dst_unused:UNUSED_PAD src0_sel:WORD_1 src1_sel:DWORD
	v_add3_u32 v87, v87, v96, s68
	v_add3_u32 v86, v86, v97, s68
	v_and_b32_e32 v87, 0xffff0000, v87
	v_and_b32_e32 v86, 0xffff0000, v86
	v_or_b32_sdwa v87, v87, v88 dst_sel:DWORD dst_unused:UNUSED_PAD src0_sel:DWORD src1_sel:WORD_1
	v_or_b32_sdwa v86, v86, v89 dst_sel:DWORD dst_unused:UNUSED_PAD src0_sel:DWORD src1_sel:WORD_1
	ds_write2_b64 v98, v[84:85], v[86:87] offset0:192 offset1:196
	ds_read_b64 v[84:85], v218 offset:11136
	v_lshlrev_b32_e32 v87, 16, v81
	v_lshlrev_b32_e32 v86, 16, v80
	v_and_b32_e32 v81, 0xffff0000, v81
	v_and_b32_e32 v80, 0xffff0000, v80
	s_waitcnt lgkmcnt(0)
; #define LAS __attribute__((address_space(3)))
; #define MFMA16(a, b, c) __builtin_amdgcn_mfma_f32_16x16x32_bf16((a), (b), (c), 0, 0, 0)
; __device__ __forceinline__ unsigned pk2(float lo, float hi) { return f2bf(lo) | (f2bf(hi) << 16); }
; __device__ __forceinline__ float bflo(unsigned w) { return __uint_as_float(w << 16); }
; __device__ __forceinline__ float bfhi(unsigned w) { return __uint_as_float(w & 0xffff0000u); }
; #define LDS_WAIT() asm volatile("s_waitcnt lgkmcnt(0)" ::: "memory")
; __device__ __forceinline__ void sgu_item(LAS unsigned char* wl, const bf16* proj, bf16* ymix, const float* vstat, const float* sgu_g, const bf16* Wm, const float* sgu_b, int chunk, int h, int lane) {
;     ...
;         for (int i = 0; i < 8; ++i) { const int s = rsub + 16 * i; const f32x2 ms = st[s]; const v4u w = raw[i];
;             v2u lo, hi; lo.x = pk2((bflo(w.x) - ms.x) * ms.y * g0[0], (bfhi(w.x) - ms.x) * ms.y * g0[1]); lo.y = pk2((bflo(w.y) - ms.x) * ms.y * g0[2], (bfhi(w.y) - ms.x) * ms.y * g0[3]);
;             hi.x = pk2((bflo(w.z) - ms.x) * ms.y * g1[0], (bfhi(w.z) - ms.x) * ms.y * g1[1]); hi.y = pk2((bflo(w.w) - ms.x) * ms.y * g1[2], (bfhi(w.w) - ms.x) * ms.y * g1[3]);
;             *(LAS v2u*)(wl + s * VP2 + (4 * c16) * 2) = lo; *(LAS v2u*)(wl + s * VP2 + (16 + 4 * c16) * 2) = hi; }
;         v4u uu8[8];
; #pragma unroll
;         for (int tb = 0; tb < 8; ++tb) uu8[tb] = __builtin_nontemporal_load((const v4u*)(proj + (R0 + 16 * tb + r) * DIN + 512 + colv + 8 * q));
;         LDS_WAIT();
;         v2u olo[8];
; #pragma unroll
;         for (int n = 0; n < 2; ++n) {
;             f32x4 z[8];
; #pragma unroll
;             for (int tb = 0; tb < 8; ++tb) z[tb] = (f32x4){0.f, 0.f, 0.f, 0.f};
;             int f = 0;
; #pragma unroll
;             for (int ks = 0; ks < 4; ++ks) {
;                 LAS unsigned char* ad = wl + (ks * 32 + 8 * q + (r >> 2)) * VP2 + (16 * n) * 2 + 8 * (r & 3);
;                 const s16x4 lo = __builtin_bit_cast(s16x4, __builtin_amdgcn_ds_read_tr16_b64_v4i16((LAS s16x4*)ad));
;                 const s16x4 hi = __builtin_bit_cast(s16x4, __builtin_amdgcn_ds_read_tr16_b64_v4i16((LAS s16x4*)(ad + 4 * VP2)));
;                 const bf16x8 vf = __builtin_shufflevector(lo, hi, 0, 1, 2, 3, 4, 5, 6, 7);
; #pragma unroll
;                 for (int tb = 2 * ks; tb < 8; ++tb) z[tb] = MFMA16(vf, wmf[f++], z[tb]);
	v_pk_add_f32 v[86:87], v[86:87], v[84:85] op_sel_hi:[1,0] neg_lo:[0,1] neg_hi:[0,1]
	v_pk_add_f32 v[80:81], v[80:81], v[84:85] op_sel_hi:[1,0] neg_lo:[0,1] neg_hi:[0,1]
	v_pk_mul_f32 v[86:87], v[84:85], v[86:87] op_sel:[1,0]
	v_pk_mul_f32 v[80:81], v[84:85], v[80:81] op_sel:[1,0]
	v_pk_mul_f32 v[86:87], v[116:117], v[86:87]
	v_pk_mul_f32 v[80:81], v[94:95], v[80:81]
	v_and_b32_sdwa v88, v87, v245 dst_sel:DWORD dst_unused:UNUSED_PAD src0_sel:WORD_1 src1_sel:DWORD
	v_and_b32_sdwa v89, v86, v245 dst_sel:DWORD dst_unused:UNUSED_PAD src0_sel:WORD_1 src1_sel:DWORD
	v_add3_u32 v86, v86, v89, s68
	v_add3_u32 v87, v87, v88, s68
	v_and_b32_sdwa v88, v81, v245 dst_sel:DWORD dst_unused:UNUSED_PAD src0_sel:WORD_1 src1_sel:DWORD
	v_and_b32_sdwa v89, v80, v245 dst_sel:DWORD dst_unused:UNUSED_PAD src0_sel:WORD_1 src1_sel:DWORD
	v_add3_u32 v81, v81, v88, s68
	v_add3_u32 v80, v80, v89, s68
	v_and_b32_e32 v81, 0xffff0000, v81
	v_and_b32_e32 v80, 0xffff0000, v80
	v_or_b32_sdwa v81, v81, v87 dst_sel:DWORD dst_unused:UNUSED_PAD src0_sel:DWORD src1_sel:WORD_1
	v_or_b32_sdwa v80, v80, v86 dst_sel:DWORD dst_unused:UNUSED_PAD src0_sel:DWORD src1_sel:WORD_1
	v_lshlrev_b32_e32 v87, 16, v83
	v_lshlrev_b32_e32 v86, 16, v82
	v_pk_add_f32 v[86:87], v[86:87], v[84:85] op_sel_hi:[1,0] neg_lo:[0,1] neg_hi:[0,1]
	v_and_b32_e32 v83, 0xffff0000, v83
	v_and_b32_e32 v82, 0xffff0000, v82
	v_pk_mul_f32 v[86:87], v[84:85], v[86:87] op_sel:[1,0]
	v_pk_add_f32 v[82:83], v[82:83], v[84:85] op_sel_hi:[1,0] neg_lo:[0,1] neg_hi:[0,1]
	v_pk_mul_f32 v[86:87], v[92:93], v[86:87]
	v_pk_mul_f32 v[82:83], v[84:85], v[82:83] op_sel:[1,0]
	v_and_b32_sdwa v84, v87, v245 dst_sel:DWORD dst_unused:UNUSED_PAD src0_sel:WORD_1 src1_sel:DWORD
	v_pk_mul_f32 v[82:83], v[90:91], v[82:83]
	v_and_b32_sdwa v85, v86, v245 dst_sel:DWORD dst_unused:UNUSED_PAD src0_sel:WORD_1 src1_sel:DWORD
	v_add3_u32 v85, v86, v85, s68
	v_add3_u32 v84, v87, v84, s68
	v_and_b32_sdwa v86, v83, v245 dst_sel:DWORD dst_unused:UNUSED_PAD src0_sel:WORD_1 src1_sel:DWORD
	v_and_b32_sdwa v87, v82, v245 dst_sel:DWORD dst_unused:UNUSED_PAD src0_sel:WORD_1 src1_sel:DWORD
	v_add3_u32 v83, v83, v86, s68
	v_add3_u32 v82, v82, v87, s68
	v_and_b32_e32 v83, 0xffff0000, v83
	v_and_b32_e32 v82, 0xffff0000, v82
	v_or_b32_sdwa v83, v83, v84 dst_sel:DWORD dst_unused:UNUSED_PAD src0_sel:DWORD src1_sel:WORD_1
	v_or_b32_sdwa v82, v82, v85 dst_sel:DWORD dst_unused:UNUSED_PAD src0_sel:DWORD src1_sel:WORD_1
	v_add_u32_e32 v84, 0x2000, v219
	ds_write2_b64 v84, v[80:81], v[82:83] offset0:96 offset1:100
	v_lshl_add_u64 v[80:81], v[188:189], 0, s[20:21]
	v_add_co_u32_e32 v82, vcc, s0, v80
	s_mov_b32 s0, 0xf10c000
	s_nop 0
	v_addc_co_u32_e32 v83, vcc, 0, v81, vcc
	global_load_dwordx4 v[104:107], v[82:83], off offset:1024 nt
	v_add_co_u32_e32 v82, vcc, s0, v80
	s_mov_b32 s0, 0xf118000
	s_nop 0
	v_addc_co_u32_e32 v83, vcc, 0, v81, vcc
	global_load_dwordx4 v[100:103], v[82:83], off offset:1024 nt
	v_add_co_u32_e32 v82, vcc, s0, v80
	s_mov_b32 s0, 0xf130000
	s_nop 0
	v_addc_co_u32_e32 v83, vcc, 0, v81, vcc
	global_load_dwordx4 v[96:99], v[82:83], off offset:1024 nt
	v_lshl_add_u64 v[82:83], v[190:191], 0, s[20:21]
	global_load_dwordx4 v[92:95], v[82:83], off nt
	v_add_co_u32_e32 v82, vcc, s0, v80
	s_mov_b32 s0, 0xf13c000
	s_nop 0
	v_addc_co_u32_e32 v83, vcc, 0, v81, vcc
	global_load_dwordx4 v[88:91], v[82:83], off offset:1024 nt
	v_add_co_u32_e32 v82, vcc, s0, v80
	s_mov_b32 s0, 0xf148000
	s_nop 0
	v_addc_co_u32_e32 v83, vcc, 0, v81, vcc
	global_load_dwordx4 v[84:87], v[82:83], off offset:1024 nt
	v_add_co_u32_e32 v80, vcc, s0, v80
	v_lshl_add_u64 v[108:109], v[186:187], 0, s[20:21]
	s_nop 0
	v_addc_co_u32_e32 v81, vcc, 0, v81, vcc
	global_load_dwordx4 v[80:83], v[80:81], off offset:1024 nt
	s_mov_b32 s0, 0x10900000
	global_load_dwordx4 v[108:111], v[108:109], off nt
	s_waitcnt lgkmcnt(0)
	ds_read_b64_tr_b16 v[116:117], v220 offset:320
	ds_read_b64_tr_b16 v[114:115], v220
	ds_read_b64_tr_b16 v[112:113], v220 offset:32
	ds_read_b64_tr_b16 v[208:209], v220 offset:2560
	ds_read_b64_tr_b16 v[210:211], v220 offset:2880
	s_waitcnt lgkmcnt(0)
	v_mfma_f32_16x16x32_bf16 v[118:121], v[114:117], v[0:3], 0
	v_mfma_f32_16x16x32_bf16 v[122:125], v[114:117], v[4:7], 0
	s_nop 6
	v_mov_b32_e32 v138, v119
	v_mov_b32_e32 v119, v120
	v_pk_add_f32 v[118:119], v[162:163], v[118:119]
	v_mfma_f32_16x16x32_bf16 v[126:129], v[114:117], v[8:11], 0
	v_mov_b32_e32 v139, v121
	v_pk_add_f32 v[138:139], v[162:163], v[138:139]
	v_mfma_f32_16x16x32_bf16 v[130:133], v[114:117], v[16:19], 0
	v_mfma_f32_16x16x32_bf16 v[134:137], v[114:117], v[24:27], 0
	v_mfma_f32_16x16x32_bf16 v[200:203], v[114:117], v[48:51], 0
	v_mfma_f32_16x16x32_bf16 v[204:207], v[114:117], v[32:35], 0
	v_mfma_f32_16x16x32_bf16 v[114:117], v[114:117], v[40:43], 0
	v_mfma_f32_16x16x32_bf16 v[126:129], v[208:211], v[12:15], v[126:129]
	v_mfma_f32_16x16x32_bf16 v[130:133], v[208:211], v[20:23], v[130:133]
	v_mfma_f32_16x16x32_bf16 v[134:137], v[208:211], v[28:31], v[134:137]
	v_mfma_f32_16x16x32_bf16 v[200:203], v[208:211], v[56:59], v[200:203]
	v_mfma_f32_16x16x32_bf16 v[204:207], v[208:211], v[36:39], v[204:207]
	v_mfma_f32_16x16x32_bf16 v[114:117], v[208:211], v[44:47], v[114:117]
	ds_read_b64_tr_b16 v[208:209], v220 offset:5120
	ds_read_b64_tr_b16 v[210:211], v220 offset:5440
	s_waitcnt lgkmcnt(0)
	v_mfma_f32_16x16x32_bf16 v[222:225], v[208:211], v[60:63], v[200:203]
	v_mfma_f32_16x16x32_bf16 v[200:203], v[208:211], v[64:67], v[204:207]
	s_nop 2
	ds_read_b64_tr_b16 v[204:205], v220 offset:7680
	ds_read_b64_tr_b16 v[206:207], v220 offset:8000
	s_waitcnt lgkmcnt(0)
	v_mfma_f32_16x16x32_bf16 v[226:229], v[204:207], v[68:71], v[200:203]
	s_waitcnt vmcnt(0)
; #define LAS __attribute__((address_space(3)))
; #define MFMA16(a, b, c) __builtin_amdgcn_mfma_f32_16x16x32_bf16((a), (b), (c), 0, 0, 0)
; __device__ __forceinline__ unsigned pk2(float lo, float hi) { return f2bf(lo) | (f2bf(hi) << 16); }
; __device__ __forceinline__ float bflo(unsigned w) { return __uint_as_float(w << 16); }
; __device__ __forceinline__ float bfhi(unsigned w) { return __uint_as_float(w & 0xffff0000u); }
; __device__ __forceinline__ void sgu_item(LAS unsigned char* wl, const bf16* proj, bf16* ymix, const float* vstat, const float* sgu_g, const bf16* Wm, const float* sgu_b, int chunk, int h, int lane) {
;     ...
;         for (int n = 0; n < 2; ++n) {
;             f32x4 z[8];
; #pragma unroll
;             for (int tb = 0; tb < 8; ++tb) z[tb] = (f32x4){0.f, 0.f, 0.f, 0.f};
;             int f = 0;
; #pragma unroll
;             for (int ks = 0; ks < 4; ++ks) {
;                 LAS unsigned char* ad = wl + (ks * 32 + 8 * q + (r >> 2)) * VP2 + (16 * n) * 2 + 8 * (r & 3);
;                 const s16x4 lo = __builtin_bit_cast(s16x4, __builtin_amdgcn_ds_read_tr16_b64_v4i16((LAS s16x4*)ad));
;                 const s16x4 hi = __builtin_bit_cast(s16x4, __builtin_amdgcn_ds_read_tr16_b64_v4i16((LAS s16x4*)(ad + 4 * VP2)));
;                 const bf16x8 vf = __builtin_shufflevector(lo, hi, 0, 1, 2, 3, 4, 5, 6, 7);
; #pragma unroll
;                 for (int tb = 2 * ks; tb < 8; ++tb) z[tb] = MFMA16(vf, wmf[f++], z[tb]);
;             }
; #pragma unroll
;             for (int tb = 0; tb < 8; ++tb) { const v4u uu = uu8[tb]; const unsigned ux = n == 0 ? uu.x : uu.z, uy = n == 0 ? uu.y : uu.w;
;                 v2u o; o.x = pk2(bflo(ux) * (z[tb][0] + bias[tb]), bfhi(ux) * (z[tb][1] + bias[tb])); o.y = pk2(bflo(uy) * (z[tb][2] + bias[tb]), bfhi(uy) * (z[tb][3] + bias[tb]));
	s_nop 1
	v_and_b32_e32 v201, 0xffff0000, v105
	v_and_b32_e32 v200, 0xffff0000, v104
	v_lshlrev_b32_e32 v105, 16, v105
	v_lshlrev_b32_e32 v104, 16, v104
	v_pk_mul_f32 v[214:215], v[118:119], v[104:105]
	v_mov_b32_e32 v104, v123
	v_mov_b32_e32 v105, v125
	v_pk_add_f32 v[104:105], v[164:165], v[104:105]
	v_and_b32_e32 v119, 0xffff0000, v101
	v_and_b32_e32 v118, 0xffff0000, v100
	v_mov_b32_e32 v123, v124
	v_mfma_f32_16x16x32_bf16 v[114:117], v[208:211], v[72:75], v[114:117]
	v_mul_f32_e64 v212, v104, v118
	v_mul_f32_e64 v213, v105, v119
	v_pk_add_f32 v[104:105], v[164:165], v[122:123]
	v_lshlrev_b32_e32 v101, 16, v101
	v_lshlrev_b32_e32 v100, 16, v100
	v_mfma_f32_16x16x32_bf16 v[134:137], v[208:211], v[52:55], v[134:137]
	v_mul_f32_e64 v210, v104, v100
	v_mul_f32_e64 v211, v105, v101
	v_mov_b32_e32 v100, v127
	v_mov_b32_e32 v101, v129
	v_pk_add_f32 v[100:101], v[166:167], v[100:101]
	v_and_b32_e32 v105, 0xffff0000, v97
	v_and_b32_e32 v104, 0xffff0000, v96
	v_mov_b32_e32 v127, v128
	v_pk_mul_f32 v[208:209], v[100:101], v[104:105]
	v_pk_add_f32 v[100:101], v[166:167], v[126:127]
	v_lshlrev_b32_e32 v97, 16, v97
	v_lshlrev_b32_e32 v96, 16, v96
	v_mfma_f32_16x16x32_bf16 v[114:117], v[204:207], v[76:79], v[114:117]
	v_mul_f32_e64 v206, v100, v96
	v_mul_f32_e64 v207, v101, v97
	v_mov_b32_e32 v96, v131
	v_mov_b32_e32 v97, v133
	v_pk_add_f32 v[96:97], v[168:169], v[96:97]
	v_and_b32_e32 v101, 0xffff0000, v93
	v_and_b32_e32 v100, 0xffff0000, v92
	v_mov_b32_e32 v131, v132
	v_pk_mul_f32 v[204:205], v[96:97], v[100:101]
	v_pk_add_f32 v[96:97], v[168:169], v[130:131]
	v_lshlrev_b32_e32 v93, 16, v93
	v_lshlrev_b32_e32 v92, 16, v92
	v_pk_mul_f32 v[202:203], v[96:97], v[92:93]
	v_mov_b32_e32 v92, v135
	v_mov_b32_e32 v93, v137
	v_pk_add_f32 v[92:93], v[170:171], v[92:93]
	v_and_b32_e32 v97, 0xffff0000, v89
	v_and_b32_e32 v96, 0xffff0000, v88
	v_mov_b32_e32 v135, v136
	v_pk_mul_f32 v[216:217], v[138:139], v[200:201]
	v_pk_mul_f32 v[200:201], v[92:93], v[96:97]
	v_pk_add_f32 v[92:93], v[170:171], v[134:135]
	v_lshlrev_b32_e32 v89, 16, v89
	v_lshlrev_b32_e32 v88, 16, v88
	v_pk_mul_f32 v[104:105], v[92:93], v[88:89]
	v_mov_b32_e32 v88, v223
	v_mov_b32_e32 v89, v225
	v_pk_add_f32 v[88:89], v[172:173], v[88:89]
	v_and_b32_e32 v93, 0xffff0000, v85
	v_and_b32_e32 v92, 0xffff0000, v84
	v_mov_b32_e32 v223, v224
	v_pk_mul_f32 v[100:101], v[88:89], v[92:93]
	v_pk_add_f32 v[88:89], v[172:173], v[222:223]
	v_lshlrev_b32_e32 v85, 16, v85
	v_lshlrev_b32_e32 v84, 16, v84
	v_pk_mul_f32 v[96:97], v[88:89], v[84:85]
	v_mov_b32_e32 v84, v227
	v_mov_b32_e32 v85, v229
	v_pk_add_f32 v[84:85], v[174:175], v[84:85]
	v_and_b32_e32 v89, 0xffff0000, v81
	v_and_b32_e32 v88, 0xffff0000, v80
	v_mov_b32_e32 v227, v228
	v_pk_mul_f32 v[92:93], v[84:85], v[88:89]
	v_pk_add_f32 v[84:85], v[174:175], v[226:227]
	v_lshlrev_b32_e32 v81, 16, v81
	v_lshlrev_b32_e32 v80, 16, v80
	v_pk_mul_f32 v[80:81], v[84:85], v[80:81]
	v_mov_b32_e32 v84, v115
	v_mov_b32_e32 v85, v117
	v_pk_add_f32 v[84:85], v[176:177], v[84:85]
	v_and_b32_e32 v89, 0xffff0000, v109
	v_and_b32_e32 v88, 0xffff0000, v108
	v_mov_b32_e32 v115, v116
	v_pk_mul_f32 v[88:89], v[84:85], v[88:89]
	v_pk_add_f32 v[84:85], v[176:177], v[114:115]
	ds_read_b64_tr_b16 v[114:115], v220 offset:352
	ds_read_b64_tr_b16 v[234:235], v220 offset:2592
	ds_read_b64_tr_b16 v[236:237], v220 offset:2912
	s_waitcnt lgkmcnt(2)
	v_mfma_f32_16x16x32_bf16 v[120:123], v[112:115], v[16:19], 0
	v_lshlrev_b32_e32 v109, 16, v109
	v_lshlrev_b32_e32 v108, 16, v108
	v_pk_mul_f32 v[84:85], v[84:85], v[108:109]
	v_mfma_f32_16x16x32_bf16 v[226:229], v[112:115], v[48:51], 0
	v_bfe_u32 v196, v216, 16, 1
	v_add3_u32 v196, v216, v196, s68
	v_bfe_u32 v195, v217, 16, 1
	v_mfma_f32_16x16x32_bf16 v[230:233], v[112:115], v[32:35], 0
	v_add3_u32 v195, v217, v195, s68
	v_mfma_f32_16x16x32_bf16 v[116:119], v[112:115], v[8:11], 0
	v_mfma_f32_16x16x32_bf16 v[124:127], v[112:115], v[24:27], 0
	v_mfma_f32_16x16x32_bf16 v[222:225], v[112:115], v[0:3], 0
	v_mfma_f32_16x16x32_bf16 v[132:135], v[112:115], v[4:7], 0
	v_mfma_f32_16x16x32_bf16 v[112:115], v[112:115], v[40:43], 0
	s_nop 5
	v_mov_b32_e32 v108, v223
	v_mov_b32_e32 v223, v224
	v_mov_b32_e32 v109, v225
	s_waitcnt lgkmcnt(0)
	v_mfma_f32_16x16x32_bf16 v[128:131], v[234:237], v[20:23], v[120:123]
	v_add_f32_e64 v222, v162, v222
	v_add_f32_e64 v223, v163, v223
	v_pk_add_f32 v[108:109], v[162:163], v[108:109]
	v_mfma_f32_16x16x32_bf16 v[120:123], v[234:237], v[56:59], v[226:229]
	v_mfma_f32_16x16x32_bf16 v[226:229], v[234:237], v[36:39], v[230:233]
	s_nop 2
	ds_read_b64_tr_b16 v[230:231], v220 offset:5152
	ds_read_b64_tr_b16 v[232:233], v220 offset:5472
	v_mfma_f32_16x16x32_bf16 v[136:139], v[234:237], v[12:15], v[116:119]
	v_mfma_f32_16x16x32_bf16 v[116:119], v[234:237], v[28:31], v[124:127]
	v_mfma_f32_16x16x32_bf16 v[112:115], v[234:237], v[44:47], v[112:115]
	s_waitcnt lgkmcnt(0)
	v_mfma_f32_16x16x32_bf16 v[124:127], v[230:233], v[52:55], v[116:119]
	v_mfma_f32_16x16x32_bf16 v[116:119], v[230:233], v[64:67], v[226:229]
	s_nop 2
	ds_read_b64_tr_b16 v[226:227], v220 offset:7712
	ds_read_b64_tr_b16 v[228:229], v220 offset:8032
	v_mfma_f32_16x16x32_bf16 v[112:115], v[230:233], v[72:75], v[112:115]
	s_waitcnt lgkmcnt(0)
; __device__ __forceinline__ unsigned pk2(float lo, float hi) { return f2bf(lo) | (f2bf(hi) << 16); }
; __device__ __forceinline__ float bflo(unsigned w) { return __uint_as_float(w << 16); }
; __device__ __forceinline__ float bfhi(unsigned w) { return __uint_as_float(w & 0xffff0000u); }
; __device__ __forceinline__ void sgu_item(LAS unsigned char* wl, const bf16* proj, bf16* ymix, const float* vstat, const float* sgu_g, const bf16* Wm, const float* sgu_b, int chunk, int h, int lane) {
;     ...
; #pragma unroll
;             for (int tb = 0; tb < 8; ++tb) { const v4u uu = uu8[tb]; const unsigned ux = n == 0 ? uu.x : uu.z, uy = n == 0 ? uu.y : uu.w;
;                 v2u o; o.x = pk2(bflo(ux) * (z[tb][0] + bias[tb]), bfhi(ux) * (z[tb][1] + bias[tb])); o.y = pk2(bflo(uy) * (z[tb][2] + bias[tb]), bfhi(uy) * (z[tb][3] + bias[tb]));
;                 if (n == 0) olo[tb] = o;
;                 else { v4u w; w.x = olo[tb].x; w.y = olo[tb].y; w.z = o.x; w.w = o.y; *(v4u*)(ymix + (R0 + 16 * tb + r) * D + 512 + colv + 8 * q) = w; } }
	v_mfma_f32_16x16x32_bf16 v[116:119], v[226:229], v[68:71], v[116:119]
	v_mfma_f32_16x16x32_bf16 v[112:115], v[226:229], v[76:79], v[112:115]
	v_and_b32_e32 v227, 0xffff0000, v107
	v_and_b32_e32 v226, 0xffff0000, v106
	v_lshlrev_b32_e32 v107, 16, v107
	v_lshlrev_b32_e32 v106, 16, v106
	v_pk_mul_f32 v[106:107], v[222:223], v[106:107]
	v_pk_mul_f32 v[108:109], v[108:109], v[226:227]
	v_bfe_u32 v197, v106, 16, 1
	v_bfe_u32 v216, v107, 16, 1
	v_bfe_u32 v192, v109, 16, 1
	v_bfe_u32 v194, v108, 16, 1
	v_add3_u32 v107, v107, v216, s68
	v_add3_u32 v106, v106, v197, s68
	v_add3_u32 v108, v108, v194, s68
	v_add3_u32 v109, v109, v192, s68
	v_bfe_u32 v192, v214, 16, 1
	v_bfe_u32 v194, v215, 16, 1
	v_lshrrev_b32_e32 v106, 16, v106
	v_lshrrev_b32_e32 v107, 16, v107
	v_add3_u32 v194, v215, v194, s68
	v_add3_u32 v192, v214, v192, s68
	v_and_or_b32 v217, v109, s37, v107
	v_and_or_b32 v216, v108, s37, v106
	v_lshl_add_u64 v[106:107], v[182:183], 0, s[20:21]
	v_lshrrev_b32_e32 v192, 16, v192
	v_lshrrev_b32_e32 v194, 16, v194
	v_add_co_u32_e32 v108, vcc, s0, v106
	v_and_or_b32 v215, v195, s37, v194
	v_and_or_b32 v214, v196, s37, v192
	v_addc_co_u32_e32 v109, vcc, 0, v107, vcc
	global_store_dwordx4 v[108:109], v[214:217], off offset:1024
	v_mov_b32_e32 v108, v133
	v_mov_b32_e32 v109, v135
	v_mov_b32_e32 v133, v134
	v_pk_add_f32 v[108:109], v[164:165], v[108:109]
	v_and_b32_e32 v215, 0xffff0000, v103
	v_and_b32_e32 v214, 0xffff0000, v102
	v_pk_add_f32 v[132:133], v[164:165], v[132:133]
	v_lshlrev_b32_e32 v103, 16, v103
	v_lshlrev_b32_e32 v102, 16, v102
	v_pk_mul_f32 v[108:109], v[108:109], v[214:215]
	v_pk_mul_f32 v[102:103], v[132:133], v[102:103]
	v_bfe_u32 v134, v213, 16, 1
	v_bfe_u32 v132, v109, 16, 1
	v_bfe_u32 v133, v108, 16, 1
	v_bfe_u32 v135, v212, 16, 1
	v_add3_u32 v194, v213, v134, s68
	v_bfe_u32 v134, v102, 16, 1
	v_add3_u32 v192, v212, v135, s68
	v_add3_u32 v108, v108, v133, s68
	v_add3_u32 v109, v109, v132, s68
	v_bfe_u32 v132, v210, 16, 1
	v_bfe_u32 v133, v211, 16, 1
	v_bfe_u32 v135, v103, 16, 1
	v_add3_u32 v102, v102, v134, s68
	v_add3_u32 v103, v103, v135, s68
	v_add3_u32 v133, v211, v133, s68
	v_add3_u32 v132, v210, v132, s68
	v_lshrrev_b32_e32 v102, 16, v102
	s_mov_b32 s0, 0x10908000
	v_lshrrev_b32_e32 v132, 16, v132
	v_lshrrev_b32_e32 v133, 16, v133
	v_lshrrev_b32_e32 v103, 16, v103
	v_and_or_b32 v134, v108, s37, v102
	v_add_co_u32_e32 v102, vcc, s0, v106
	v_and_or_b32 v135, v109, s37, v103
	v_and_or_b32 v133, v194, s37, v133
	v_and_or_b32 v132, v192, s37, v132
	v_addc_co_u32_e32 v103, vcc, 0, v107, vcc
	global_store_dwordx4 v[102:103], v[132:135], off offset:1024
	v_mov_b32_e32 v102, v137
	v_mov_b32_e32 v103, v139
	v_pk_add_f32 v[102:103], v[166:167], v[102:103]
	v_and_b32_e32 v109, 0xffff0000, v99
	v_and_b32_e32 v108, 0xffff0000, v98
	v_mov_b32_e32 v137, v138
	v_pk_mul_f32 v[102:103], v[102:103], v[108:109]
	v_pk_add_f32 v[108:109], v[166:167], v[136:137]
	v_lshlrev_b32_e32 v99, 16, v99
	v_lshlrev_b32_e32 v98, 16, v98
	v_pk_mul_f32 v[98:99], v[108:109], v[98:99]
	v_bfe_u32 v133, v208, 16, 1
	v_bfe_u32 v108, v103, 16, 1
	v_bfe_u32 v109, v102, 16, 1
	v_add3_u32 v136, v208, v133, s68
	v_bfe_u32 v133, v98, 16, 1
	v_add3_u32 v102, v102, v109, s68
	v_add3_u32 v103, v103, v108, s68
	v_bfe_u32 v108, v206, 16, 1
	v_bfe_u32 v109, v207, 16, 1
	v_bfe_u32 v134, v99, 16, 1
	v_add3_u32 v98, v98, v133, s68
	v_bfe_u32 v132, v209, 16, 1
	v_add3_u32 v99, v99, v134, s68
	v_add3_u32 v109, v207, v109, s68
	v_add3_u32 v108, v206, v108, s68
	v_lshrrev_b32_e32 v98, 16, v98
	s_mov_b32 s0, 0x10910000
	v_add3_u32 v132, v209, v132, s68
	v_lshrrev_b32_e32 v108, 16, v108
	v_lshrrev_b32_e32 v109, 16, v109
	v_lshrrev_b32_e32 v99, 16, v99
	v_and_or_b32 v134, v102, s37, v98
	v_add_co_u32_e32 v98, vcc, s0, v106
	v_and_or_b32 v135, v103, s37, v99
	v_and_or_b32 v133, v132, s37, v109
	v_and_or_b32 v132, v136, s37, v108
	v_addc_co_u32_e32 v99, vcc, 0, v107, vcc
	global_store_dwordx4 v[98:99], v[132:135], off offset:1024
	v_mov_b32_e32 v98, v129
	v_mov_b32_e32 v99, v131
	v_pk_add_f32 v[98:99], v[168:169], v[98:99]
	v_and_b32_e32 v103, 0xffff0000, v95
	v_and_b32_e32 v102, 0xffff0000, v94
	v_mov_b32_e32 v129, v130
	v_pk_mul_f32 v[98:99], v[98:99], v[102:103]
	v_pk_add_f32 v[102:103], v[168:169], v[128:129]
	v_lshlrev_b32_e32 v95, 16, v95
	v_lshlrev_b32_e32 v94, 16, v94
	v_pk_mul_f32 v[94:95], v[102:103], v[94:95]
	v_bfe_u32 v102, v99, 16, 1
	v_bfe_u32 v103, v98, 16, 1
	v_add3_u32 v98, v98, v103, s68
	v_add3_u32 v99, v99, v102, s68
	v_bfe_u32 v102, v202, 16, 1
	v_bfe_u32 v103, v203, 16, 1
	v_bfe_u32 v128, v94, 16, 1
	v_bfe_u32 v129, v95, 16, 1
	v_bfe_u32 v108, v205, 16, 1
	v_bfe_u32 v109, v204, 16, 1
	v_add3_u32 v95, v95, v129, s68
	v_add3_u32 v94, v94, v128, s68
	v_add3_u32 v103, v203, v103, s68
	v_add3_u32 v102, v202, v102, s68
	v_add3_u32 v109, v204, v109, s68
	v_add3_u32 v108, v205, v108, s68
	v_lshrrev_b32_e32 v102, 16, v102
	v_lshrrev_b32_e32 v103, 16, v103
	v_lshrrev_b32_e32 v94, 16, v94
	v_lshrrev_b32_e32 v95, 16, v95
	v_and_or_b32 v131, v99, s37, v95
	v_and_or_b32 v130, v98, s37, v94
	v_and_or_b32 v129, v108, s37, v103
	v_and_or_b32 v128, v109, s37, v102
	v_lshl_add_u64 v[94:95], v[184:185], 0, s[20:21]
	global_store_dwordx4 v[94:95], v[128:131], off
	v_mov_b32_e32 v94, v125
	v_mov_b32_e32 v95, v127
	v_pk_add_f32 v[94:95], v[170:171], v[94:95]
; __device__ __forceinline__ unsigned pk2(float lo, float hi) { return f2bf(lo) | (f2bf(hi) << 16); }
; __device__ __forceinline__ float bflo(unsigned w) { return __uint_as_float(w << 16); }
; __device__ __forceinline__ float bfhi(unsigned w) { return __uint_as_float(w & 0xffff0000u); }
; #define LDS_WAIT() asm volatile("s_waitcnt lgkmcnt(0)" ::: "memory")
; #define lane (hw_lane())
; __device__ __forceinline__ void sgu_item(LAS unsigned char* wl, const bf16* proj, bf16* ymix, const float* vstat, const float* sgu_g, const bf16* Wm, const float* sgu_b, int chunk, int h, int lane) {
;     ...
; #pragma unroll
;             for (int tb = 0; tb < 8; ++tb) { const v4u uu = uu8[tb]; const unsigned ux = n == 0 ? uu.x : uu.z, uy = n == 0 ? uu.y : uu.w;
;                 v2u o; o.x = pk2(bflo(ux) * (z[tb][0] + bias[tb]), bfhi(ux) * (z[tb][1] + bias[tb])); o.y = pk2(bflo(uy) * (z[tb][2] + bias[tb]), bfhi(uy) * (z[tb][3] + bias[tb]));
;                 if (n == 0) olo[tb] = o;
;                 else { v4u w; w.x = olo[tb].x; w.y = olo[tb].y; w.z = o.x; w.w = o.y; *(v4u*)(ymix + (R0 + 16 * tb + r) * D + 512 + colv + 8 * q) = w; } }
;         }
;         LDS_WAIT();
;     }
; __device__ __forceinline__ void mixer_phase(LAS unsigned char* lds, const bf16* proj, bf16* ymix, const float* vstat, const bf16* WpT, const float* pscale, const float* sgu_g, const bf16* Wm, const float* sgu_b, int pool_first, int pool_step, int pool_limit, int sgu_first, int sgu_step, int sgu_limi ...
;     ...
;     for (int j = sgu_first; j < sgu_limit; j += sgu_step) sgu_item(wl, proj, ymix, vstat, sgu_g, Wm, sgu_b, j >> 2, j & 3, lane);
	v_and_b32_e32 v99, 0xffff0000, v91
	v_and_b32_e32 v98, 0xffff0000, v90
	v_mov_b32_e32 v125, v126
	v_pk_mul_f32 v[94:95], v[94:95], v[98:99]
	v_pk_add_f32 v[98:99], v[170:171], v[124:125]
	v_lshlrev_b32_e32 v91, 16, v91
	v_lshlrev_b32_e32 v90, 16, v90
	v_pk_mul_f32 v[90:91], v[98:99], v[90:91]
	v_bfe_u32 v103, v200, 16, 1
	v_bfe_u32 v98, v95, 16, 1
	v_bfe_u32 v99, v94, 16, 1
	v_add3_u32 v108, v200, v103, s68
	v_bfe_u32 v103, v90, 16, 1
	v_mfma_f32_16x16x32_bf16 v[120:123], v[230:233], v[60:63], v[120:123]
	v_add3_u32 v94, v94, v99, s68
	v_add3_u32 v95, v95, v98, s68
	v_bfe_u32 v98, v104, 16, 1
	v_bfe_u32 v99, v105, 16, 1
	v_bfe_u32 v109, v91, 16, 1
	v_add3_u32 v90, v90, v103, s68
	v_bfe_u32 v102, v201, 16, 1
	v_add3_u32 v91, v91, v109, s68
	v_add3_u32 v99, v105, v99, s68
	v_add3_u32 v98, v104, v98, s68
	v_lshrrev_b32_e32 v90, 16, v90
	s_mov_b32 s0, 0x10920000
	v_add3_u32 v102, v201, v102, s68
	v_lshrrev_b32_e32 v98, 16, v98
	v_lshrrev_b32_e32 v99, 16, v99
	v_lshrrev_b32_e32 v91, 16, v91
	v_and_or_b32 v104, v94, s37, v90
	v_add_co_u32_e32 v90, vcc, s0, v106
	v_and_or_b32 v105, v95, s37, v91
	v_and_or_b32 v103, v102, s37, v99
	v_and_or_b32 v102, v108, s37, v98
	v_addc_co_u32_e32 v91, vcc, 0, v107, vcc
	global_store_dwordx4 v[90:91], v[102:105], off offset:1024
	v_mov_b32_e32 v90, v121
	v_mov_b32_e32 v91, v123
	v_pk_add_f32 v[90:91], v[172:173], v[90:91]
	v_and_b32_e32 v95, 0xffff0000, v87
	v_and_b32_e32 v94, 0xffff0000, v86
	v_mov_b32_e32 v121, v122
	v_pk_mul_f32 v[90:91], v[90:91], v[94:95]
	v_pk_add_f32 v[94:95], v[172:173], v[120:121]
	v_lshlrev_b32_e32 v87, 16, v87
	v_lshlrev_b32_e32 v86, 16, v86
	v_pk_mul_f32 v[86:87], v[94:95], v[86:87]
	v_bfe_u32 v99, v100, 16, 1
	v_bfe_u32 v94, v91, 16, 1
	v_bfe_u32 v95, v90, 16, 1
	v_bfe_u32 v98, v101, 16, 1
	v_add3_u32 v99, v100, v99, s68
	v_bfe_u32 v100, v86, 16, 1
	v_add3_u32 v98, v101, v98, s68
	v_add3_u32 v90, v90, v95, s68
	v_add3_u32 v91, v91, v94, s68
	v_bfe_u32 v94, v96, 16, 1
	v_bfe_u32 v95, v97, 16, 1
	v_bfe_u32 v101, v87, 16, 1
	v_add3_u32 v86, v86, v100, s68
	v_add3_u32 v87, v87, v101, s68
	v_add3_u32 v95, v97, v95, s68
	v_add3_u32 v94, v96, v94, s68
	v_lshrrev_b32_e32 v86, 16, v86
	s_mov_b32 s0, 0x10928000
	v_lshrrev_b32_e32 v94, 16, v94
	v_lshrrev_b32_e32 v95, 16, v95
	v_lshrrev_b32_e32 v87, 16, v87
	v_and_or_b32 v96, v90, s37, v86
	v_add_co_u32_e32 v86, vcc, s0, v106
	v_and_or_b32 v97, v91, s37, v87
	v_and_or_b32 v95, v98, s37, v95
	v_and_or_b32 v94, v99, s37, v94
	v_addc_co_u32_e32 v87, vcc, 0, v107, vcc
	global_store_dwordx4 v[86:87], v[94:97], off offset:1024
	v_mov_b32_e32 v86, v117
	v_mov_b32_e32 v87, v119
	v_pk_add_f32 v[86:87], v[174:175], v[86:87]
	v_and_b32_e32 v91, 0xffff0000, v83
	v_and_b32_e32 v90, 0xffff0000, v82
	v_mov_b32_e32 v117, v118
	v_pk_mul_f32 v[86:87], v[86:87], v[90:91]
	v_pk_add_f32 v[90:91], v[174:175], v[116:117]
	v_lshlrev_b32_e32 v83, 16, v83
	v_lshlrev_b32_e32 v82, 16, v82
	v_pk_mul_f32 v[82:83], v[90:91], v[82:83]
	v_bfe_u32 v94, v93, 16, 1
	v_bfe_u32 v90, v87, 16, 1
	v_bfe_u32 v91, v86, 16, 1
	v_bfe_u32 v95, v92, 16, 1
	v_add3_u32 v93, v93, v94, s68
	v_bfe_u32 v94, v82, 16, 1
	v_add3_u32 v92, v92, v95, s68
	v_add3_u32 v86, v86, v91, s68
	v_add3_u32 v87, v87, v90, s68
	v_bfe_u32 v90, v80, 16, 1
	v_bfe_u32 v91, v81, 16, 1
	v_bfe_u32 v95, v83, 16, 1
	v_add3_u32 v82, v82, v94, s68
	v_add3_u32 v83, v83, v95, s68
	v_add3_u32 v81, v81, v91, s68
	v_add3_u32 v80, v80, v90, s68
	v_lshrrev_b32_e32 v82, 16, v82
	s_mov_b32 s0, 0x10930000
	v_lshrrev_b32_e32 v80, 16, v80
	v_lshrrev_b32_e32 v81, 16, v81
	v_lshrrev_b32_e32 v83, 16, v83
	v_and_or_b32 v82, v86, s37, v82
	v_add_co_u32_e32 v86, vcc, s0, v106
	v_and_or_b32 v83, v87, s37, v83
	v_and_or_b32 v81, v93, s37, v81
	v_and_or_b32 v80, v92, s37, v80
	v_addc_co_u32_e32 v87, vcc, 0, v107, vcc
	global_store_dwordx4 v[86:87], v[80:83], off offset:1024
	v_lshlrev_b32_e32 v87, 16, v111
	v_lshlrev_b32_e32 v86, 16, v110
	v_mov_b32_e32 v80, v113
	v_mov_b32_e32 v81, v115
	v_pk_add_f32 v[80:81], v[176:177], v[80:81]
	v_and_b32_e32 v83, 0xffff0000, v111
	v_and_b32_e32 v82, 0xffff0000, v110
	v_mov_b32_e32 v113, v114
	v_pk_mul_f32 v[80:81], v[80:81], v[82:83]
	v_pk_add_f32 v[82:83], v[176:177], v[112:113]
	v_bfe_u32 v90, v89, 16, 1
	v_pk_mul_f32 v[82:83], v[82:83], v[86:87]
	v_bfe_u32 v86, v81, 16, 1
	v_bfe_u32 v87, v80, 16, 1
	v_bfe_u32 v91, v88, 16, 1
	v_add3_u32 v88, v88, v91, s68
	v_add3_u32 v89, v89, v90, s68
	v_add3_u32 v80, v80, v87, s68
	v_add3_u32 v81, v81, v86, s68
	v_bfe_u32 v86, v84, 16, 1
	v_bfe_u32 v87, v85, 16, 1
	v_bfe_u32 v90, v82, 16, 1
	v_bfe_u32 v91, v83, 16, 1
	v_add3_u32 v83, v83, v91, s68
	v_add3_u32 v82, v82, v90, s68
	v_add3_u32 v85, v85, v87, s68
	v_add3_u32 v84, v84, v86, s68
	v_lshrrev_b32_e32 v84, 16, v84
	v_lshrrev_b32_e32 v85, 16, v85
	v_lshrrev_b32_e32 v82, 16, v82
	v_lshrrev_b32_e32 v83, 16, v83
	v_and_or_b32 v83, v81, s37, v83
	v_and_or_b32 v82, v80, s37, v82
	v_and_or_b32 v81, v89, s37, v85
	v_and_or_b32 v80, v88, s37, v84
	v_lshl_add_u64 v[84:85], v[180:181], 0, s[20:21]
	global_store_dwordx4 v[84:85], v[80:83], off
	s_waitcnt lgkmcnt(0)
	s_add_u32 s20, s20, 64
	s_addc_u32 s21, s21, 0
	s_cmpk_lg_i32 s20, 0x100
	s_cbranch_scc1 .LBB0_511
	s_add_i32 s5, s5, s77
	s_add_i32 s4, s4, s7
	s_cmp_lt_i32 s5, s2
	s_cbranch_scc1 .LBB0_510

; __device__ __forceinline__ float row_rstd(const float* slots, int row) {
;     const f32x4* s = (const f32x4*)(slots + (size_t)row * 16);
;     const f32x4 a = s[0], b = s[1], c = s[2], d = s[3];
;     const f32x4 t = (a + b) + (c + d);
;     const float ss = (t[0] + t[1]) + (t[2] + t[3]);
;     return __builtin_amdgcn_rsqf(ss * (1.0f / 1024.0f) + 1e-6f);
; }
;     __device__ __forceinline__ void operator()(f32x4 (&acc)[2][2][4][2], const Unit& u, int wr, int wc, int fr, int fq) const {
;         float loc[2];
; #pragma unroll
;         for (int ai = 0; ai < 2; ++ai) loc[ai] = scale * row_rstd(slots, u.pm * BM + wr * 64 + ai * HALF + fq * 16 + fr);
; #pragma unroll
;         for (int ai = 0; ai < 2; ++ai)
; #pragma unroll
;             for (int m = 0; m < 4; ++m) { float mx = -3.0e38f; const float rsm = __shfl(loc[ai], m * 16 + fr);
; #pragma unroll
;                 for (int bj = 0; bj < 2; ++bj)
; #pragma unroll
;                     for (int n = 0; n < 2; ++n) { const f32x4 x = acc[ai][bj][m][n] * rsm; acc[ai][bj][m][n] = x; mx = fmaxf(fmaxf(mx, fmaxf(x[0], x[1])), fmaxf(x[2], x[3])); }
;                 mx = fmaxf(mx, __shfl_xor(mx, 16)); mx = fmaxf(mx, __shfl_xor(mx, 32));
;                 if (fq == 0) xch[(ai * HALF + wr * 64 + m * 16 + fr) * 4 + wc] = mx; }
.LBB0_690:
	s_lshl_b32 s13, s67, 8
	v_add_u32_e32 v158, s13, v213
	v_ashrrev_i32_e32 v159, 31, v158
	v_lshlrev_b64 v[128:129], 6, v[158:159]
	v_lshl_add_u64 v[140:141], s[4:5], 0, v[128:129]
	global_load_dwordx4 v[128:131], v[140:141], off
	global_load_dwordx4 v[132:135], v[140:141], off offset:16
	global_load_dwordx4 v[136:139], v[140:141], off offset:32
	s_nop 0
	global_load_dwordx4 v[140:143], v[140:141], off offset:48
	v_and_b32_e32 v157, 64, v252
	v_xor_b32_e32 v159, 16, v252
	s_waitcnt vmcnt(0) lgkmcnt(0)
	v_pk_add_f32 v[130:131], v[130:131], v[134:135]
	v_pk_add_f32 v[128:129], v[128:129], v[132:133]
	v_pk_add_f32 v[132:133], v[138:139], v[142:143]
	v_pk_add_f32 v[134:135], v[136:137], v[140:141]
	v_pk_add_f32 v[130:131], v[130:131], v[132:133]
	v_pk_add_f32 v[128:129], v[128:129], v[134:135]
	s_nop 0
	v_pk_mov_b32 v[132:133], v[128:129], v[130:131] op_sel:[1,0]
	v_mov_b32_e32 v129, v131
	v_pk_add_f32 v[128:129], v[132:133], v[128:129]
	s_nop 0
	v_add_f32_e32 v128, v128, v129
	v_fmamk_f32 v128, v128, 0x3a800000, v244
	v_rsq_f32_e32 v128, v128
	s_nop 0
	v_mul_f32_e32 v156, 0x3db8aa3b, v128
	v_add_u32_e32 v128, 0x80, v158
	v_ashrrev_i32_e32 v129, 31, v128
	v_lshlrev_b64 v[128:129], 6, v[128:129]
	v_lshl_add_u64 v[132:133], s[4:5], 0, v[128:129]
	global_load_dwordx4 v[136:139], v[132:133], off
	global_load_dwordx4 v[140:143], v[132:133], off offset:16
	global_load_dwordx4 v[128:131], v[132:133], off offset:32
	s_nop 0
	global_load_dwordx4 v[132:135], v[132:133], off offset:48
	v_or_b32_e32 v158, v157, v210
	v_lshlrev_b32_e32 v236, 2, v158
	ds_bpermute_b32 v158, v236, v156
	v_add_u32_e32 v157, 64, v157
	v_cmp_lt_i32_e32 vcc, v159, v157
	s_nop 1
	v_cndmask_b32_e32 v159, v252, v159, vcc
	v_lshlrev_b32_e32 v234, 2, v159
	v_xor_b32_e32 v159, 32, v252
	v_cmp_lt_i32_e32 vcc, v159, v157
	s_waitcnt lgkmcnt(0)
	v_pk_mul_f32 v[126:127], v[126:127], v[158:159] op_sel_hi:[1,0]
	v_pk_mul_f32 v[124:125], v[124:125], v[158:159] op_sel_hi:[1,0]
	v_cndmask_b32_e32 v157, v252, v159, vcc
	v_max_f32_e32 v159, v126, v127
	v_lshlrev_b32_e32 v235, 2, v157
	v_max_f32_e32 v157, v124, v125
	v_pk_mul_f32 v[122:123], v[122:123], v[158:159] op_sel_hi:[1,0]
	v_pk_mul_f32 v[180:181], v[120:121], v[158:159] op_sel_hi:[1,0]
	v_max3_f32 v157, v157, s6, v159
	v_max_f32_e32 v120, v180, v181
	v_max_f32_e32 v121, v122, v123
	v_max3_f32 v157, v157, v120, v121
	v_pk_mul_f32 v[120:121], v[118:119], v[158:159] op_sel_hi:[1,0]
	v_pk_mul_f32 v[182:183], v[116:117], v[158:159] op_sel_hi:[1,0]
	v_max_f32_e32 v117, v120, v121
	v_max_f32_e32 v116, v182, v183
	v_pk_mul_f32 v[114:115], v[114:115], v[158:159] op_sel_hi:[1,0]
	v_pk_mul_f32 v[112:113], v[112:113], v[158:159] op_sel_hi:[1,0]
	v_max3_f32 v116, v157, v116, v117
	v_max_f32_e32 v117, v112, v113
	v_max_f32_e32 v118, v114, v115
	v_max3_f32 v116, v116, v117, v118
	ds_bpermute_b32 v117, v234, v116
	s_waitcnt lgkmcnt(0)
	v_max_f32_e32 v117, v117, v117
	v_max_f32_e32 v116, v116, v117
	ds_bpermute_b32 v117, v235, v116
	s_and_saveexec_b64 s[22:23], s[40:41]
	s_cbranch_execz .LBB0_692
	s_waitcnt lgkmcnt(0)
	v_max_f32_e32 v117, v117, v117
	v_max_f32_e32 v116, v116, v116
	v_max_f32_e32 v116, v116, v117
	ds_write_b32 v223, v116

; #define PG8_LAS __attribute__((address_space(3)))
; __device__ __forceinline__ unsigned cvt_pk_bf16(float lo, float hi) { unsigned r; asm volatile("v_cvt_pk_bf16_f32 %0, %1, %2" : "=v"(r) : "v"(lo), "v"(hi)); return r; }
;     __device__ __forceinline__ void operator()(f32x4 (&acc)[2][2][4][2], const Unit& u, int wr, int wc, int fr, int fq) const {
;     ...
;         asm volatile("s_waitcnt lgkmcnt(0)" ::: "memory"); __builtin_amdgcn_s_barrier(); asm volatile("" ::: "memory");
; #pragma unroll
;         for (int ai = 0; ai < 2; ++ai)
; #pragma unroll
;             for (int m = 0; m < 4; ++m) { const int r = ai * HALF + wr * 64 + m * 16 + fr; const f32x4 s4 = *(const PG8_LAS f32x4*)(xch + 1024 + r * 4);
;                 const float inv = 1.0f / ((s4[0] + s4[1]) + (s4[2] + s4[3]));
;                 bf16_t* rowp = P + (size_t)(u.pm >> 5) * bgap + (size_t)(u.pm * BM + r) * 1024 + u.pn * BM + wc * 32 + 8 * fq;
; #pragma unroll
;                 for (int bj = 0; bj < 2; ++bj) { const f32x4 v0 = acc[ai][bj][m][0] * inv, v1 = acc[ai][bj][m][1] * inv;
;                     u32x4 w; w.x = cvt_pk_bf16(v0[0], v0[1]); w.y = cvt_pk_bf16(v0[2], v0[3]); w.z = cvt_pk_bf16(v1[0], v1[1]); w.w = cvt_pk_bf16(v1[2], v1[3]);
;                     *(u32x4*)(rowp + bj * HALF) = w; }
;                 asm volatile("" ::: "memory"); }
.LBB0_722:
	s_or_b64 exec, exec, s[22:23]
	s_waitcnt lgkmcnt(0)
	s_barrier
	v_add_u32_e32 v128, s2, v214
	s_waitcnt lgkmcnt(0)
	ds_read_b128 v[128:131], v128
	s_ashr_i32 s17, s67, 5
	s_lshl_b32 s24, s66, 8
	s_ashr_i32 s25, s24, 31
	s_waitcnt lgkmcnt(0)
	v_mov_b32_e32 v132, v129
	v_mov_b32_e32 v133, v130
	v_mov_b32_e32 v129, v131
	v_pk_add_f32 v[128:129], v[132:133], v[128:129]
	s_nop 0
	v_add_f32_e32 v128, v128, v129
	v_div_scale_f32 v129, s[22:23], v128, v128, 1.0
	v_rcp_f32_e32 v130, v129
	s_mul_hi_i32 s23, s17, 0x1c00000
	s_mul_i32 s17, s17, 0x1c00000
	s_add_u32 s22, s47, s17
	v_fma_f32 v131, -v129, v130, 1.0
	v_fmac_f32_e32 v130, v131, v130
	v_div_scale_f32 v131, vcc, 1.0, v128, 1.0
	v_mul_f32_e32 v132, v131, v130
	v_fma_f32 v133, -v129, v132, v131
	v_fmac_f32_e32 v132, v133, v130
	v_fma_f32 v129, -v129, v132, v131
	v_div_fmas_f32 v129, v129, v130, v132
	v_add_u32_e32 v130, s13, v211
	v_ashrrev_i32_e32 v131, 31, v130
	s_addc_u32 s23, s60, s23
	v_lshlrev_b64 v[130:131], 11, v[130:131]
	v_lshl_add_u64 v[130:131], s[22:23], 0, v[130:131]
	s_lshl_b64 s[24:25], s[24:25], 1
	v_div_fixup_f32 v128, v129, v128, 1.0
	v_lshl_add_u64 v[130:131], v[130:131], 0, s[24:25]
	v_lshl_add_u64 v[130:131], v[130:131], 0, s[86:87]
	v_pk_mul_f32 v[118:119], v[118:119], v[128:129] op_sel_hi:[1,0]
	v_pk_mul_f32 v[110:111], v[110:111], v[128:129] op_sel_hi:[1,0]
	v_lshl_add_u64 v[130:131], v[130:131], 0, v[192:193]
	v_pk_mul_f32 v[124:125], v[124:125], v[128:129] op_sel_hi:[1,0]
	v_pk_mul_f32 v[132:133], v[116:117], v[128:129] op_sel_hi:[1,0]
	v_cvt_pk_bf16_f32 v116, v110, v111
	v_cvt_pk_bf16_f32 v117, v118, v119
	v_pk_mul_f32 v[110:111], v[122:123], v[128:129] op_sel_hi:[1,0]
	v_cvt_pk_bf16_f32 v118, v132, v133
	v_cvt_pk_bf16_f32 v119, v124, v125
	v_pk_mul_f32 v[108:109], v[108:109], v[128:129] op_sel_hi:[1,0]
	global_store_dwordx4 v[130:131], v[116:119], off
	v_cvt_pk_bf16_f32 v108, v108, v109
	v_cvt_pk_bf16_f32 v109, v110, v111
	s_nop 1
	v_pk_mul_f32 v[116:117], v[126:127], v[128:129] op_sel_hi:[1,0]
	v_pk_mul_f32 v[118:119], v[120:121], v[128:129] op_sel_hi:[1,0]
	s_nop 0
	v_cvt_pk_bf16_f32 v110, v118, v119
	v_cvt_pk_bf16_f32 v111, v116, v117
	global_store_dwordx4 v[130:131], v[108:111], off offset:256
	ds_read_b128 v[108:111], v228
	s_waitcnt lgkmcnt(0)
	v_mov_b32_e32 v116, v109
	v_mov_b32_e32 v117, v110
	v_mov_b32_e32 v109, v111
	v_pk_add_f32 v[108:109], v[116:117], v[108:109]
	s_nop 0
	v_add_f32_e32 v108, v108, v109
	v_div_scale_f32 v109, s[26:27], v108, v108, 1.0
	v_rcp_f32_e32 v110, v109
	s_nop 0
	v_fma_f32 v111, -v109, v110, 1.0
	v_fmac_f32_e32 v110, v111, v110
	v_div_scale_f32 v111, vcc, 1.0, v108, 1.0
	v_mul_f32_e32 v116, v111, v110
	v_fma_f32 v117, -v109, v116, v111
	v_fmac_f32_e32 v116, v117, v110
	v_fma_f32 v109, -v109, v116, v111
	v_div_fmas_f32 v109, v109, v110, v116
	v_div_fixup_f32 v110, v109, v108, 1.0
	v_add_u32_e32 v108, s13, v217
	v_ashrrev_i32_e32 v109, 31, v108
	v_lshlrev_b64 v[108:109], 11, v[108:109]
	v_lshl_add_u64 v[108:109], s[22:23], 0, v[108:109]
	v_lshl_add_u64 v[108:109], v[108:109], 0, s[24:25]
	v_lshl_add_u64 v[108:109], v[108:109], 0, s[86:87]
	v_pk_mul_f32 v[94:95], v[94:95], v[110:111] op_sel_hi:[1,0]
	v_lshl_add_u64 v[116:117], v[108:109], 0, v[192:193]
	v_pk_mul_f32 v[108:109], v[106:107], v[110:111] op_sel_hi:[1,0]
	v_pk_mul_f32 v[100:101], v[100:101], v[110:111] op_sel_hi:[1,0]
	v_cvt_pk_bf16_f32 v106, v94, v95
	v_pk_mul_f32 v[94:95], v[104:105], v[110:111] op_sel_hi:[1,0]
	v_pk_mul_f32 v[92:93], v[92:93], v[110:111] op_sel_hi:[1,0]
	v_pk_mul_f32 v[112:113], v[112:113], v[110:111] op_sel_hi:[1,0]
	v_cvt_pk_bf16_f32 v107, v108, v109
	v_cvt_pk_bf16_f32 v108, v100, v101
	v_pk_mul_f32 v[100:101], v[114:115], v[110:111] op_sel_hi:[1,0]
	v_cvt_pk_bf16_f32 v109, v112, v113
	global_store_dwordx4 v[116:117], v[106:109], off
	v_pk_mul_f32 v[102:103], v[102:103], v[110:111] op_sel_hi:[1,0]
	v_cvt_pk_bf16_f32 v92, v92, v93
	v_cvt_pk_bf16_f32 v93, v94, v95
	s_nop 0
	v_cvt_pk_bf16_f32 v94, v102, v103
	v_cvt_pk_bf16_f32 v95, v100, v101
	global_store_dwordx4 v[116:117], v[92:95], off offset:256
	ds_read_b128 v[92:95], v229
	s_waitcnt lgkmcnt(0)
	v_mov_b32_e32 v100, v93
	v_mov_b32_e32 v101, v94
	v_mov_b32_e32 v93, v95
	v_pk_add_f32 v[92:93], v[100:101], v[92:93]
	s_nop 0
	v_add_f32_e32 v92, v92, v93
	v_div_scale_f32 v93, s[26:27], v92, v92, 1.0
	v_rcp_f32_e32 v94, v93
	s_nop 0
	v_fma_f32 v95, -v93, v94, 1.0
	v_fmac_f32_e32 v94, v95, v94
	v_div_scale_f32 v95, vcc, 1.0, v92, 1.0
	v_mul_f32_e32 v100, v95, v94
	v_fma_f32 v101, -v93, v100, v95
	v_fmac_f32_e32 v100, v101, v94
	v_fma_f32 v93, -v93, v100, v95
	v_div_fmas_f32 v93, v93, v94, v100
	v_div_fixup_f32 v94, v93, v92, 1.0
	v_add_u32_e32 v92, s13, v218
	v_ashrrev_i32_e32 v93, 31, v92
	v_lshlrev_b64 v[92:93], 11, v[92:93]
	v_lshl_add_u64 v[92:93], s[22:23], 0, v[92:93]
	v_lshl_add_u64 v[92:93], v[92:93], 0, s[24:25]
	v_lshl_add_u64 v[92:93], v[92:93], 0, s[86:87]
	v_pk_mul_f32 v[78:79], v[78:79], v[94:95] op_sel_hi:[1,0]
	v_lshl_add_u64 v[100:101], v[92:93], 0, v[192:193]
	v_pk_mul_f32 v[92:93], v[90:91], v[94:95] op_sel_hi:[1,0]
	v_pk_mul_f32 v[84:85], v[84:85], v[94:95] op_sel_hi:[1,0]
	v_cvt_pk_bf16_f32 v90, v78, v79
	v_pk_mul_f32 v[78:79], v[88:89], v[94:95] op_sel_hi:[1,0]
	v_pk_mul_f32 v[76:77], v[76:77], v[94:95] op_sel_hi:[1,0]
	v_pk_mul_f32 v[96:97], v[96:97], v[94:95] op_sel_hi:[1,0]
	v_cvt_pk_bf16_f32 v91, v92, v93
	v_cvt_pk_bf16_f32 v92, v84, v85
	v_pk_mul_f32 v[84:85], v[98:99], v[94:95] op_sel_hi:[1,0]
	v_cvt_pk_bf16_f32 v93, v96, v97
	global_store_dwordx4 v[100:101], v[90:93], off
	v_pk_mul_f32 v[86:87], v[86:87], v[94:95] op_sel_hi:[1,0]
	v_cvt_pk_bf16_f32 v76, v76, v77
	v_cvt_pk_bf16_f32 v77, v78, v79
	s_nop 0
	v_cvt_pk_bf16_f32 v78, v86, v87
	v_cvt_pk_bf16_f32 v79, v84, v85
	global_store_dwordx4 v[100:101], v[76:79], off offset:256
	ds_read_b128 v[76:79], v230
	s_waitcnt lgkmcnt(0)
; #define PG8_LAS __attribute__((address_space(3)))
; __device__ __forceinline__ unsigned cvt_pk_bf16(float lo, float hi) { unsigned r; asm volatile("v_cvt_pk_bf16_f32 %0, %1, %2" : "=v"(r) : "v"(lo), "v"(hi)); return r; }
;     __device__ __forceinline__ void operator()(f32x4 (&acc)[2][2][4][2], const Unit& u, int wr, int wc, int fr, int fq) const {
;     ...
;         for (int ai = 0; ai < 2; ++ai)
; #pragma unroll
;             for (int m = 0; m < 4; ++m) { const int r = ai * HALF + wr * 64 + m * 16 + fr; const f32x4 s4 = *(const PG8_LAS f32x4*)(xch + 1024 + r * 4);
;                 const float inv = 1.0f / ((s4[0] + s4[1]) + (s4[2] + s4[3]));
;                 bf16_t* rowp = P + (size_t)(u.pm >> 5) * bgap + (size_t)(u.pm * BM + r) * 1024 + u.pn * BM + wc * 32 + 8 * fq;
; #pragma unroll
;                 for (int bj = 0; bj < 2; ++bj) { const f32x4 v0 = acc[ai][bj][m][0] * inv, v1 = acc[ai][bj][m][1] * inv;
;                     u32x4 w; w.x = cvt_pk_bf16(v0[0], v0[1]); w.y = cvt_pk_bf16(v0[2], v0[3]); w.z = cvt_pk_bf16(v1[0], v1[1]); w.w = cvt_pk_bf16(v1[2], v1[3]);
;                     *(u32x4*)(rowp + bj * HALF) = w; }
;                 asm volatile("" ::: "memory"); }
	v_mov_b32_e32 v84, v77
	v_mov_b32_e32 v85, v78
	v_mov_b32_e32 v77, v79
	v_pk_add_f32 v[76:77], v[84:85], v[76:77]
	s_nop 0
	v_add_f32_e32 v76, v76, v77
	v_div_scale_f32 v77, s[26:27], v76, v76, 1.0
	v_rcp_f32_e32 v78, v77
	s_nop 0
	v_fma_f32 v79, -v77, v78, 1.0
	v_fmac_f32_e32 v78, v79, v78
	v_div_scale_f32 v79, vcc, 1.0, v76, 1.0
	v_mul_f32_e32 v84, v79, v78
	v_fma_f32 v85, -v77, v84, v79
	v_fmac_f32_e32 v84, v85, v78
	v_fma_f32 v77, -v77, v84, v79
	v_div_fmas_f32 v77, v77, v78, v84
	v_div_fixup_f32 v78, v77, v76, 1.0
	v_add_u32_e32 v76, s13, v219
	v_ashrrev_i32_e32 v77, 31, v76
	v_lshlrev_b64 v[76:77], 11, v[76:77]
	v_lshl_add_u64 v[76:77], s[22:23], 0, v[76:77]
	v_lshl_add_u64 v[76:77], v[76:77], 0, s[24:25]
	v_lshl_add_u64 v[76:77], v[76:77], 0, s[86:87]
	v_lshl_add_u64 v[84:85], v[76:77], 0, v[192:193]
	v_pk_mul_f32 v[76:77], v[74:75], v[78:79] op_sel_hi:[1,0]
	v_pk_mul_f32 v[64:65], v[64:65], v[78:79] op_sel_hi:[1,0]
	v_pk_mul_f32 v[68:69], v[68:69], v[78:79] op_sel_hi:[1,0]
	v_pk_mul_f32 v[70:71], v[70:71], v[78:79] op_sel_hi:[1,0]
	v_pk_mul_f32 v[80:81], v[80:81], v[78:79] op_sel_hi:[1,0]
	v_cvt_pk_bf16_f32 v74, v64, v65
	v_cvt_pk_bf16_f32 v75, v76, v77
	v_cvt_pk_bf16_f32 v76, v68, v69
	v_pk_mul_f32 v[64:65], v[72:73], v[78:79] op_sel_hi:[1,0]
	v_cvt_pk_bf16_f32 v77, v80, v81
	global_store_dwordx4 v[84:85], v[74:77], off
	v_pk_mul_f32 v[60:61], v[60:61], v[78:79] op_sel_hi:[1,0]
	v_pk_mul_f32 v[72:73], v[82:83], v[78:79] op_sel_hi:[1,0]
	v_cvt_pk_bf16_f32 v68, v60, v61
	v_cvt_pk_bf16_f32 v69, v64, v65
	v_cvt_pk_bf16_f32 v70, v70, v71
	v_add_u32_e32 v60, s2, v216
	v_cvt_pk_bf16_f32 v71, v72, v73
	global_store_dwordx4 v[84:85], v[68:71], off offset:256
	ds_read_b128 v[68:71], v60
	s_waitcnt lgkmcnt(0)
	v_mov_b32_e32 v60, v69
	v_mov_b32_e32 v61, v70
	v_mov_b32_e32 v69, v71
	v_pk_add_f32 v[60:61], v[60:61], v[68:69]
	s_nop 0
	v_add_f32_e32 v60, v60, v61
	v_div_scale_f32 v61, s[26:27], v60, v60, 1.0
	v_rcp_f32_e32 v64, v61
	s_nop 0
	v_fma_f32 v65, -v61, v64, 1.0
	v_fmac_f32_e32 v64, v65, v64
	v_div_scale_f32 v65, vcc, 1.0, v60, 1.0
	v_mul_f32_e32 v68, v65, v64
	v_fma_f32 v69, -v61, v68, v65
	v_fmac_f32_e32 v68, v69, v64
	v_fma_f32 v61, -v61, v68, v65
	v_div_fmas_f32 v61, v61, v64, v68
	v_div_fixup_f32 v64, v61, v60, 1.0
	v_add_u32_e32 v60, s13, v215
	v_ashrrev_i32_e32 v61, 31, v60
	v_lshlrev_b64 v[60:61], 11, v[60:61]
	v_lshl_add_u64 v[60:61], s[22:23], 0, v[60:61]
	v_lshl_add_u64 v[60:61], v[60:61], 0, s[24:25]
	v_lshl_add_u64 v[60:61], v[60:61], 0, s[86:87]
	v_pk_mul_f32 v[46:47], v[46:47], v[64:65] op_sel_hi:[1,0]
	v_lshl_add_u64 v[68:69], v[60:61], 0, v[192:193]
	v_pk_mul_f32 v[60:61], v[58:59], v[64:65] op_sel_hi:[1,0]
	v_pk_mul_f32 v[52:53], v[52:53], v[64:65] op_sel_hi:[1,0]
	v_cvt_pk_bf16_f32 v58, v46, v47
	v_pk_mul_f32 v[46:47], v[56:57], v[64:65] op_sel_hi:[1,0]
	v_pk_mul_f32 v[44:45], v[44:45], v[64:65] op_sel_hi:[1,0]
	v_pk_mul_f32 v[62:63], v[62:63], v[64:65] op_sel_hi:[1,0]
	v_cvt_pk_bf16_f32 v59, v60, v61
	v_cvt_pk_bf16_f32 v60, v52, v53
	v_pk_mul_f32 v[52:53], v[66:67], v[64:65] op_sel_hi:[1,0]
	v_cvt_pk_bf16_f32 v61, v62, v63
	global_store_dwordx4 v[68:69], v[58:61], off
	v_pk_mul_f32 v[54:55], v[54:55], v[64:65] op_sel_hi:[1,0]
	v_cvt_pk_bf16_f32 v44, v44, v45
	v_cvt_pk_bf16_f32 v45, v46, v47
	s_nop 0
	v_cvt_pk_bf16_f32 v46, v54, v55
	v_cvt_pk_bf16_f32 v47, v52, v53
	global_store_dwordx4 v[68:69], v[44:47], off offset:256
	ds_read_b128 v[44:47], v231
	s_waitcnt lgkmcnt(0)
	v_mov_b32_e32 v52, v45
	v_mov_b32_e32 v53, v46
	v_mov_b32_e32 v45, v47
	v_pk_add_f32 v[44:45], v[52:53], v[44:45]
	s_nop 0
	v_add_f32_e32 v44, v44, v45
	v_div_scale_f32 v45, s[26:27], v44, v44, 1.0
	v_rcp_f32_e32 v46, v45
	s_nop 0
	v_fma_f32 v47, -v45, v46, 1.0
	v_fmac_f32_e32 v46, v47, v46
	v_div_scale_f32 v47, vcc, 1.0, v44, 1.0
	v_mul_f32_e32 v52, v47, v46
	v_fma_f32 v53, -v45, v52, v47
	v_fmac_f32_e32 v52, v53, v46
	v_fma_f32 v45, -v45, v52, v47
	v_div_fmas_f32 v45, v45, v46, v52
	v_div_fixup_f32 v46, v45, v44, 1.0
	v_add_u32_e32 v44, s13, v220
	v_ashrrev_i32_e32 v45, 31, v44
	v_lshlrev_b64 v[44:45], 11, v[44:45]
	v_lshl_add_u64 v[44:45], s[22:23], 0, v[44:45]
	v_lshl_add_u64 v[44:45], v[44:45], 0, s[24:25]
	v_lshl_add_u64 v[44:45], v[44:45], 0, s[86:87]
	v_pk_mul_f32 v[30:31], v[30:31], v[46:47] op_sel_hi:[1,0]
	v_lshl_add_u64 v[52:53], v[44:45], 0, v[192:193]
	v_pk_mul_f32 v[44:45], v[42:43], v[46:47] op_sel_hi:[1,0]
	v_pk_mul_f32 v[36:37], v[36:37], v[46:47] op_sel_hi:[1,0]
	v_cvt_pk_bf16_f32 v42, v30, v31
	v_pk_mul_f32 v[30:31], v[40:41], v[46:47] op_sel_hi:[1,0]
	v_pk_mul_f32 v[28:29], v[28:29], v[46:47] op_sel_hi:[1,0]
	v_pk_mul_f32 v[48:49], v[48:49], v[46:47] op_sel_hi:[1,0]
	v_cvt_pk_bf16_f32 v43, v44, v45
	v_cvt_pk_bf16_f32 v44, v36, v37
	v_pk_mul_f32 v[36:37], v[50:51], v[46:47] op_sel_hi:[1,0]
	v_cvt_pk_bf16_f32 v45, v48, v49
	global_store_dwordx4 v[52:53], v[42:45], off
	v_pk_mul_f32 v[38:39], v[38:39], v[46:47] op_sel_hi:[1,0]
	v_cvt_pk_bf16_f32 v28, v28, v29
	v_cvt_pk_bf16_f32 v29, v30, v31
	s_nop 0
	v_cvt_pk_bf16_f32 v30, v38, v39
	v_cvt_pk_bf16_f32 v31, v36, v37
	global_store_dwordx4 v[52:53], v[28:31], off offset:256
	ds_read_b128 v[28:31], v232
	s_waitcnt lgkmcnt(0)
; #define PG8_LAS __attribute__((address_space(3)))
; __device__ __forceinline__ unsigned cvt_pk_bf16(float lo, float hi) { unsigned r; asm volatile("v_cvt_pk_bf16_f32 %0, %1, %2" : "=v"(r) : "v"(lo), "v"(hi)); return r; }
;     __device__ __forceinline__ void operator()(f32x4 (&acc)[2][2][4][2], const Unit& u, int wr, int wc, int fr, int fq) const {
;     ...
;         for (int ai = 0; ai < 2; ++ai)
; #pragma unroll
;             for (int m = 0; m < 4; ++m) { const int r = ai * HALF + wr * 64 + m * 16 + fr; const f32x4 s4 = *(const PG8_LAS f32x4*)(xch + 1024 + r * 4);
;                 const float inv = 1.0f / ((s4[0] + s4[1]) + (s4[2] + s4[3]));
;                 bf16_t* rowp = P + (size_t)(u.pm >> 5) * bgap + (size_t)(u.pm * BM + r) * 1024 + u.pn * BM + wc * 32 + 8 * fq;
; #pragma unroll
;                 for (int bj = 0; bj < 2; ++bj) { const f32x4 v0 = acc[ai][bj][m][0] * inv, v1 = acc[ai][bj][m][1] * inv;
;                     u32x4 w; w.x = cvt_pk_bf16(v0[0], v0[1]); w.y = cvt_pk_bf16(v0[2], v0[3]); w.z = cvt_pk_bf16(v1[0], v1[1]); w.w = cvt_pk_bf16(v1[2], v1[3]);
;                     *(u32x4*)(rowp + bj * HALF) = w; }
;                 asm volatile("" ::: "memory"); }
	v_mov_b32_e32 v36, v29
	v_mov_b32_e32 v37, v30
	v_mov_b32_e32 v29, v31
	v_pk_add_f32 v[28:29], v[36:37], v[28:29]
	s_nop 0
	v_add_f32_e32 v28, v28, v29
	v_div_scale_f32 v29, s[26:27], v28, v28, 1.0
	v_rcp_f32_e32 v30, v29
	s_nop 0
	v_fma_f32 v31, -v29, v30, 1.0
	v_fmac_f32_e32 v30, v31, v30
	v_div_scale_f32 v31, vcc, 1.0, v28, 1.0
	v_mul_f32_e32 v36, v31, v30
	v_fma_f32 v37, -v29, v36, v31
	v_fmac_f32_e32 v36, v37, v30
	v_fma_f32 v29, -v29, v36, v31
	v_div_fmas_f32 v29, v29, v30, v36
	v_div_fixup_f32 v30, v29, v28, 1.0
	v_add_u32_e32 v28, s13, v221
	v_ashrrev_i32_e32 v29, 31, v28
	v_lshlrev_b64 v[28:29], 11, v[28:29]
	v_lshl_add_u64 v[28:29], s[22:23], 0, v[28:29]
	v_lshl_add_u64 v[28:29], v[28:29], 0, s[24:25]
	v_lshl_add_u64 v[28:29], v[28:29], 0, s[86:87]
	v_pk_mul_f32 v[14:15], v[14:15], v[30:31] op_sel_hi:[1,0]
	v_lshl_add_u64 v[36:37], v[28:29], 0, v[192:193]
	v_pk_mul_f32 v[28:29], v[26:27], v[30:31] op_sel_hi:[1,0]
	v_pk_mul_f32 v[20:21], v[20:21], v[30:31] op_sel_hi:[1,0]
	v_cvt_pk_bf16_f32 v26, v14, v15
	v_pk_mul_f32 v[14:15], v[24:25], v[30:31] op_sel_hi:[1,0]
	v_pk_mul_f32 v[12:13], v[12:13], v[30:31] op_sel_hi:[1,0]
	v_pk_mul_f32 v[32:33], v[32:33], v[30:31] op_sel_hi:[1,0]
	v_cvt_pk_bf16_f32 v27, v28, v29
	v_cvt_pk_bf16_f32 v28, v20, v21
	v_pk_mul_f32 v[20:21], v[34:35], v[30:31] op_sel_hi:[1,0]
	v_cvt_pk_bf16_f32 v29, v32, v33
	global_store_dwordx4 v[36:37], v[26:29], off
	v_pk_mul_f32 v[22:23], v[22:23], v[30:31] op_sel_hi:[1,0]
	v_cvt_pk_bf16_f32 v12, v12, v13
	v_cvt_pk_bf16_f32 v13, v14, v15
	s_nop 0
	v_cvt_pk_bf16_f32 v14, v22, v23
	v_cvt_pk_bf16_f32 v15, v20, v21
	global_store_dwordx4 v[36:37], v[12:15], off offset:256
	ds_read_b128 v[12:15], v233
	s_waitcnt lgkmcnt(0)
	v_mov_b32_e32 v20, v13
	v_mov_b32_e32 v21, v14
	v_mov_b32_e32 v13, v15
	v_pk_add_f32 v[12:13], v[20:21], v[12:13]
	s_nop 0
	v_add_f32_e32 v12, v12, v13
	v_div_scale_f32 v13, s[26:27], v12, v12, 1.0
	v_rcp_f32_e32 v14, v13
	s_nop 0
	v_fma_f32 v15, -v13, v14, 1.0
	v_fmac_f32_e32 v14, v15, v14
	v_div_scale_f32 v15, vcc, 1.0, v12, 1.0
	v_mul_f32_e32 v20, v15, v14
	v_fma_f32 v21, -v13, v20, v15
	v_fmac_f32_e32 v20, v21, v14
	v_fma_f32 v13, -v13, v20, v15
	v_div_fmas_f32 v13, v13, v14, v20
	v_add_u32_e32 v14, s13, v222
	v_ashrrev_i32_e32 v15, 31, v14
	v_lshlrev_b64 v[14:15], 11, v[14:15]
	v_lshl_add_u64 v[14:15], s[22:23], 0, v[14:15]
	v_div_fixup_f32 v12, v13, v12, 1.0
	v_lshl_add_u64 v[14:15], v[14:15], 0, s[24:25]
	v_lshl_add_u64 v[14:15], v[14:15], 0, s[86:87]
	v_pk_mul_f32 v[2:3], v[2:3], v[12:13] op_sel_hi:[1,0]
	v_lshl_add_u64 v[14:15], v[14:15], 0, v[192:193]
	v_pk_mul_f32 v[10:11], v[10:11], v[12:13] op_sel_hi:[1,0]
	v_pk_mul_f32 v[4:5], v[4:5], v[12:13] op_sel_hi:[1,0]
	v_cvt_pk_bf16_f32 v2, v2, v3
	v_cvt_pk_bf16_f32 v3, v10, v11
	v_pk_mul_f32 v[16:17], v[16:17], v[12:13] op_sel_hi:[1,0]
	v_cvt_pk_bf16_f32 v4, v4, v5
	v_pk_mul_f32 v[0:1], v[0:1], v[12:13] op_sel_hi:[1,0]
	v_cvt_pk_bf16_f32 v5, v16, v17
	global_store_dwordx4 v[14:15], v[2:5], off
	v_pk_mul_f32 v[6:7], v[6:7], v[12:13] op_sel_hi:[1,0]
	v_cvt_pk_bf16_f32 v0, v0, v1
	s_andn2_b64 vcc, exec, s[42:43]
	v_pk_mul_f32 v[2:3], v[8:9], v[12:13] op_sel_hi:[1,0]
	v_pk_mul_f32 v[4:5], v[18:19], v[12:13] op_sel_hi:[1,0]
	v_cvt_pk_bf16_f32 v1, v2, v3
	v_cvt_pk_bf16_f32 v2, v6, v7
	s_mov_b64 s[22:23], -1
	v_cvt_pk_bf16_f32 v3, v4, v5
	global_store_dwordx4 v[14:15], v[0:3], off offset:256
	s_cbranch_vccnz .LBB0_679
	s_andn2_b64 vcc, exec, s[0:1]
	s_cbranch_vccnz .LBB0_678
	s_barrier
	s_branch .LBB0_678

; #define lane (hw_lane())
; __device__ __forceinline__ float row_rstd(const float* slots, int row) {
;     const f32x4* s = (const f32x4*)(slots + (size_t)row * 16);
;     const f32x4 a = s[0], b = s[1], c = s[2], d = s[3];
;     const f32x4 t = (a + b) + (c + d);
;     const float ss = (t[0] + t[1]) + (t[2] + t[3]);
;     return __builtin_amdgcn_rsqf(ss * (1.0f / 1024.0f) + 1e-6f);
; }
; __global__ void __launch_bounds__(512, 2) fwd_megakernel(Args a) {
;     ...
;     { const float* fg = a.in[I_FING]; const int ln = lane, gw0 = grouped ? grp * SEQ + gj * 256 + wave * 32 : gw, fstep = grouped ? 1 : NGW, flim = grouped ? gw0 + 32 : M;
;       v2u nw[4]; float nrs = 0.f;
;       if (gw0 < flim) { const v2u* xr = (const v2u*)(HB + (size_t)gw0 * D) + ln; nrs = pg8::row_rstd(slots, gw0);
; #pragma unroll
;         for (int j = 0; j < 4; ++j) nw[j] = __builtin_nontemporal_load(xr + 64 * j); }
.Lfn_generic:
	s_mov_b64 s[0:1], s[58:59]
	s_ashr_i32 s19, s18, 31
	s_lshl_b64 s[2:3], s[18:19], 11
	s_add_u32 s0, s0, s2
	s_addc_u32 s1, s1, s3
	s_mov_b64 s[2:3], s[58:59]
	s_lshl_b64 s[4:5], s[18:19], 6
	s_add_u32 s4, s2, s4
	s_addc_u32 s5, s3, s5
	s_mov_b32 s6, 0x5500000
	v_mov_b32_e32 v2, s4
	s_add_u32 s2, s4, 0x5500000
	v_mov_b32_e32 v3, s5
	v_add_co_u32_e32 v2, vcc, s6, v2
	s_addc_u32 s3, s5, 0
	s_nop 0
	v_addc_co_u32_e32 v3, vcc, 0, v3, vcc
	v_mov_b64_e32 v[4:5], s[2:3]
	global_load_dwordx4 v[16:19], v[2:3], off
	global_load_dwordx4 v[20:23], v[4:5], off offset:16
	global_load_dwordx4 v[24:27], v[4:5], off offset:32
	global_load_dwordx4 v[28:31], v[4:5], off offset:48
	v_ashrrev_i32_e32 v1, 31, v0
	v_lshlrev_b64 v[4:5], 3, v[0:1]
	v_lshl_add_u64 v[2:3], s[0:1], 0, v[4:5]
	s_mov_b32 s0, 0x7100000
	v_add_co_u32_e32 v10, vcc, s0, v2
	s_mov_b64 s[4:5], 0x7100000
	s_nop 0
	v_addc_co_u32_e32 v11, vcc, 0, v3, vcc
	v_lshl_add_u64 v[8:9], v[2:3], 0, s[4:5]
	global_load_dwordx2 v[14:15], v[10:11], off nt
	global_load_dwordx2 v[12:13], v[8:9], off offset:512 nt
	global_load_dwordx2 v[6:7], v[8:9], off offset:1024 nt
	global_load_dwordx2 v[2:3], v[8:9], off offset:1536 nt
	s_add_i32 s0, s18, s16
	s_ashr_i32 s1, s0, 31
	s_lshl_b64 s[2:3], s[0:1], 6
	s_add_u32 s9, s2, 0x5500000
	v_mov_b32_e32 v11, 0x358637bd
	s_addc_u32 s10, s3, 0
	s_ashr_i32 s17, s16, 31
	s_lshl_b64 s[2:3], s[0:1], 11
	s_lshl_b64 s[6:7], s[18:19], 12
	s_lshl_b64 s[0:1], s[16:17], 6
	v_lshl_add_u64 v[4:5], s[2:3], 0, v[4:5]
	s_lshl_b64 s[2:3], s[16:17], 11
	v_lshl_add_u64 v[4:5], v[4:5], 0, s[4:5]
	s_add_u32 s4, s56, s6
	v_lshlrev_b64 v[8:9], 4, v[0:1]
	s_addc_u32 s5, s57, s7
	v_lshl_add_u64 v[0:1], s[54:55], 0, v[8:9]
	v_lshl_add_u64 v[8:9], s[4:5], 0, v[8:9]
	s_mov_b64 s[4:5], 0xc00
	v_lshl_add_u64 v[8:9], v[8:9], 0, s[4:5]
	s_lshl_b64 s[4:5], s[16:17], 12
	s_waitcnt vmcnt(0) lgkmcnt(0)
	v_pk_add_f32 v[18:19], v[18:19], v[22:23]
	v_pk_add_f32 v[16:17], v[16:17], v[20:21]
	v_pk_add_f32 v[20:21], v[26:27], v[30:31]
	v_pk_add_f32 v[22:23], v[24:25], v[28:29]
	v_pk_add_f32 v[18:19], v[18:19], v[20:21]
	v_pk_add_f32 v[16:17], v[16:17], v[22:23]
	s_nop 0
	v_pk_mov_b32 v[20:21], v[16:17], v[18:19] op_sel:[1,0]
	v_mov_b32_e32 v17, v19
	v_pk_add_f32 v[16:17], v[20:21], v[16:17]
	s_nop 0
	v_add_f32_e32 v10, v16, v17
	v_fmamk_f32 v10, v10, 0x3a800000, v11
	v_rsq_f32_e32 v10, v10
	s_branch .LBB0_1118

; __global__ void __launch_bounds__(512, 2) fwd_megakernel(Args a) {
;     ...
;       for (int m = gw0; m < flim; m += fstep) { f32x4* orow = (f32x4*)(hres + (size_t)m * D) + ln;
;         v2u w[4]; const float rs = nrs;
; #pragma unroll
;         for (int j = 0; j < 4; ++j) w[j] = nw[j];
;         { const int mn = m + fstep; if (mn < flim) { const v2u* xr = (const v2u*)(HB + (size_t)mn * D) + ln; nrs = pg8::row_rstd(slots, mn);
; #pragma unroll
;             for (int j = 0; j < 4; ++j) nw[j] = __builtin_nontemporal_load(xr + 64 * j); } }
.LBB0_1118:
	s_add_i32 s18, s18, s16
	s_cmp_ge_i32 s18, s8
	s_cselect_b64 s[6:7], -1, 0
	s_and_b64 vcc, exec, s[6:7]
	v_mov_b32_e32 v24, v10
	v_mov_b32_e32 v16, v14
	v_mov_b32_e32 v17, v15
	v_mov_b32_e32 v18, v12
	v_mov_b32_e32 v19, v13
	v_mov_b32_e32 v20, v6
	v_mov_b32_e32 v21, v7
	v_mov_b32_e32 v22, v2
	v_mov_b32_e32 v23, v3
	s_cbranch_vccnz .LBB0_1117
	s_mov_b64 s[12:13], s[58:59]
	s_mov_b64 s[14:15], s[58:59]
	s_add_u32 s14, s14, s9
	s_addc_u32 s15, s15, s10
	v_mov_b64_e32 v[16:17], s[14:15]
	global_load_dwordx4 v[24:27], v[16:17], off
	global_load_dwordx4 v[28:31], v[16:17], off offset:16
	global_load_dwordx4 v[32:35], v[16:17], off offset:32
	global_load_dwordx4 v[36:39], v[16:17], off offset:48
	v_lshl_add_u64 v[40:41], s[12:13], 0, v[4:5]
	global_load_dwordx2 v[16:17], v[40:41], off nt
	global_load_dwordx2 v[18:19], v[40:41], off offset:512 nt
	global_load_dwordx2 v[20:21], v[40:41], off offset:1024 nt
	global_load_dwordx2 v[22:23], v[40:41], off offset:1536 nt
	s_waitcnt vmcnt(0) lgkmcnt(0)
	v_pk_add_f32 v[26:27], v[26:27], v[30:31]
	v_pk_add_f32 v[24:25], v[24:25], v[28:29]
	v_pk_add_f32 v[28:29], v[34:35], v[38:39]
	v_pk_add_f32 v[30:31], v[32:33], v[36:37]
	v_pk_add_f32 v[26:27], v[26:27], v[28:29]
	v_pk_add_f32 v[24:25], v[24:25], v[30:31]
	s_nop 0
	v_pk_mov_b32 v[28:29], v[24:25], v[26:27] op_sel:[1,0]
	v_mov_b32_e32 v25, v27
	v_pk_add_f32 v[24:25], v[28:29], v[24:25]
	s_nop 0
	v_add_f32_e32 v24, v24, v25
	v_fmamk_f32 v24, v24, 0x3a800000, v11
	v_rsq_f32_e32 v24, v24
	s_branch .LBB0_1117
